# v11 + all per-segment s_setprio flips deleted, one static s_setprio 1 for waves 4-7 at kernel entry
# speedup vs baseline: 1.0005x; 1.0005x over previous
.LBB0_2:
	s_cmp_lt_u32 s91, 0x100
	s_cbranch_scc1 .Lprio_done
	s_setprio 1

.LBB0_472:
	ds_read_b128 v[152:155], v148
	ds_read_b128 v[156:159], v148 offset:1024
	ds_read_b128 v[166:169], v148 offset:2048
	ds_read_b128 v[170:173], v148 offset:3072
	ds_read_b128 v[174:177], v149
	ds_read_b128 v[178:181], v149 offset:1024
	ds_read_b128 v[182:185], v149 offset:2048
	ds_read_b128 v[186:189], v149 offset:3072
	s_add_u32 s44, s54, 0xfff00080
	s_addc_u32 s56, s55, -1
	s_cmp_eq_u32 s72, 60
	s_cselect_b32 s59, s17, s56
	s_cselect_b32 s58, s68, s44
	s_cselect_b32 s57, s15, s71
	s_cselect_b32 s56, s69, s70
	v_lshl_add_u64 v[160:161], s[54:55], 0, v[138:139]
	s_add_i32 m0, s41, 0xc000
	ds_read_b128 v[190:193], v150
	ds_read_b128 v[194:197], v150 offset:1024
	ds_read_b128 v[198:201], v150 offset:2048
	ds_read_b128 v[202:205], v150 offset:3072
	ds_read_b128 v[206:209], v150 offset:4096
	ds_read_b128 v[210:213], v150 offset:5120
	ds_read_b128 v[214:217], v150 offset:6144
	ds_read_b128 v[218:221], v150 offset:7168
	global_load_lds_dwordx4 v[160:161], off
	v_lshl_add_u64 v[160:161], s[54:55], 0, v[140:141]
	s_add_i32 m0, s41, 0xe000
	s_nop 0
	global_load_lds_dwordx4 v[160:161], off
	s_waitcnt vmcnt(8)
	s_waitcnt lgkmcnt(0)
	s_barrier
	s_waitcnt lgkmcnt(0)
	v_mfma_f32_16x16x32_bf16 v[126:129], v[152:155], v[190:193], v[126:129]
	v_mfma_f32_16x16x32_bf16 v[126:129], v[156:159], v[194:197], v[126:129]
	v_mfma_f32_16x16x32_bf16 v[122:125], v[170:173], v[194:197], v[122:125]
	v_mfma_f32_16x16x32_bf16 v[122:125], v[166:169], v[190:193], v[122:125]
	v_mfma_f32_16x16x32_bf16 v[110:113], v[166:169], v[198:201], v[110:113]
	v_mfma_f32_16x16x32_bf16 v[110:113], v[170:173], v[202:205], v[110:113]
	v_mfma_f32_16x16x32_bf16 v[118:121], v[156:159], v[202:205], v[118:121]
	v_mfma_f32_16x16x32_bf16 v[118:121], v[152:155], v[198:201], v[118:121]
	v_mfma_f32_16x16x32_bf16 v[102:105], v[152:155], v[206:209], v[102:105]
	v_mfma_f32_16x16x32_bf16 v[102:105], v[156:159], v[210:213], v[102:105]
	v_mfma_f32_16x16x32_bf16 v[94:97], v[170:173], v[210:213], v[94:97]
	v_mfma_f32_16x16x32_bf16 v[94:97], v[166:169], v[206:209], v[94:97]
	v_mfma_f32_16x16x32_bf16 v[78:81], v[166:169], v[214:217], v[78:81]
	v_mfma_f32_16x16x32_bf16 v[78:81], v[170:173], v[218:221], v[78:81]
	v_mfma_f32_16x16x32_bf16 v[86:89], v[156:159], v[218:221], v[86:89]
	v_mfma_f32_16x16x32_bf16 v[86:89], v[152:155], v[214:217], v[86:89]
	v_mfma_f32_16x16x32_bf16 v[114:117], v[174:177], v[190:193], v[114:117]
	v_mfma_f32_16x16x32_bf16 v[114:117], v[178:181], v[194:197], v[114:117]
	v_mfma_f32_16x16x32_bf16 v[106:109], v[186:189], v[194:197], v[106:109]
	v_mfma_f32_16x16x32_bf16 v[106:109], v[182:185], v[190:193], v[106:109]
	v_mfma_f32_16x16x32_bf16 v[90:93], v[182:185], v[198:201], v[90:93]
	v_mfma_f32_16x16x32_bf16 v[90:93], v[186:189], v[202:205], v[90:93]
	v_mfma_f32_16x16x32_bf16 v[98:101], v[178:181], v[202:205], v[98:101]
	v_mfma_f32_16x16x32_bf16 v[98:101], v[174:177], v[198:201], v[98:101]
	v_mfma_f32_16x16x32_bf16 v[82:85], v[174:177], v[206:209], v[82:85]
	v_mfma_f32_16x16x32_bf16 v[82:85], v[178:181], v[210:213], v[82:85]
	v_mfma_f32_16x16x32_bf16 v[74:77], v[186:189], v[210:213], v[74:77]
	v_mfma_f32_16x16x32_bf16 v[74:77], v[182:185], v[206:209], v[74:77]
	v_mfma_f32_16x16x32_bf16 v[66:69], v[182:185], v[214:217], v[66:69]
	v_mfma_f32_16x16x32_bf16 v[66:69], v[186:189], v[218:221], v[66:69]
	v_mfma_f32_16x16x32_bf16 v[70:73], v[178:181], v[218:221], v[70:73]
	v_mfma_f32_16x16x32_bf16 v[70:73], v[174:177], v[214:217], v[70:73]
	s_barrier
	s_add_i32 s44, s64, s27
	v_lshl_add_u64 v[160:161], s[56:57], 0, v[134:135]
	s_mov_b32 m0, s44
	ds_read_b128 v[190:193], v150 offset:16384
	ds_read_b128 v[194:197], v150 offset:17408
	ds_read_b128 v[198:201], v150 offset:18432
	ds_read_b128 v[202:205], v150 offset:19456
	ds_read_b128 v[206:209], v150 offset:20480
	ds_read_b128 v[210:213], v150 offset:21504
	ds_read_b128 v[214:217], v150 offset:22528
	ds_read_b128 v[218:221], v150 offset:23552
	global_load_lds_dwordx4 v[160:161], off
	s_add_i32 m0, s44, 0x2000
	s_add_u32 s74, s56, 0x100000
	v_lshl_add_u64 v[222:223], s[56:57], 0, v[130:131]
	s_addc_u32 s75, s57, 0
	s_add_i32 s44, s65, s27
	global_load_lds_dwordx4 v[222:223], off
	v_lshl_add_u64 v[224:225], s[74:75], 0, v[134:135]
	s_mov_b32 m0, s44
	v_lshl_add_u64 v[226:227], s[58:59], 0, v[132:133]
	global_load_lds_dwordx4 v[224:225], off
	v_lshl_add_u64 v[224:225], s[74:75], 0, v[130:131]
	s_add_i32 m0, s44, 0x2000
	s_nop 0
	global_load_lds_dwordx4 v[224:225], off
	v_lshl_add_u64 v[224:225], s[58:59], 0, v[136:137]
	s_mov_b32 m0, s41
	s_nop 0
	global_load_lds_dwordx4 v[224:225], off
	s_mov_b32 m0, s43
	s_nop 0
	global_load_lds_dwordx4 v[226:227], off
	s_waitcnt vmcnt(8)
	s_waitcnt lgkmcnt(0)
	s_barrier
	s_waitcnt lgkmcnt(0)
	v_mfma_f32_16x16x32_bf16 v[62:65], v[152:155], v[190:193], v[62:65]
	v_mfma_f32_16x16x32_bf16 v[62:65], v[156:159], v[194:197], v[62:65]
	v_mfma_f32_16x16x32_bf16 v[58:61], v[170:173], v[194:197], v[58:61]
	v_mfma_f32_16x16x32_bf16 v[58:61], v[166:169], v[190:193], v[58:61]
	v_mfma_f32_16x16x32_bf16 v[46:49], v[166:169], v[198:201], v[46:49]
	v_mfma_f32_16x16x32_bf16 v[46:49], v[170:173], v[202:205], v[46:49]
	v_mfma_f32_16x16x32_bf16 v[54:57], v[156:159], v[202:205], v[54:57]
	v_mfma_f32_16x16x32_bf16 v[54:57], v[152:155], v[198:201], v[54:57]
	v_mfma_f32_16x16x32_bf16 v[38:41], v[152:155], v[206:209], v[38:41]
	v_mfma_f32_16x16x32_bf16 v[38:41], v[156:159], v[210:213], v[38:41]
	v_mfma_f32_16x16x32_bf16 v[30:33], v[170:173], v[210:213], v[30:33]
	v_mfma_f32_16x16x32_bf16 v[30:33], v[166:169], v[206:209], v[30:33]
	v_mfma_f32_16x16x32_bf16 v[14:17], v[166:169], v[214:217], v[14:17]
	v_mfma_f32_16x16x32_bf16 v[14:17], v[170:173], v[218:221], v[14:17]
	v_mfma_f32_16x16x32_bf16 v[22:25], v[156:159], v[218:221], v[22:25]
	v_mfma_f32_16x16x32_bf16 v[22:25], v[152:155], v[214:217], v[22:25]
	v_mfma_f32_16x16x32_bf16 v[50:53], v[174:177], v[190:193], v[50:53]
	v_mfma_f32_16x16x32_bf16 v[50:53], v[178:181], v[194:197], v[50:53]
	v_mfma_f32_16x16x32_bf16 v[42:45], v[186:189], v[194:197], v[42:45]
	v_mfma_f32_16x16x32_bf16 v[42:45], v[182:185], v[190:193], v[42:45]
	v_mfma_f32_16x16x32_bf16 v[26:29], v[182:185], v[198:201], v[26:29]
	v_mfma_f32_16x16x32_bf16 v[26:29], v[186:189], v[202:205], v[26:29]
	v_mfma_f32_16x16x32_bf16 v[34:37], v[178:181], v[202:205], v[34:37]
	v_mfma_f32_16x16x32_bf16 v[34:37], v[174:177], v[198:201], v[34:37]
	v_mfma_f32_16x16x32_bf16 v[18:21], v[174:177], v[206:209], v[18:21]
	v_mfma_f32_16x16x32_bf16 v[18:21], v[178:181], v[210:213], v[18:21]
	v_mfma_f32_16x16x32_bf16 v[10:13], v[186:189], v[210:213], v[10:13]
	v_mfma_f32_16x16x32_bf16 v[10:13], v[182:185], v[206:209], v[10:13]
	v_mfma_f32_16x16x32_bf16 v[2:5], v[182:185], v[214:217], v[2:5]
	v_mfma_f32_16x16x32_bf16 v[2:5], v[186:189], v[218:221], v[2:5]
	v_mfma_f32_16x16x32_bf16 v[6:9], v[178:181], v[218:221], v[6:9]
	v_mfma_f32_16x16x32_bf16 v[6:9], v[174:177], v[214:217], v[6:9]
	s_barrier
	s_add_i32 s44, 0, 0x18000
	v_add_u32_e32 v151, s44, v146
	s_add_i32 s73, 0, 0x1c000
	ds_read_b128 v[152:155], v151
	ds_read_b128 v[156:159], v151 offset:1024
	ds_read_b128 v[166:169], v151 offset:2048
	ds_read_b128 v[170:173], v151 offset:3072
	v_add_u32_e32 v151, s73, v146
	ds_read_b128 v[174:177], v151
	ds_read_b128 v[178:181], v151 offset:1024
	ds_read_b128 v[182:185], v151 offset:2048
	ds_read_b128 v[186:189], v151 offset:3072
	s_add_u32 s58, s58, 0x100000
	s_addc_u32 s59, s59, 0
	s_mov_b32 m0, s45
	v_lshl_add_u64 v[228:229], s[58:59], 0, v[136:137]
	ds_read_b128 v[190:193], v150 offset:32768
	ds_read_b128 v[194:197], v150 offset:33792
	ds_read_b128 v[198:201], v150 offset:34816
	ds_read_b128 v[202:205], v150 offset:35840
	ds_read_b128 v[206:209], v150 offset:36864
	ds_read_b128 v[210:213], v150 offset:37888
	ds_read_b128 v[214:217], v150 offset:38912
	ds_read_b128 v[218:221], v150 offset:39936
	global_load_lds_dwordx4 v[228:229], off
	v_lshl_add_u64 v[228:229], s[58:59], 0, v[132:133]
	s_mov_b32 m0, s53
	s_nop 0
	global_load_lds_dwordx4 v[228:229], off
	s_waitcnt vmcnt(8)
	s_waitcnt lgkmcnt(0)
	s_barrier
	s_waitcnt lgkmcnt(0)
	v_mfma_f32_16x16x32_bf16 v[126:129], v[152:155], v[190:193], v[126:129]
	v_mfma_f32_16x16x32_bf16 v[126:129], v[156:159], v[194:197], v[126:129]
	v_mfma_f32_16x16x32_bf16 v[122:125], v[170:173], v[194:197], v[122:125]
	v_mfma_f32_16x16x32_bf16 v[122:125], v[166:169], v[190:193], v[122:125]
	v_mfma_f32_16x16x32_bf16 v[110:113], v[166:169], v[198:201], v[110:113]
	v_mfma_f32_16x16x32_bf16 v[110:113], v[170:173], v[202:205], v[110:113]
	v_mfma_f32_16x16x32_bf16 v[118:121], v[156:159], v[202:205], v[118:121]
	v_mfma_f32_16x16x32_bf16 v[118:121], v[152:155], v[198:201], v[118:121]
	v_mfma_f32_16x16x32_bf16 v[102:105], v[152:155], v[206:209], v[102:105]
	v_mfma_f32_16x16x32_bf16 v[102:105], v[156:159], v[210:213], v[102:105]
	v_mfma_f32_16x16x32_bf16 v[94:97], v[170:173], v[210:213], v[94:97]
	v_mfma_f32_16x16x32_bf16 v[94:97], v[166:169], v[206:209], v[94:97]
	v_mfma_f32_16x16x32_bf16 v[78:81], v[166:169], v[214:217], v[78:81]
	v_mfma_f32_16x16x32_bf16 v[78:81], v[170:173], v[218:221], v[78:81]
	v_mfma_f32_16x16x32_bf16 v[86:89], v[156:159], v[218:221], v[86:89]
	v_mfma_f32_16x16x32_bf16 v[86:89], v[152:155], v[214:217], v[86:89]
	v_mfma_f32_16x16x32_bf16 v[114:117], v[174:177], v[190:193], v[114:117]
	v_mfma_f32_16x16x32_bf16 v[114:117], v[178:181], v[194:197], v[114:117]
	v_mfma_f32_16x16x32_bf16 v[106:109], v[186:189], v[194:197], v[106:109]
	v_mfma_f32_16x16x32_bf16 v[106:109], v[182:185], v[190:193], v[106:109]
	v_mfma_f32_16x16x32_bf16 v[90:93], v[182:185], v[198:201], v[90:93]
	v_mfma_f32_16x16x32_bf16 v[90:93], v[186:189], v[202:205], v[90:93]
	v_mfma_f32_16x16x32_bf16 v[98:101], v[178:181], v[202:205], v[98:101]
	v_mfma_f32_16x16x32_bf16 v[98:101], v[174:177], v[198:201], v[98:101]
	v_mfma_f32_16x16x32_bf16 v[82:85], v[174:177], v[206:209], v[82:85]
	v_mfma_f32_16x16x32_bf16 v[82:85], v[178:181], v[210:213], v[82:85]
	v_mfma_f32_16x16x32_bf16 v[74:77], v[186:189], v[210:213], v[74:77]
	v_mfma_f32_16x16x32_bf16 v[74:77], v[182:185], v[206:209], v[74:77]
	v_mfma_f32_16x16x32_bf16 v[66:69], v[182:185], v[214:217], v[66:69]
	v_mfma_f32_16x16x32_bf16 v[66:69], v[186:189], v[218:221], v[66:69]
	v_mfma_f32_16x16x32_bf16 v[70:73], v[178:181], v[218:221], v[70:73]
	v_mfma_f32_16x16x32_bf16 v[70:73], v[174:177], v[214:217], v[70:73]
	s_barrier
	s_add_i32 s44, s44, s27
	v_lshl_add_u64 v[160:161], v[160:161], 0, s[10:11]
	s_mov_b32 m0, s44
	ds_read_b128 v[190:193], v150 offset:49152
	ds_read_b128 v[194:197], v150 offset:50176
	ds_read_b128 v[198:201], v150 offset:51200
	ds_read_b128 v[202:205], v150 offset:52224
	ds_read_b128 v[206:209], v150 offset:53248
	ds_read_b128 v[210:213], v150 offset:54272
	ds_read_b128 v[214:217], v150 offset:55296
	ds_read_b128 v[218:221], v150 offset:56320
	global_load_lds_dwordx4 v[160:161], off
	s_add_i32 m0, s44, 0x2000
	s_add_u32 s56, s56, 0x100080
	v_lshl_add_u64 v[160:161], v[222:223], 0, s[10:11]
	s_addc_u32 s57, s57, 0
	s_add_i32 s44, s73, s27
	global_load_lds_dwordx4 v[160:161], off
	v_lshl_add_u64 v[160:161], s[56:57], 0, v[134:135]
	s_mov_b32 m0, s44
	s_nop 0
	global_load_lds_dwordx4 v[160:161], off
	v_lshl_add_u64 v[160:161], s[56:57], 0, v[130:131]
	s_add_i32 m0, s44, 0x2000
	s_nop 0
	global_load_lds_dwordx4 v[160:161], off
	v_lshl_add_u64 v[160:161], v[224:225], 0, s[10:11]
	s_mov_b32 m0, s61
	s_nop 0
	global_load_lds_dwordx4 v[160:161], off
	v_lshl_add_u64 v[160:161], v[226:227], 0, s[10:11]
	s_mov_b32 m0, s62
	s_nop 0
	global_load_lds_dwordx4 v[160:161], off
	s_waitcnt vmcnt(8)
	s_waitcnt lgkmcnt(0)
	s_barrier
	s_waitcnt lgkmcnt(0)
	v_mfma_f32_16x16x32_bf16 v[62:65], v[152:155], v[190:193], v[62:65]
	v_mfma_f32_16x16x32_bf16 v[62:65], v[156:159], v[194:197], v[62:65]
	v_mfma_f32_16x16x32_bf16 v[58:61], v[170:173], v[194:197], v[58:61]
	v_mfma_f32_16x16x32_bf16 v[58:61], v[166:169], v[190:193], v[58:61]
	v_mfma_f32_16x16x32_bf16 v[46:49], v[166:169], v[198:201], v[46:49]
	v_mfma_f32_16x16x32_bf16 v[46:49], v[170:173], v[202:205], v[46:49]
	v_mfma_f32_16x16x32_bf16 v[54:57], v[156:159], v[202:205], v[54:57]
	v_mfma_f32_16x16x32_bf16 v[54:57], v[152:155], v[198:201], v[54:57]
	v_mfma_f32_16x16x32_bf16 v[38:41], v[152:155], v[206:209], v[38:41]
	v_mfma_f32_16x16x32_bf16 v[38:41], v[156:159], v[210:213], v[38:41]
	v_mfma_f32_16x16x32_bf16 v[30:33], v[170:173], v[210:213], v[30:33]
	v_mfma_f32_16x16x32_bf16 v[30:33], v[166:169], v[206:209], v[30:33]
	v_mfma_f32_16x16x32_bf16 v[14:17], v[166:169], v[214:217], v[14:17]
	v_mfma_f32_16x16x32_bf16 v[14:17], v[170:173], v[218:221], v[14:17]
	v_mfma_f32_16x16x32_bf16 v[22:25], v[156:159], v[218:221], v[22:25]
	v_mfma_f32_16x16x32_bf16 v[22:25], v[152:155], v[214:217], v[22:25]
	v_mfma_f32_16x16x32_bf16 v[50:53], v[174:177], v[190:193], v[50:53]
	v_mfma_f32_16x16x32_bf16 v[50:53], v[178:181], v[194:197], v[50:53]
	v_mfma_f32_16x16x32_bf16 v[42:45], v[186:189], v[194:197], v[42:45]
	v_mfma_f32_16x16x32_bf16 v[42:45], v[182:185], v[190:193], v[42:45]
	v_mfma_f32_16x16x32_bf16 v[26:29], v[182:185], v[198:201], v[26:29]
	v_mfma_f32_16x16x32_bf16 v[26:29], v[186:189], v[202:205], v[26:29]
	v_mfma_f32_16x16x32_bf16 v[34:37], v[178:181], v[202:205], v[34:37]
	v_mfma_f32_16x16x32_bf16 v[34:37], v[174:177], v[198:201], v[34:37]
	v_mfma_f32_16x16x32_bf16 v[18:21], v[174:177], v[206:209], v[18:21]
	v_mfma_f32_16x16x32_bf16 v[18:21], v[178:181], v[210:213], v[18:21]
	v_mfma_f32_16x16x32_bf16 v[10:13], v[186:189], v[210:213], v[10:13]
	v_mfma_f32_16x16x32_bf16 v[10:13], v[182:185], v[206:209], v[10:13]
	v_mfma_f32_16x16x32_bf16 v[2:5], v[182:185], v[214:217], v[2:5]
	v_mfma_f32_16x16x32_bf16 v[2:5], v[186:189], v[218:221], v[2:5]
	v_mfma_f32_16x16x32_bf16 v[6:9], v[178:181], v[218:221], v[6:9]
	v_mfma_f32_16x16x32_bf16 v[6:9], v[174:177], v[214:217], v[6:9]
	s_barrier
	s_add_i32 s72, s72, 2
	s_add_u32 s54, s54, 0x100
	s_addc_u32 s55, s55, 0
	s_add_u32 s70, s70, 0x100
	s_addc_u32 s71, s71, 0
	s_cmp_gt_u32 s72, 61
	s_cbranch_scc0 .LBB0_472
	s_and_b64 vcc, exec, s[12:13]
	s_cbranch_vccz .LBB0_475
	s_barrier

.LBB0_706:
	s_add_u32 s72, s60, s44
	s_addc_u32 s73, s61, 0
	s_add_u32 s68, s72, 0x100
	s_addc_u32 s69, s73, 0
	s_and_b64 s[66:67], s[64:65], exec
	s_cselect_b32 s69, s17, s69
	s_cselect_b32 s68, s86, s68
	s_add_u32 s44, s56, s44
	s_addc_u32 s66, s57, 0
	s_add_u32 s44, s44, 0x100
	s_addc_u32 s66, s66, 0
	s_and_b64 s[64:65], s[64:65], exec
	s_cselect_b32 s71, s15, s66
	s_cselect_b32 s70, s87, s44
	s_add_u32 s74, s72, 0x10080
	s_addc_u32 s75, s73, 0
	s_add_i32 vcc_hi, s82, s27
	ds_read_b128 v[150:153], v147
	ds_read_b128 v[154:157], v147 offset:1024
	ds_read_b128 v[158:161], v147 offset:2048
	ds_read_b128 v[166:169], v147 offset:3072
	ds_read_b128 v[170:173], v148
	ds_read_b128 v[174:177], v148 offset:1024
	ds_read_b128 v[178:181], v148 offset:2048
	ds_read_b128 v[182:185], v148 offset:3072
	s_add_i32 m0, s36, 0xc000
	s_add_i32 s45, s36, 0xe000
	s_add_i32 s96, vcc_hi, 0x2000
	s_add_u32 s72, s70, 0x10000
	s_addc_u32 s73, s71, 0
	s_add_i32 vcc_lo, s83, s27
	s_add_i32 s97, vcc_lo, 0x2000
	s_add_i32 s95, 0, 0x18000
	s_add_i32 s94, 0, 0x1c000
	s_add_u32 s66, s68, 0x10000
	s_addc_u32 s67, s69, 0
	s_add_i32 s93, s95, s27
	s_add_i32 s89, s93, 0x2000
	s_add_u32 s64, s70, 0x10080
	s_addc_u32 s65, s71, 0
	s_add_i32 s92, s94, s27
	s_add_i32 s44, s92, 0x2000
	v_lshl_add_u64 v[198:199], s[74:75], 0, v[130:131]
	ds_read_b128 v[186:189], v149
	ds_read_b128 v[190:193], v149 offset:1024
	ds_read_b128 v[194:197], v149 offset:2048
	ds_read_b128 v[202:205], v149 offset:3072
	ds_read_b128 v[206:209], v149 offset:4096
	ds_read_b128 v[210:213], v149 offset:5120
	ds_read_b128 v[214:217], v149 offset:6144
	ds_read_b128 v[218:221], v149 offset:7168
	global_load_lds_dwordx4 v[198:199], off
	v_lshl_add_u64 v[198:199], s[74:75], 0, v[134:135]
	s_mov_b32 m0, s45
	s_nop 0
	global_load_lds_dwordx4 v[198:199], off
	s_waitcnt vmcnt(8)
	s_waitcnt lgkmcnt(0)
	s_barrier
	s_waitcnt lgkmcnt(0)
	v_mfma_f32_16x16x32_bf16 v[126:129], v[150:153], v[186:189], v[126:129]
	v_mfma_f32_16x16x32_bf16 v[126:129], v[154:157], v[190:193], v[126:129]
	v_mfma_f32_16x16x32_bf16 v[122:125], v[166:169], v[190:193], v[122:125]
	v_mfma_f32_16x16x32_bf16 v[122:125], v[158:161], v[186:189], v[122:125]
	v_mfma_f32_16x16x32_bf16 v[110:113], v[158:161], v[194:197], v[110:113]
	v_mfma_f32_16x16x32_bf16 v[110:113], v[166:169], v[202:205], v[110:113]
	v_mfma_f32_16x16x32_bf16 v[118:121], v[154:157], v[202:205], v[118:121]
	v_mfma_f32_16x16x32_bf16 v[118:121], v[150:153], v[194:197], v[118:121]
	v_mfma_f32_16x16x32_bf16 v[102:105], v[150:153], v[206:209], v[102:105]
	v_mfma_f32_16x16x32_bf16 v[102:105], v[154:157], v[210:213], v[102:105]
	v_mfma_f32_16x16x32_bf16 v[94:97], v[166:169], v[210:213], v[94:97]
	v_mfma_f32_16x16x32_bf16 v[94:97], v[158:161], v[206:209], v[94:97]
	v_mfma_f32_16x16x32_bf16 v[78:81], v[158:161], v[214:217], v[78:81]
	v_mfma_f32_16x16x32_bf16 v[78:81], v[166:169], v[218:221], v[78:81]
	v_mfma_f32_16x16x32_bf16 v[86:89], v[154:157], v[218:221], v[86:89]
	v_mfma_f32_16x16x32_bf16 v[86:89], v[150:153], v[214:217], v[86:89]
	v_mfma_f32_16x16x32_bf16 v[114:117], v[170:173], v[186:189], v[114:117]
	v_mfma_f32_16x16x32_bf16 v[114:117], v[174:177], v[190:193], v[114:117]
	v_mfma_f32_16x16x32_bf16 v[106:109], v[182:185], v[190:193], v[106:109]
	v_mfma_f32_16x16x32_bf16 v[106:109], v[178:181], v[186:189], v[106:109]
	v_mfma_f32_16x16x32_bf16 v[90:93], v[178:181], v[194:197], v[90:93]
	v_mfma_f32_16x16x32_bf16 v[90:93], v[182:185], v[202:205], v[90:93]
	v_mfma_f32_16x16x32_bf16 v[98:101], v[174:177], v[202:205], v[98:101]
	v_mfma_f32_16x16x32_bf16 v[98:101], v[170:173], v[194:197], v[98:101]
	v_mfma_f32_16x16x32_bf16 v[82:85], v[170:173], v[206:209], v[82:85]
	v_mfma_f32_16x16x32_bf16 v[82:85], v[174:177], v[210:213], v[82:85]
	v_mfma_f32_16x16x32_bf16 v[74:77], v[182:185], v[210:213], v[74:77]
	v_mfma_f32_16x16x32_bf16 v[74:77], v[178:181], v[206:209], v[74:77]
	v_mfma_f32_16x16x32_bf16 v[66:69], v[178:181], v[214:217], v[66:69]
	v_mfma_f32_16x16x32_bf16 v[66:69], v[182:185], v[218:221], v[66:69]
	v_mfma_f32_16x16x32_bf16 v[70:73], v[174:177], v[218:221], v[70:73]
	v_mfma_f32_16x16x32_bf16 v[70:73], v[170:173], v[214:217], v[70:73]
	s_barrier
	s_mov_b32 m0, vcc_hi
	v_lshl_add_u64 v[198:199], s[70:71], 0, v[132:133]
	ds_read_b128 v[186:189], v149 offset:16384
	ds_read_b128 v[190:193], v149 offset:17408
	ds_read_b128 v[194:197], v149 offset:18432
	ds_read_b128 v[202:205], v149 offset:19456
	ds_read_b128 v[206:209], v149 offset:20480
	ds_read_b128 v[210:213], v149 offset:21504
	ds_read_b128 v[214:217], v149 offset:22528
	ds_read_b128 v[218:221], v149 offset:23552
	global_load_lds_dwordx4 v[198:199], off
	v_lshl_add_u64 v[222:223], s[70:71], 0, v[136:137]
	s_mov_b32 m0, s96
	v_lshl_add_u64 v[224:225], s[72:73], 0, v[132:133]
	global_load_lds_dwordx4 v[222:223], off
	s_mov_b32 m0, vcc_lo
	v_lshl_add_u64 v[226:227], s[68:69], 0, v[134:135]
	global_load_lds_dwordx4 v[224:225], off
	v_lshl_add_u64 v[224:225], s[72:73], 0, v[136:137]
	s_mov_b32 m0, s97
	s_nop 0
	global_load_lds_dwordx4 v[224:225], off
	v_lshl_add_u64 v[224:225], s[68:69], 0, v[130:131]
	s_mov_b32 m0, s36
	s_nop 0
	global_load_lds_dwordx4 v[224:225], off
	s_mov_b32 m0, s55
	s_nop 0
	global_load_lds_dwordx4 v[226:227], off
	s_waitcnt vmcnt(8)
	s_waitcnt lgkmcnt(0)
	s_barrier
	s_waitcnt lgkmcnt(0)
	v_mfma_f32_16x16x32_bf16 v[62:65], v[150:153], v[186:189], v[62:65]
	v_mfma_f32_16x16x32_bf16 v[62:65], v[154:157], v[190:193], v[62:65]
	v_mfma_f32_16x16x32_bf16 v[58:61], v[166:169], v[190:193], v[58:61]
	v_mfma_f32_16x16x32_bf16 v[58:61], v[158:161], v[186:189], v[58:61]
	v_mfma_f32_16x16x32_bf16 v[46:49], v[158:161], v[194:197], v[46:49]
	v_mfma_f32_16x16x32_bf16 v[46:49], v[166:169], v[202:205], v[46:49]
	v_mfma_f32_16x16x32_bf16 v[54:57], v[154:157], v[202:205], v[54:57]
	v_mfma_f32_16x16x32_bf16 v[54:57], v[150:153], v[194:197], v[54:57]
	v_mfma_f32_16x16x32_bf16 v[38:41], v[150:153], v[206:209], v[38:41]
	v_mfma_f32_16x16x32_bf16 v[38:41], v[154:157], v[210:213], v[38:41]
	v_mfma_f32_16x16x32_bf16 v[30:33], v[166:169], v[210:213], v[30:33]
	v_mfma_f32_16x16x32_bf16 v[30:33], v[158:161], v[206:209], v[30:33]
	v_mfma_f32_16x16x32_bf16 v[14:17], v[158:161], v[214:217], v[14:17]
	v_mfma_f32_16x16x32_bf16 v[14:17], v[166:169], v[218:221], v[14:17]
	v_mfma_f32_16x16x32_bf16 v[22:25], v[154:157], v[218:221], v[22:25]
	v_mfma_f32_16x16x32_bf16 v[22:25], v[150:153], v[214:217], v[22:25]
	v_mfma_f32_16x16x32_bf16 v[50:53], v[170:173], v[186:189], v[50:53]
	v_mfma_f32_16x16x32_bf16 v[50:53], v[174:177], v[190:193], v[50:53]
	v_mfma_f32_16x16x32_bf16 v[42:45], v[182:185], v[190:193], v[42:45]
	v_mfma_f32_16x16x32_bf16 v[42:45], v[178:181], v[186:189], v[42:45]
	v_mfma_f32_16x16x32_bf16 v[26:29], v[178:181], v[194:197], v[26:29]
	v_mfma_f32_16x16x32_bf16 v[26:29], v[182:185], v[202:205], v[26:29]
	v_mfma_f32_16x16x32_bf16 v[34:37], v[174:177], v[202:205], v[34:37]
	v_mfma_f32_16x16x32_bf16 v[34:37], v[170:173], v[194:197], v[34:37]
	v_mfma_f32_16x16x32_bf16 v[18:21], v[170:173], v[206:209], v[18:21]
	v_mfma_f32_16x16x32_bf16 v[18:21], v[174:177], v[210:213], v[18:21]
	v_mfma_f32_16x16x32_bf16 v[10:13], v[182:185], v[210:213], v[10:13]
	v_mfma_f32_16x16x32_bf16 v[10:13], v[178:181], v[206:209], v[10:13]
	v_mfma_f32_16x16x32_bf16 v[2:5], v[178:181], v[214:217], v[2:5]
	v_mfma_f32_16x16x32_bf16 v[2:5], v[182:185], v[218:221], v[2:5]
	v_mfma_f32_16x16x32_bf16 v[6:9], v[174:177], v[218:221], v[6:9]
	v_mfma_f32_16x16x32_bf16 v[6:9], v[170:173], v[214:217], v[6:9]
	s_barrier
	v_add_u32_e32 v166, s95, v145
	v_add_u32_e32 v182, s94, v145
	ds_read_b128 v[150:153], v166
	ds_read_b128 v[154:157], v166 offset:1024
	ds_read_b128 v[158:161], v166 offset:2048
	ds_read_b128 v[166:169], v166 offset:3072
	ds_read_b128 v[170:173], v182
	ds_read_b128 v[174:177], v182 offset:1024
	ds_read_b128 v[178:181], v182 offset:2048
	ds_read_b128 v[182:185], v182 offset:3072
	s_mov_b32 m0, s76
	v_lshl_add_u64 v[228:229], s[66:67], 0, v[130:131]
	ds_read_b128 v[186:189], v149 offset:32768
	ds_read_b128 v[190:193], v149 offset:33792
	ds_read_b128 v[194:197], v149 offset:34816
	ds_read_b128 v[202:205], v149 offset:35840
	ds_read_b128 v[206:209], v149 offset:36864
	ds_read_b128 v[210:213], v149 offset:37888
	ds_read_b128 v[214:217], v149 offset:38912
	ds_read_b128 v[218:221], v149 offset:39936
	global_load_lds_dwordx4 v[228:229], off
	v_lshl_add_u64 v[228:229], s[66:67], 0, v[134:135]
	s_mov_b32 m0, s77
	s_nop 0
	global_load_lds_dwordx4 v[228:229], off
	s_waitcnt vmcnt(8)
	s_waitcnt lgkmcnt(0)
	s_barrier
	s_waitcnt lgkmcnt(0)
	v_mfma_f32_16x16x32_bf16 v[126:129], v[150:153], v[186:189], v[126:129]
	v_mfma_f32_16x16x32_bf16 v[126:129], v[154:157], v[190:193], v[126:129]
	v_mfma_f32_16x16x32_bf16 v[122:125], v[166:169], v[190:193], v[122:125]
	v_mfma_f32_16x16x32_bf16 v[122:125], v[158:161], v[186:189], v[122:125]
	v_mfma_f32_16x16x32_bf16 v[110:113], v[158:161], v[194:197], v[110:113]
	v_mfma_f32_16x16x32_bf16 v[110:113], v[166:169], v[202:205], v[110:113]
	v_mfma_f32_16x16x32_bf16 v[118:121], v[154:157], v[202:205], v[118:121]
	v_mfma_f32_16x16x32_bf16 v[118:121], v[150:153], v[194:197], v[118:121]
	v_mfma_f32_16x16x32_bf16 v[102:105], v[150:153], v[206:209], v[102:105]
	v_mfma_f32_16x16x32_bf16 v[102:105], v[154:157], v[210:213], v[102:105]
	v_mfma_f32_16x16x32_bf16 v[94:97], v[166:169], v[210:213], v[94:97]
	v_mfma_f32_16x16x32_bf16 v[94:97], v[158:161], v[206:209], v[94:97]
	v_mfma_f32_16x16x32_bf16 v[78:81], v[158:161], v[214:217], v[78:81]
	v_mfma_f32_16x16x32_bf16 v[78:81], v[166:169], v[218:221], v[78:81]
	v_mfma_f32_16x16x32_bf16 v[86:89], v[154:157], v[218:221], v[86:89]
	v_mfma_f32_16x16x32_bf16 v[86:89], v[150:153], v[214:217], v[86:89]
	v_mfma_f32_16x16x32_bf16 v[114:117], v[170:173], v[186:189], v[114:117]
	v_mfma_f32_16x16x32_bf16 v[114:117], v[174:177], v[190:193], v[114:117]
	v_mfma_f32_16x16x32_bf16 v[106:109], v[182:185], v[190:193], v[106:109]
	v_mfma_f32_16x16x32_bf16 v[106:109], v[178:181], v[186:189], v[106:109]
	v_mfma_f32_16x16x32_bf16 v[90:93], v[178:181], v[194:197], v[90:93]
	v_mfma_f32_16x16x32_bf16 v[90:93], v[182:185], v[202:205], v[90:93]
	v_mfma_f32_16x16x32_bf16 v[98:101], v[174:177], v[202:205], v[98:101]
	v_mfma_f32_16x16x32_bf16 v[98:101], v[170:173], v[194:197], v[98:101]
	v_mfma_f32_16x16x32_bf16 v[82:85], v[170:173], v[206:209], v[82:85]
	v_mfma_f32_16x16x32_bf16 v[82:85], v[174:177], v[210:213], v[82:85]
	v_mfma_f32_16x16x32_bf16 v[74:77], v[182:185], v[210:213], v[74:77]
	v_mfma_f32_16x16x32_bf16 v[74:77], v[178:181], v[206:209], v[74:77]
	v_mfma_f32_16x16x32_bf16 v[66:69], v[178:181], v[214:217], v[66:69]
	v_mfma_f32_16x16x32_bf16 v[66:69], v[182:185], v[218:221], v[66:69]
	v_mfma_f32_16x16x32_bf16 v[70:73], v[174:177], v[218:221], v[70:73]
	v_mfma_f32_16x16x32_bf16 v[70:73], v[170:173], v[214:217], v[70:73]
	s_barrier
	s_mov_b32 m0, s93
	v_lshl_add_u64 v[198:199], v[198:199], 0, s[10:11]
	ds_read_b128 v[186:189], v149 offset:49152
	ds_read_b128 v[190:193], v149 offset:50176
	ds_read_b128 v[194:197], v149 offset:51200
	ds_read_b128 v[202:205], v149 offset:52224
	ds_read_b128 v[206:209], v149 offset:53248
	ds_read_b128 v[210:213], v149 offset:54272
	ds_read_b128 v[214:217], v149 offset:55296
	ds_read_b128 v[218:221], v149 offset:56320
	global_load_lds_dwordx4 v[198:199], off
	v_lshl_add_u64 v[198:199], v[222:223], 0, s[10:11]
	s_mov_b32 m0, s89
	s_nop 0
	global_load_lds_dwordx4 v[198:199], off
	v_lshl_add_u64 v[198:199], s[64:65], 0, v[132:133]
	s_mov_b32 m0, s92
	s_nop 0
	global_load_lds_dwordx4 v[198:199], off
	v_lshl_add_u64 v[198:199], s[64:65], 0, v[136:137]
	s_mov_b32 m0, s44
	s_nop 0
	global_load_lds_dwordx4 v[198:199], off
	v_lshl_add_u64 v[198:199], v[224:225], 0, s[10:11]
	s_mov_b32 m0, s79
	s_nop 0
	global_load_lds_dwordx4 v[198:199], off
	v_lshl_add_u64 v[198:199], v[226:227], 0, s[10:11]
	s_mov_b32 m0, s80
	s_nop 0
	global_load_lds_dwordx4 v[198:199], off
	s_waitcnt vmcnt(8)
	s_waitcnt lgkmcnt(0)
	s_barrier
	s_waitcnt lgkmcnt(0)
	v_mfma_f32_16x16x32_bf16 v[62:65], v[150:153], v[186:189], v[62:65]
	v_mfma_f32_16x16x32_bf16 v[62:65], v[154:157], v[190:193], v[62:65]
	v_mfma_f32_16x16x32_bf16 v[58:61], v[166:169], v[190:193], v[58:61]
	v_mfma_f32_16x16x32_bf16 v[58:61], v[158:161], v[186:189], v[58:61]
	v_mfma_f32_16x16x32_bf16 v[46:49], v[158:161], v[194:197], v[46:49]
	v_mfma_f32_16x16x32_bf16 v[46:49], v[166:169], v[202:205], v[46:49]
	v_mfma_f32_16x16x32_bf16 v[54:57], v[154:157], v[202:205], v[54:57]
	v_mfma_f32_16x16x32_bf16 v[54:57], v[150:153], v[194:197], v[54:57]
	v_mfma_f32_16x16x32_bf16 v[38:41], v[150:153], v[206:209], v[38:41]
	v_mfma_f32_16x16x32_bf16 v[38:41], v[154:157], v[210:213], v[38:41]
	v_mfma_f32_16x16x32_bf16 v[30:33], v[166:169], v[210:213], v[30:33]
	v_mfma_f32_16x16x32_bf16 v[30:33], v[158:161], v[206:209], v[30:33]
	v_mfma_f32_16x16x32_bf16 v[14:17], v[158:161], v[214:217], v[14:17]
	v_mfma_f32_16x16x32_bf16 v[14:17], v[166:169], v[218:221], v[14:17]
	v_mfma_f32_16x16x32_bf16 v[22:25], v[154:157], v[218:221], v[22:25]
	v_mfma_f32_16x16x32_bf16 v[22:25], v[150:153], v[214:217], v[22:25]
	v_mfma_f32_16x16x32_bf16 v[50:53], v[170:173], v[186:189], v[50:53]
	v_mfma_f32_16x16x32_bf16 v[50:53], v[174:177], v[190:193], v[50:53]
	v_mfma_f32_16x16x32_bf16 v[42:45], v[182:185], v[190:193], v[42:45]
	v_mfma_f32_16x16x32_bf16 v[42:45], v[178:181], v[186:189], v[42:45]
	v_mfma_f32_16x16x32_bf16 v[26:29], v[178:181], v[194:197], v[26:29]
	v_mfma_f32_16x16x32_bf16 v[26:29], v[182:185], v[202:205], v[26:29]
	v_mfma_f32_16x16x32_bf16 v[34:37], v[174:177], v[202:205], v[34:37]
	v_mfma_f32_16x16x32_bf16 v[34:37], v[170:173], v[194:197], v[34:37]
	v_mfma_f32_16x16x32_bf16 v[18:21], v[170:173], v[206:209], v[18:21]
	v_mfma_f32_16x16x32_bf16 v[18:21], v[174:177], v[210:213], v[18:21]
	v_mfma_f32_16x16x32_bf16 v[10:13], v[182:185], v[210:213], v[10:13]
	v_mfma_f32_16x16x32_bf16 v[10:13], v[178:181], v[206:209], v[10:13]
	v_mfma_f32_16x16x32_bf16 v[2:5], v[178:181], v[214:217], v[2:5]
	v_mfma_f32_16x16x32_bf16 v[2:5], v[182:185], v[218:221], v[2:5]
	v_mfma_f32_16x16x32_bf16 v[6:9], v[174:177], v[218:221], v[6:9]
	v_mfma_f32_16x16x32_bf16 v[6:9], v[170:173], v[214:217], v[6:9]
	s_barrier
	s_movk_i32 s44, 0x100
	s_andn2_b64 vcc, exec, s[62:63]
	s_mov_b64 s[64:65], -1
	s_mov_b64 s[62:63], 0
	s_cbranch_vccz .LBB0_706
	s_and_b64 vcc, exec, s[12:13]
	s_cbranch_vccz .LBB0_709
	s_barrier

.LBB0_722:
	s_add_u32 s36, s56, s44
	s_addc_u32 s37, s57, 0
	s_add_u32 s66, s36, 0x100
	s_addc_u32 s67, s37, 0
	s_and_b64 s[64:65], s[62:63], exec
	s_cselect_b32 s67, s17, s67
	s_cselect_b32 s66, s83, s66
	s_add_u32 s44, s54, s44
	s_addc_u32 s64, s55, 0
	s_add_u32 s44, s44, 0x100
	s_addc_u32 s64, s64, 0
	s_and_b64 s[62:63], s[62:63], exec
	s_cselect_b32 s69, s15, s64
	s_cselect_b32 s68, s84, s44
	s_add_u32 s72, s36, 0x10080
	s_addc_u32 s73, s37, 0
	s_add_i32 s96, s79, s27
	ds_read_b128 v[148:151], v143
	ds_read_b128 v[152:155], v143 offset:1024
	ds_read_b128 v[156:159], v143 offset:2048
	ds_read_b128 v[166:169], v143 offset:3072
	ds_read_b128 v[170:173], v145
	ds_read_b128 v[174:177], v145 offset:1024
	ds_read_b128 v[178:181], v145 offset:2048
	ds_read_b128 v[182:185], v145 offset:3072
	s_add_i32 m0, s43, 0xc000
	s_add_i32 s97, s43, 0xe000
	s_add_i32 s93, s96, 0x2000
	s_add_u32 s70, s68, 0x10000
	s_addc_u32 s71, s69, 0
	s_add_i32 s95, s80, s27
	s_add_i32 s94, s95, 0x2000
	s_add_i32 s92, 0, 0x18000
	s_add_i32 s89, 0, 0x1c000
	s_add_u32 s64, s66, 0x10000
	s_addc_u32 s65, s67, 0
	s_add_i32 s87, s92, s27
	s_add_i32 s85, s87, 0x2000
	s_add_u32 s62, s68, 0x10080
	s_addc_u32 s63, s69, 0
	s_add_i32 s86, s89, s27
	s_add_i32 s44, s86, 0x2000
	v_lshl_add_u64 v[160:161], s[72:73], 0, v[130:131]
	ds_read_b128 v[186:189], v146
	ds_read_b128 v[190:193], v146 offset:1024
	ds_read_b128 v[194:197], v146 offset:2048
	ds_read_b128 v[202:205], v146 offset:3072
	ds_read_b128 v[206:209], v146 offset:4096
	ds_read_b128 v[210:213], v146 offset:5120
	ds_read_b128 v[214:217], v146 offset:6144
	ds_read_b128 v[218:221], v146 offset:7168
	global_load_lds_dwordx4 v[160:161], off
	v_lshl_add_u64 v[160:161], s[72:73], 0, v[134:135]
	s_mov_b32 m0, s97
	s_nop 0
	global_load_lds_dwordx4 v[160:161], off
	s_waitcnt vmcnt(8)
	s_waitcnt lgkmcnt(0)
	s_barrier
	s_waitcnt lgkmcnt(0)
	v_mfma_f32_16x16x32_bf16 v[126:129], v[148:151], v[186:189], v[126:129]
	v_mfma_f32_16x16x32_bf16 v[126:129], v[152:155], v[190:193], v[126:129]
	v_mfma_f32_16x16x32_bf16 v[122:125], v[166:169], v[190:193], v[122:125]
	v_mfma_f32_16x16x32_bf16 v[122:125], v[156:159], v[186:189], v[122:125]
	v_mfma_f32_16x16x32_bf16 v[110:113], v[156:159], v[194:197], v[110:113]
	v_mfma_f32_16x16x32_bf16 v[110:113], v[166:169], v[202:205], v[110:113]
	v_mfma_f32_16x16x32_bf16 v[118:121], v[152:155], v[202:205], v[118:121]
	v_mfma_f32_16x16x32_bf16 v[118:121], v[148:151], v[194:197], v[118:121]
	v_mfma_f32_16x16x32_bf16 v[102:105], v[148:151], v[206:209], v[102:105]
	v_mfma_f32_16x16x32_bf16 v[102:105], v[152:155], v[210:213], v[102:105]
	v_mfma_f32_16x16x32_bf16 v[94:97], v[166:169], v[210:213], v[94:97]
	v_mfma_f32_16x16x32_bf16 v[94:97], v[156:159], v[206:209], v[94:97]
	v_mfma_f32_16x16x32_bf16 v[78:81], v[156:159], v[214:217], v[78:81]
	v_mfma_f32_16x16x32_bf16 v[78:81], v[166:169], v[218:221], v[78:81]
	v_mfma_f32_16x16x32_bf16 v[86:89], v[152:155], v[218:221], v[86:89]
	v_mfma_f32_16x16x32_bf16 v[86:89], v[148:151], v[214:217], v[86:89]
	v_mfma_f32_16x16x32_bf16 v[114:117], v[170:173], v[186:189], v[114:117]
	v_mfma_f32_16x16x32_bf16 v[114:117], v[174:177], v[190:193], v[114:117]
	v_mfma_f32_16x16x32_bf16 v[106:109], v[182:185], v[190:193], v[106:109]
	v_mfma_f32_16x16x32_bf16 v[106:109], v[178:181], v[186:189], v[106:109]
	v_mfma_f32_16x16x32_bf16 v[90:93], v[178:181], v[194:197], v[90:93]
	v_mfma_f32_16x16x32_bf16 v[90:93], v[182:185], v[202:205], v[90:93]
	v_mfma_f32_16x16x32_bf16 v[98:101], v[174:177], v[202:205], v[98:101]
	v_mfma_f32_16x16x32_bf16 v[98:101], v[170:173], v[194:197], v[98:101]
	v_mfma_f32_16x16x32_bf16 v[82:85], v[170:173], v[206:209], v[82:85]
	v_mfma_f32_16x16x32_bf16 v[82:85], v[174:177], v[210:213], v[82:85]
	v_mfma_f32_16x16x32_bf16 v[74:77], v[182:185], v[210:213], v[74:77]
	v_mfma_f32_16x16x32_bf16 v[74:77], v[178:181], v[206:209], v[74:77]
	v_mfma_f32_16x16x32_bf16 v[66:69], v[178:181], v[214:217], v[66:69]
	v_mfma_f32_16x16x32_bf16 v[66:69], v[182:185], v[218:221], v[66:69]
	v_mfma_f32_16x16x32_bf16 v[70:73], v[174:177], v[218:221], v[70:73]
	v_mfma_f32_16x16x32_bf16 v[70:73], v[170:173], v[214:217], v[70:73]
	s_barrier
	s_mov_b32 m0, s96
	v_lshl_add_u64 v[160:161], s[68:69], 0, v[132:133]
	ds_read_b128 v[186:189], v146 offset:16384
	ds_read_b128 v[190:193], v146 offset:17408
	ds_read_b128 v[194:197], v146 offset:18432
	ds_read_b128 v[202:205], v146 offset:19456
	ds_read_b128 v[206:209], v146 offset:20480
	ds_read_b128 v[210:213], v146 offset:21504
	ds_read_b128 v[214:217], v146 offset:22528
	ds_read_b128 v[218:221], v146 offset:23552
	global_load_lds_dwordx4 v[160:161], off
	v_lshl_add_u64 v[198:199], s[68:69], 0, v[136:137]
	s_mov_b32 m0, s93
	v_lshl_add_u64 v[222:223], s[70:71], 0, v[132:133]
	global_load_lds_dwordx4 v[198:199], off
	s_mov_b32 m0, s95
	v_lshl_add_u64 v[224:225], s[66:67], 0, v[134:135]
	global_load_lds_dwordx4 v[222:223], off
	v_lshl_add_u64 v[222:223], s[70:71], 0, v[136:137]
	s_mov_b32 m0, s94
	s_nop 0
	global_load_lds_dwordx4 v[222:223], off
	v_lshl_add_u64 v[222:223], s[66:67], 0, v[130:131]
	s_mov_b32 m0, s43
	s_nop 0
	global_load_lds_dwordx4 v[222:223], off
	s_mov_b32 m0, s45
	s_nop 0
	global_load_lds_dwordx4 v[224:225], off
	s_waitcnt vmcnt(8)
	s_waitcnt lgkmcnt(0)
	s_barrier
	s_waitcnt lgkmcnt(0)
	v_mfma_f32_16x16x32_bf16 v[62:65], v[148:151], v[186:189], v[62:65]
	v_mfma_f32_16x16x32_bf16 v[62:65], v[152:155], v[190:193], v[62:65]
	v_mfma_f32_16x16x32_bf16 v[58:61], v[166:169], v[190:193], v[58:61]
	v_mfma_f32_16x16x32_bf16 v[58:61], v[156:159], v[186:189], v[58:61]
	v_mfma_f32_16x16x32_bf16 v[46:49], v[156:159], v[194:197], v[46:49]
	v_mfma_f32_16x16x32_bf16 v[46:49], v[166:169], v[202:205], v[46:49]
	v_mfma_f32_16x16x32_bf16 v[54:57], v[152:155], v[202:205], v[54:57]
	v_mfma_f32_16x16x32_bf16 v[54:57], v[148:151], v[194:197], v[54:57]
	v_mfma_f32_16x16x32_bf16 v[38:41], v[148:151], v[206:209], v[38:41]
	v_mfma_f32_16x16x32_bf16 v[38:41], v[152:155], v[210:213], v[38:41]
	v_mfma_f32_16x16x32_bf16 v[30:33], v[166:169], v[210:213], v[30:33]
	v_mfma_f32_16x16x32_bf16 v[30:33], v[156:159], v[206:209], v[30:33]
	v_mfma_f32_16x16x32_bf16 v[14:17], v[156:159], v[214:217], v[14:17]
	v_mfma_f32_16x16x32_bf16 v[14:17], v[166:169], v[218:221], v[14:17]
	v_mfma_f32_16x16x32_bf16 v[22:25], v[152:155], v[218:221], v[22:25]
	v_mfma_f32_16x16x32_bf16 v[22:25], v[148:151], v[214:217], v[22:25]
	v_mfma_f32_16x16x32_bf16 v[50:53], v[170:173], v[186:189], v[50:53]
	v_mfma_f32_16x16x32_bf16 v[50:53], v[174:177], v[190:193], v[50:53]
	v_mfma_f32_16x16x32_bf16 v[42:45], v[182:185], v[190:193], v[42:45]
	v_mfma_f32_16x16x32_bf16 v[42:45], v[178:181], v[186:189], v[42:45]
	v_mfma_f32_16x16x32_bf16 v[26:29], v[178:181], v[194:197], v[26:29]
	v_mfma_f32_16x16x32_bf16 v[26:29], v[182:185], v[202:205], v[26:29]
	v_mfma_f32_16x16x32_bf16 v[34:37], v[174:177], v[202:205], v[34:37]
	v_mfma_f32_16x16x32_bf16 v[34:37], v[170:173], v[194:197], v[34:37]
	v_mfma_f32_16x16x32_bf16 v[18:21], v[170:173], v[206:209], v[18:21]
	v_mfma_f32_16x16x32_bf16 v[18:21], v[174:177], v[210:213], v[18:21]
	v_mfma_f32_16x16x32_bf16 v[10:13], v[182:185], v[210:213], v[10:13]
	v_mfma_f32_16x16x32_bf16 v[10:13], v[178:181], v[206:209], v[10:13]
	v_mfma_f32_16x16x32_bf16 v[2:5], v[178:181], v[214:217], v[2:5]
	v_mfma_f32_16x16x32_bf16 v[2:5], v[182:185], v[218:221], v[2:5]
	v_mfma_f32_16x16x32_bf16 v[6:9], v[174:177], v[218:221], v[6:9]
	v_mfma_f32_16x16x32_bf16 v[6:9], v[170:173], v[214:217], v[6:9]
	s_barrier
	v_add_u32_e32 v147, s92, v142
	ds_read_b128 v[148:151], v147
	ds_read_b128 v[152:155], v147 offset:1024
	ds_read_b128 v[156:159], v147 offset:2048
	ds_read_b128 v[166:169], v147 offset:3072
	v_add_u32_e32 v147, s89, v142
	ds_read_b128 v[170:173], v147
	ds_read_b128 v[174:177], v147 offset:1024
	ds_read_b128 v[178:181], v147 offset:2048
	ds_read_b128 v[182:185], v147 offset:3072
	s_mov_b32 m0, s49
	v_lshl_add_u64 v[226:227], s[64:65], 0, v[130:131]
	ds_read_b128 v[186:189], v146 offset:32768
	ds_read_b128 v[190:193], v146 offset:33792
	ds_read_b128 v[194:197], v146 offset:34816
	ds_read_b128 v[202:205], v146 offset:35840
	ds_read_b128 v[206:209], v146 offset:36864
	ds_read_b128 v[210:213], v146 offset:37888
	ds_read_b128 v[214:217], v146 offset:38912
	ds_read_b128 v[218:221], v146 offset:39936
	global_load_lds_dwordx4 v[226:227], off
	v_lshl_add_u64 v[226:227], s[64:65], 0, v[134:135]
	s_mov_b32 m0, s74
	s_nop 0
	global_load_lds_dwordx4 v[226:227], off
	s_waitcnt vmcnt(8)
	s_waitcnt lgkmcnt(0)
	s_barrier
	s_waitcnt lgkmcnt(0)
	v_mfma_f32_16x16x32_bf16 v[126:129], v[148:151], v[186:189], v[126:129]
	v_mfma_f32_16x16x32_bf16 v[126:129], v[152:155], v[190:193], v[126:129]
	v_mfma_f32_16x16x32_bf16 v[122:125], v[166:169], v[190:193], v[122:125]
	v_mfma_f32_16x16x32_bf16 v[122:125], v[156:159], v[186:189], v[122:125]
	v_mfma_f32_16x16x32_bf16 v[110:113], v[156:159], v[194:197], v[110:113]
	v_mfma_f32_16x16x32_bf16 v[110:113], v[166:169], v[202:205], v[110:113]
	v_mfma_f32_16x16x32_bf16 v[118:121], v[152:155], v[202:205], v[118:121]
	v_mfma_f32_16x16x32_bf16 v[118:121], v[148:151], v[194:197], v[118:121]
	v_mfma_f32_16x16x32_bf16 v[102:105], v[148:151], v[206:209], v[102:105]
	v_mfma_f32_16x16x32_bf16 v[102:105], v[152:155], v[210:213], v[102:105]
	v_mfma_f32_16x16x32_bf16 v[94:97], v[166:169], v[210:213], v[94:97]
	v_mfma_f32_16x16x32_bf16 v[94:97], v[156:159], v[206:209], v[94:97]
	v_mfma_f32_16x16x32_bf16 v[78:81], v[156:159], v[214:217], v[78:81]
	v_mfma_f32_16x16x32_bf16 v[78:81], v[166:169], v[218:221], v[78:81]
	v_mfma_f32_16x16x32_bf16 v[86:89], v[152:155], v[218:221], v[86:89]
	v_mfma_f32_16x16x32_bf16 v[86:89], v[148:151], v[214:217], v[86:89]
	v_mfma_f32_16x16x32_bf16 v[114:117], v[170:173], v[186:189], v[114:117]
	v_mfma_f32_16x16x32_bf16 v[114:117], v[174:177], v[190:193], v[114:117]
	v_mfma_f32_16x16x32_bf16 v[106:109], v[182:185], v[190:193], v[106:109]
	v_mfma_f32_16x16x32_bf16 v[106:109], v[178:181], v[186:189], v[106:109]
	v_mfma_f32_16x16x32_bf16 v[90:93], v[178:181], v[194:197], v[90:93]
	v_mfma_f32_16x16x32_bf16 v[90:93], v[182:185], v[202:205], v[90:93]
	v_mfma_f32_16x16x32_bf16 v[98:101], v[174:177], v[202:205], v[98:101]
	v_mfma_f32_16x16x32_bf16 v[98:101], v[170:173], v[194:197], v[98:101]
	v_mfma_f32_16x16x32_bf16 v[82:85], v[170:173], v[206:209], v[82:85]
	v_mfma_f32_16x16x32_bf16 v[82:85], v[174:177], v[210:213], v[82:85]
	v_mfma_f32_16x16x32_bf16 v[74:77], v[182:185], v[210:213], v[74:77]
	v_mfma_f32_16x16x32_bf16 v[74:77], v[178:181], v[206:209], v[74:77]
	v_mfma_f32_16x16x32_bf16 v[66:69], v[178:181], v[214:217], v[66:69]
	v_mfma_f32_16x16x32_bf16 v[66:69], v[182:185], v[218:221], v[66:69]
	v_mfma_f32_16x16x32_bf16 v[70:73], v[174:177], v[218:221], v[70:73]
	v_mfma_f32_16x16x32_bf16 v[70:73], v[170:173], v[214:217], v[70:73]
	s_barrier
	s_mov_b32 m0, s87
	v_lshl_add_u64 v[160:161], v[160:161], 0, s[10:11]
	ds_read_b128 v[186:189], v146 offset:49152
	ds_read_b128 v[190:193], v146 offset:50176
	ds_read_b128 v[194:197], v146 offset:51200
	ds_read_b128 v[202:205], v146 offset:52224
	ds_read_b128 v[206:209], v146 offset:53248
	ds_read_b128 v[210:213], v146 offset:54272
	ds_read_b128 v[214:217], v146 offset:55296
	ds_read_b128 v[218:221], v146 offset:56320
	global_load_lds_dwordx4 v[160:161], off
	v_lshl_add_u64 v[160:161], v[198:199], 0, s[10:11]
	s_mov_b32 m0, s85
	s_nop 0
	global_load_lds_dwordx4 v[160:161], off
	v_lshl_add_u64 v[160:161], s[62:63], 0, v[132:133]
	s_mov_b32 m0, s86
	s_nop 0
	global_load_lds_dwordx4 v[160:161], off
	v_lshl_add_u64 v[160:161], s[62:63], 0, v[136:137]
	s_mov_b32 m0, s44
	s_nop 0
	global_load_lds_dwordx4 v[160:161], off
	v_lshl_add_u64 v[160:161], v[222:223], 0, s[10:11]
	s_mov_b32 m0, s76
	s_nop 0
	global_load_lds_dwordx4 v[160:161], off
	v_lshl_add_u64 v[160:161], v[224:225], 0, s[10:11]
	s_mov_b32 m0, s77
	s_nop 0
	global_load_lds_dwordx4 v[160:161], off
	s_waitcnt vmcnt(8)
	s_waitcnt lgkmcnt(0)
	s_barrier
	s_waitcnt lgkmcnt(0)
	v_mfma_f32_16x16x32_bf16 v[62:65], v[148:151], v[186:189], v[62:65]
	v_mfma_f32_16x16x32_bf16 v[62:65], v[152:155], v[190:193], v[62:65]
	v_mfma_f32_16x16x32_bf16 v[58:61], v[166:169], v[190:193], v[58:61]
	v_mfma_f32_16x16x32_bf16 v[58:61], v[156:159], v[186:189], v[58:61]
	v_mfma_f32_16x16x32_bf16 v[46:49], v[156:159], v[194:197], v[46:49]
	v_mfma_f32_16x16x32_bf16 v[46:49], v[166:169], v[202:205], v[46:49]
	v_mfma_f32_16x16x32_bf16 v[54:57], v[152:155], v[202:205], v[54:57]
	v_mfma_f32_16x16x32_bf16 v[54:57], v[148:151], v[194:197], v[54:57]
	v_mfma_f32_16x16x32_bf16 v[38:41], v[148:151], v[206:209], v[38:41]
	v_mfma_f32_16x16x32_bf16 v[38:41], v[152:155], v[210:213], v[38:41]
	v_mfma_f32_16x16x32_bf16 v[30:33], v[166:169], v[210:213], v[30:33]
	v_mfma_f32_16x16x32_bf16 v[30:33], v[156:159], v[206:209], v[30:33]
	v_mfma_f32_16x16x32_bf16 v[14:17], v[156:159], v[214:217], v[14:17]
	v_mfma_f32_16x16x32_bf16 v[14:17], v[166:169], v[218:221], v[14:17]
	v_mfma_f32_16x16x32_bf16 v[22:25], v[152:155], v[218:221], v[22:25]
	v_mfma_f32_16x16x32_bf16 v[22:25], v[148:151], v[214:217], v[22:25]
	v_mfma_f32_16x16x32_bf16 v[50:53], v[170:173], v[186:189], v[50:53]
	v_mfma_f32_16x16x32_bf16 v[50:53], v[174:177], v[190:193], v[50:53]
	v_mfma_f32_16x16x32_bf16 v[42:45], v[182:185], v[190:193], v[42:45]
	v_mfma_f32_16x16x32_bf16 v[42:45], v[178:181], v[186:189], v[42:45]
	v_mfma_f32_16x16x32_bf16 v[26:29], v[178:181], v[194:197], v[26:29]
	v_mfma_f32_16x16x32_bf16 v[26:29], v[182:185], v[202:205], v[26:29]
	v_mfma_f32_16x16x32_bf16 v[34:37], v[174:177], v[202:205], v[34:37]
	v_mfma_f32_16x16x32_bf16 v[34:37], v[170:173], v[194:197], v[34:37]
	v_mfma_f32_16x16x32_bf16 v[18:21], v[170:173], v[206:209], v[18:21]
	v_mfma_f32_16x16x32_bf16 v[18:21], v[174:177], v[210:213], v[18:21]
	v_mfma_f32_16x16x32_bf16 v[10:13], v[182:185], v[210:213], v[10:13]
	v_mfma_f32_16x16x32_bf16 v[10:13], v[178:181], v[206:209], v[10:13]
	v_mfma_f32_16x16x32_bf16 v[2:5], v[178:181], v[214:217], v[2:5]
	v_mfma_f32_16x16x32_bf16 v[2:5], v[182:185], v[218:221], v[2:5]
	v_mfma_f32_16x16x32_bf16 v[6:9], v[174:177], v[218:221], v[6:9]
	v_mfma_f32_16x16x32_bf16 v[6:9], v[170:173], v[214:217], v[6:9]
	s_barrier
	s_movk_i32 s44, 0x100
	s_andn2_b64 vcc, exec, s[60:61]
	s_mov_b64 s[62:63], -1
	s_mov_b64 s[60:61], 0
	s_cbranch_vccz .LBB0_722
	s_and_b64 vcc, exec, s[12:13]
	s_cbranch_vccz .LBB0_725
	s_barrier

.LBB0_1226:
	v_add_u32_e32 v3, s71, v165
	ds_read_b128 v[150:153], v3
	ds_read_b128 v[154:157], v3 offset:1024
	ds_read_b128 v[158:161], v3 offset:2048
	ds_read_b128 v[170:173], v3 offset:3072
	v_add_u32_e32 v3, s72, v165
	ds_read_b128 v[174:177], v3
	ds_read_b128 v[178:181], v3 offset:1024
	ds_read_b128 v[182:185], v3 offset:2048
	ds_read_b128 v[186:189], v3 offset:3072
	s_add_u32 s36, s52, 0xfff80080
	s_addc_u32 s37, s53, -1
	s_cmp_eq_u32 s78, 28
	s_cselect_b32 s59, s21, s37
	s_cselect_b32 s58, s44, s36
	s_cselect_b32 s57, s19, s77
	s_cselect_b32 s56, s55, s76
	v_lshl_add_u64 v[4:5], s[52:53], 0, v[142:143]
	s_add_i32 m0, s63, 0xc000
	ds_read_b128 v[190:193], v169
	ds_read_b128 v[194:197], v169 offset:1024
	ds_read_b128 v[202:205], v169 offset:2048
	ds_read_b128 v[206:209], v169 offset:3072
	ds_read_b128 v[210:213], v169 offset:4096
	ds_read_b128 v[214:217], v169 offset:5120
	ds_read_b128 v[218:221], v169 offset:6144
	ds_read_b128 v[222:225], v169 offset:7168
	global_load_lds_dwordx4 v[4:5], off
	v_lshl_add_u64 v[4:5], s[52:53], 0, v[144:145]
	s_add_i32 m0, s63, 0xe000
	s_nop 0
	global_load_lds_dwordx4 v[4:5], off
	s_waitcnt vmcnt(8)
	s_waitcnt lgkmcnt(0)
	s_barrier
	s_waitcnt lgkmcnt(0)
	v_mfma_f32_16x16x32_bf16 v[130:133], v[150:153], v[190:193], v[130:133]
	v_mfma_f32_16x16x32_bf16 v[130:133], v[154:157], v[194:197], v[130:133]
	v_mfma_f32_16x16x32_bf16 v[126:129], v[170:173], v[194:197], v[126:129]
	v_mfma_f32_16x16x32_bf16 v[126:129], v[158:161], v[190:193], v[126:129]
	v_mfma_f32_16x16x32_bf16 v[118:121], v[158:161], v[202:205], v[118:121]
	v_mfma_f32_16x16x32_bf16 v[118:121], v[170:173], v[206:209], v[118:121]
	v_mfma_f32_16x16x32_bf16 v[122:125], v[154:157], v[206:209], v[122:125]
	v_mfma_f32_16x16x32_bf16 v[122:125], v[150:153], v[202:205], v[122:125]
	v_mfma_f32_16x16x32_bf16 v[114:117], v[150:153], v[210:213], v[114:117]
	v_mfma_f32_16x16x32_bf16 v[114:117], v[154:157], v[214:217], v[114:117]
	v_mfma_f32_16x16x32_bf16 v[110:113], v[170:173], v[214:217], v[110:113]
	v_mfma_f32_16x16x32_bf16 v[110:113], v[158:161], v[210:213], v[110:113]
	v_mfma_f32_16x16x32_bf16 v[102:105], v[158:161], v[218:221], v[102:105]
	v_mfma_f32_16x16x32_bf16 v[102:105], v[170:173], v[222:225], v[102:105]
	v_mfma_f32_16x16x32_bf16 v[106:109], v[154:157], v[222:225], v[106:109]
	v_mfma_f32_16x16x32_bf16 v[106:109], v[150:153], v[218:221], v[106:109]
	v_mfma_f32_16x16x32_bf16 v[98:101], v[174:177], v[190:193], v[98:101]
	v_mfma_f32_16x16x32_bf16 v[98:101], v[178:181], v[194:197], v[98:101]
	v_mfma_f32_16x16x32_bf16 v[94:97], v[186:189], v[194:197], v[94:97]
	v_mfma_f32_16x16x32_bf16 v[94:97], v[182:185], v[190:193], v[94:97]
	v_mfma_f32_16x16x32_bf16 v[86:89], v[182:185], v[202:205], v[86:89]
	v_mfma_f32_16x16x32_bf16 v[86:89], v[186:189], v[206:209], v[86:89]
	v_mfma_f32_16x16x32_bf16 v[90:93], v[178:181], v[206:209], v[90:93]
	v_mfma_f32_16x16x32_bf16 v[90:93], v[174:177], v[202:205], v[90:93]
	v_mfma_f32_16x16x32_bf16 v[82:85], v[174:177], v[210:213], v[82:85]
	v_mfma_f32_16x16x32_bf16 v[82:85], v[178:181], v[214:217], v[82:85]
	v_mfma_f32_16x16x32_bf16 v[78:81], v[186:189], v[214:217], v[78:81]
	v_mfma_f32_16x16x32_bf16 v[78:81], v[182:185], v[210:213], v[78:81]
	v_mfma_f32_16x16x32_bf16 v[70:73], v[182:185], v[218:221], v[70:73]
	v_mfma_f32_16x16x32_bf16 v[70:73], v[186:189], v[222:225], v[70:73]
	v_mfma_f32_16x16x32_bf16 v[74:77], v[178:181], v[222:225], v[74:77]
	v_mfma_f32_16x16x32_bf16 v[74:77], v[174:177], v[218:221], v[74:77]
	s_barrier
	s_add_i32 s36, s71, s43
	v_lshl_add_u64 v[166:167], s[56:57], 0, v[138:139]
	s_mov_b32 m0, s36
	ds_read_b128 v[190:193], v169 offset:16384
	ds_read_b128 v[194:197], v169 offset:17408
	ds_read_b128 v[202:205], v169 offset:18432
	ds_read_b128 v[206:209], v169 offset:19456
	ds_read_b128 v[210:213], v169 offset:20480
	ds_read_b128 v[214:217], v169 offset:21504
	ds_read_b128 v[218:221], v169 offset:22528
	ds_read_b128 v[222:225], v169 offset:23552
	global_load_lds_dwordx4 v[166:167], off
	s_add_i32 m0, s36, 0x2000
	s_add_u32 s80, s56, 0x80000
	v_lshl_add_u64 v[198:199], s[56:57], 0, v[134:135]
	s_addc_u32 s81, s57, 0
	s_add_i32 s36, s72, s43
	global_load_lds_dwordx4 v[198:199], off
	v_lshl_add_u64 v[4:5], s[80:81], 0, v[138:139]
	s_mov_b32 m0, s36
	v_lshl_add_u64 v[226:227], s[58:59], 0, v[140:141]
	global_load_lds_dwordx4 v[4:5], off
	v_lshl_add_u64 v[4:5], s[80:81], 0, v[134:135]
	s_add_i32 m0, s36, 0x2000
	v_lshl_add_u64 v[228:229], s[58:59], 0, v[136:137]
	global_load_lds_dwordx4 v[4:5], off
	s_mov_b32 m0, s63
	s_nop 0
	global_load_lds_dwordx4 v[226:227], off
	s_mov_b32 m0, s64
	s_nop 0
	global_load_lds_dwordx4 v[228:229], off
	s_waitcnt vmcnt(8)
	s_waitcnt lgkmcnt(0)
	s_barrier
	s_waitcnt lgkmcnt(0)
	v_mfma_f32_16x16x32_bf16 v[66:69], v[150:153], v[190:193], v[66:69]
	v_mfma_f32_16x16x32_bf16 v[66:69], v[154:157], v[194:197], v[66:69]
	v_mfma_f32_16x16x32_bf16 v[62:65], v[170:173], v[194:197], v[62:65]
	v_mfma_f32_16x16x32_bf16 v[62:65], v[158:161], v[190:193], v[62:65]
	v_mfma_f32_16x16x32_bf16 v[54:57], v[158:161], v[202:205], v[54:57]
	v_mfma_f32_16x16x32_bf16 v[54:57], v[170:173], v[206:209], v[54:57]
	v_mfma_f32_16x16x32_bf16 v[58:61], v[154:157], v[206:209], v[58:61]
	v_mfma_f32_16x16x32_bf16 v[58:61], v[150:153], v[202:205], v[58:61]
	v_mfma_f32_16x16x32_bf16 v[50:53], v[150:153], v[210:213], v[50:53]
	v_mfma_f32_16x16x32_bf16 v[50:53], v[154:157], v[214:217], v[50:53]
	v_mfma_f32_16x16x32_bf16 v[46:49], v[170:173], v[214:217], v[46:49]
	v_mfma_f32_16x16x32_bf16 v[46:49], v[158:161], v[210:213], v[46:49]
	v_mfma_f32_16x16x32_bf16 v[38:41], v[158:161], v[218:221], v[38:41]
	v_mfma_f32_16x16x32_bf16 v[38:41], v[170:173], v[222:225], v[38:41]
	v_mfma_f32_16x16x32_bf16 v[42:45], v[154:157], v[222:225], v[42:45]
	v_mfma_f32_16x16x32_bf16 v[42:45], v[150:153], v[218:221], v[42:45]
	v_mfma_f32_16x16x32_bf16 v[34:37], v[174:177], v[190:193], v[34:37]
	v_mfma_f32_16x16x32_bf16 v[30:33], v[182:185], v[190:193], v[30:33]
	v_mfma_f32_16x16x32_bf16 v[26:29], v[174:177], v[202:205], v[26:29]
	v_mfma_f32_16x16x32_bf16 v[22:25], v[182:185], v[202:205], v[22:25]
	v_mfma_f32_16x16x32_bf16 v[18:21], v[174:177], v[210:213], v[18:21]
	v_mfma_f32_16x16x32_bf16 v[14:17], v[182:185], v[210:213], v[14:17]
	v_mfma_f32_16x16x32_bf16 v[10:13], v[174:177], v[218:221], v[10:13]
	v_mfma_f32_16x16x32_bf16 v[4:7], v[182:185], v[218:221], v[6:9]
	v_mfma_f32_16x16x32_bf16 v[34:37], v[178:181], v[194:197], v[34:37]
	v_mfma_f32_16x16x32_bf16 v[30:33], v[186:189], v[194:197], v[30:33]
	v_mfma_f32_16x16x32_bf16 v[26:29], v[178:181], v[206:209], v[26:29]
	v_mfma_f32_16x16x32_bf16 v[22:25], v[186:189], v[206:209], v[22:25]
	v_mfma_f32_16x16x32_bf16 v[18:21], v[178:181], v[214:217], v[18:21]
	v_mfma_f32_16x16x32_bf16 v[14:17], v[186:189], v[214:217], v[14:17]
	v_mfma_f32_16x16x32_bf16 v[10:13], v[178:181], v[222:225], v[10:13]
	v_mfma_f32_16x16x32_bf16 v[4:7], v[186:189], v[222:225], v[4:7]
	s_barrier
	s_add_i32 s36, 0, 0x18000
	v_add_u32_e32 v3, s36, v165
	s_add_i32 s37, 0, 0x1c000
	ds_read_b128 v[150:153], v3
	ds_read_b128 v[154:157], v3 offset:1024
	ds_read_b128 v[158:161], v3 offset:2048
	ds_read_b128 v[170:173], v3 offset:3072
	v_add_u32_e32 v3, s37, v165
	ds_read_b128 v[174:177], v3
	ds_read_b128 v[178:181], v3 offset:1024
	ds_read_b128 v[182:185], v3 offset:2048
	ds_read_b128 v[186:189], v3 offset:3072
	s_add_u32 s58, s58, 0x80000
	s_addc_u32 s59, s59, 0
	s_mov_b32 m0, s65
	v_lshl_add_u64 v[8:9], s[58:59], 0, v[140:141]
	ds_read_b128 v[190:193], v169 offset:32768
	ds_read_b128 v[194:197], v169 offset:33792
	ds_read_b128 v[202:205], v169 offset:34816
	ds_read_b128 v[206:209], v169 offset:35840
	ds_read_b128 v[210:213], v169 offset:36864
	ds_read_b128 v[214:217], v169 offset:37888
	ds_read_b128 v[218:221], v169 offset:38912
	ds_read_b128 v[222:225], v169 offset:39936
	global_load_lds_dwordx4 v[8:9], off
	v_lshl_add_u64 v[8:9], s[58:59], 0, v[136:137]
	s_mov_b32 m0, s66
	s_nop 0
	global_load_lds_dwordx4 v[8:9], off
	s_waitcnt vmcnt(8)
	s_waitcnt lgkmcnt(0)
	s_barrier
	s_waitcnt lgkmcnt(0)
	v_mfma_f32_16x16x32_bf16 v[130:133], v[150:153], v[190:193], v[130:133]
	v_mfma_f32_16x16x32_bf16 v[130:133], v[154:157], v[194:197], v[130:133]
	v_mfma_f32_16x16x32_bf16 v[126:129], v[170:173], v[194:197], v[126:129]
	v_mfma_f32_16x16x32_bf16 v[126:129], v[158:161], v[190:193], v[126:129]
	v_mfma_f32_16x16x32_bf16 v[118:121], v[158:161], v[202:205], v[118:121]
	v_mfma_f32_16x16x32_bf16 v[118:121], v[170:173], v[206:209], v[118:121]
	v_mfma_f32_16x16x32_bf16 v[122:125], v[154:157], v[206:209], v[122:125]
	v_mfma_f32_16x16x32_bf16 v[122:125], v[150:153], v[202:205], v[122:125]
	v_mfma_f32_16x16x32_bf16 v[114:117], v[150:153], v[210:213], v[114:117]
	v_mfma_f32_16x16x32_bf16 v[114:117], v[154:157], v[214:217], v[114:117]
	v_mfma_f32_16x16x32_bf16 v[110:113], v[170:173], v[214:217], v[110:113]
	v_mfma_f32_16x16x32_bf16 v[110:113], v[158:161], v[210:213], v[110:113]
	v_mfma_f32_16x16x32_bf16 v[102:105], v[158:161], v[218:221], v[102:105]
	v_mfma_f32_16x16x32_bf16 v[102:105], v[170:173], v[222:225], v[102:105]
	v_mfma_f32_16x16x32_bf16 v[106:109], v[154:157], v[222:225], v[106:109]
	v_mfma_f32_16x16x32_bf16 v[106:109], v[150:153], v[218:221], v[106:109]
	v_mfma_f32_16x16x32_bf16 v[98:101], v[174:177], v[190:193], v[98:101]
	v_mfma_f32_16x16x32_bf16 v[98:101], v[178:181], v[194:197], v[98:101]
	v_mfma_f32_16x16x32_bf16 v[94:97], v[186:189], v[194:197], v[94:97]
	v_mfma_f32_16x16x32_bf16 v[94:97], v[182:185], v[190:193], v[94:97]
	v_mfma_f32_16x16x32_bf16 v[86:89], v[182:185], v[202:205], v[86:89]
	v_mfma_f32_16x16x32_bf16 v[86:89], v[186:189], v[206:209], v[86:89]
	v_mfma_f32_16x16x32_bf16 v[90:93], v[178:181], v[206:209], v[90:93]
	v_mfma_f32_16x16x32_bf16 v[90:93], v[174:177], v[202:205], v[90:93]
	v_mfma_f32_16x16x32_bf16 v[82:85], v[174:177], v[210:213], v[82:85]
	v_mfma_f32_16x16x32_bf16 v[82:85], v[178:181], v[214:217], v[82:85]
	v_mfma_f32_16x16x32_bf16 v[78:81], v[186:189], v[214:217], v[78:81]
	v_mfma_f32_16x16x32_bf16 v[78:81], v[182:185], v[210:213], v[78:81]
	v_mfma_f32_16x16x32_bf16 v[70:73], v[182:185], v[218:221], v[70:73]
	v_mfma_f32_16x16x32_bf16 v[70:73], v[186:189], v[222:225], v[70:73]
	v_mfma_f32_16x16x32_bf16 v[74:77], v[178:181], v[222:225], v[74:77]
	v_mfma_f32_16x16x32_bf16 v[74:77], v[174:177], v[218:221], v[74:77]
	s_barrier
	s_add_i32 s36, s36, s43
	v_lshl_add_u64 v[8:9], v[166:167], 0, s[10:11]
	s_mov_b32 m0, s36
	ds_read_b128 v[190:193], v169 offset:49152
	ds_read_b128 v[194:197], v169 offset:50176
	ds_read_b128 v[202:205], v169 offset:51200
	ds_read_b128 v[206:209], v169 offset:52224
	ds_read_b128 v[210:213], v169 offset:53248
	ds_read_b128 v[214:217], v169 offset:54272
	ds_read_b128 v[218:221], v169 offset:55296
	ds_read_b128 v[222:225], v169 offset:56320
	global_load_lds_dwordx4 v[8:9], off
	s_add_i32 m0, s36, 0x2000
	s_add_u32 s56, s56, 0x80080
	v_lshl_add_u64 v[8:9], v[198:199], 0, s[10:11]
	s_addc_u32 s57, s57, 0
	s_add_i32 s36, s37, s43
	global_load_lds_dwordx4 v[8:9], off
	v_lshl_add_u64 v[8:9], s[56:57], 0, v[138:139]
	s_mov_b32 m0, s36
	s_nop 0
	global_load_lds_dwordx4 v[8:9], off
	v_lshl_add_u64 v[8:9], s[56:57], 0, v[134:135]
	s_add_i32 m0, s36, 0x2000
	s_nop 0
	global_load_lds_dwordx4 v[8:9], off
	v_lshl_add_u64 v[8:9], v[226:227], 0, s[10:11]
	s_mov_b32 m0, s69
	s_nop 0
	global_load_lds_dwordx4 v[8:9], off
	v_lshl_add_u64 v[8:9], v[228:229], 0, s[10:11]
	s_mov_b32 m0, s70
	s_nop 0
	global_load_lds_dwordx4 v[8:9], off
	s_waitcnt vmcnt(8)
	s_waitcnt lgkmcnt(0)
	s_barrier
	s_waitcnt lgkmcnt(0)
	v_mfma_f32_16x16x32_bf16 v[66:69], v[150:153], v[190:193], v[66:69]
	v_mfma_f32_16x16x32_bf16 v[66:69], v[154:157], v[194:197], v[66:69]
	v_mfma_f32_16x16x32_bf16 v[62:65], v[170:173], v[194:197], v[62:65]
	v_mfma_f32_16x16x32_bf16 v[62:65], v[158:161], v[190:193], v[62:65]
	v_mfma_f32_16x16x32_bf16 v[54:57], v[158:161], v[202:205], v[54:57]
	v_mfma_f32_16x16x32_bf16 v[54:57], v[170:173], v[206:209], v[54:57]
	v_mfma_f32_16x16x32_bf16 v[58:61], v[154:157], v[206:209], v[58:61]
	v_mfma_f32_16x16x32_bf16 v[58:61], v[150:153], v[202:205], v[58:61]
	v_mfma_f32_16x16x32_bf16 v[50:53], v[150:153], v[210:213], v[50:53]
	v_mfma_f32_16x16x32_bf16 v[50:53], v[154:157], v[214:217], v[50:53]
	v_mfma_f32_16x16x32_bf16 v[46:49], v[170:173], v[214:217], v[46:49]
	v_mfma_f32_16x16x32_bf16 v[46:49], v[158:161], v[210:213], v[46:49]
	v_mfma_f32_16x16x32_bf16 v[38:41], v[158:161], v[218:221], v[38:41]
	v_mfma_f32_16x16x32_bf16 v[38:41], v[170:173], v[222:225], v[38:41]
	v_mfma_f32_16x16x32_bf16 v[42:45], v[154:157], v[222:225], v[42:45]
	v_mfma_f32_16x16x32_bf16 v[42:45], v[150:153], v[218:221], v[42:45]
	v_mfma_f32_16x16x32_bf16 v[34:37], v[174:177], v[190:193], v[34:37]
	v_mfma_f32_16x16x32_bf16 v[30:33], v[182:185], v[190:193], v[30:33]
	v_mfma_f32_16x16x32_bf16 v[26:29], v[174:177], v[202:205], v[26:29]
	v_mfma_f32_16x16x32_bf16 v[22:25], v[182:185], v[202:205], v[22:25]
	v_mfma_f32_16x16x32_bf16 v[18:21], v[174:177], v[210:213], v[18:21]
	v_mfma_f32_16x16x32_bf16 v[14:17], v[182:185], v[210:213], v[14:17]
	v_mfma_f32_16x16x32_bf16 v[8:11], v[174:177], v[218:221], v[10:13]
	v_mfma_f32_16x16x32_bf16 v[4:7], v[182:185], v[218:221], v[4:7]
	v_mfma_f32_16x16x32_bf16 v[34:37], v[178:181], v[194:197], v[34:37]
	v_mfma_f32_16x16x32_bf16 v[30:33], v[186:189], v[194:197], v[30:33]
	v_mfma_f32_16x16x32_bf16 v[26:29], v[178:181], v[206:209], v[26:29]
	v_mfma_f32_16x16x32_bf16 v[22:25], v[186:189], v[206:209], v[22:25]
	v_mfma_f32_16x16x32_bf16 v[18:21], v[178:181], v[214:217], v[18:21]
	v_mfma_f32_16x16x32_bf16 v[14:17], v[186:189], v[214:217], v[14:17]
	v_mfma_f32_16x16x32_bf16 v[10:13], v[178:181], v[222:225], v[8:11]
	v_mfma_f32_16x16x32_bf16 v[6:9], v[186:189], v[222:225], v[4:7]
	s_barrier
	s_add_i32 s78, s78, 2
	s_add_u32 s52, s52, 0x100
	s_addc_u32 s53, s53, 0
	s_add_u32 s76, s76, 0x100
	s_addc_u32 s77, s77, 0
	s_cmp_gt_u32 s78, 29
	s_cbranch_scc0 .LBB0_1226
	s_and_b64 vcc, exec, s[12:13]
	s_cbranch_vccz .LBB0_1229
	s_barrier

.LBB0_1397:
	ds_read_b128 v[146:149], v154
	ds_read_b128 v[158:161], v154 offset:1024
	ds_read_b128 v[166:169], v154 offset:2048
	ds_read_b128 v[170:173], v154 offset:3072
	ds_read_b128 v[174:177], v155
	ds_read_b128 v[178:181], v155 offset:1024
	ds_read_b128 v[182:185], v155 offset:2048
	ds_read_b128 v[186:189], v155 offset:3072
	s_add_i32 s93, s44, 2
	s_add_u32 s36, s62, 0xfff00080
	s_addc_u32 s37, s63, -1
	s_cmp_eq_u32 s59, s44
	s_cselect_b32 s67, s38, s37
	s_cselect_b32 s66, s39, s36
	s_cselect_b32 s65, s51, s92
	s_cselect_b32 s64, s53, s61
	v_lshl_add_u64 v[150:151], s[62:63], 0, v[140:141]
	s_add_i32 m0, s72, 0xc000
	ds_read_b128 v[190:193], v156
	ds_read_b128 v[194:197], v156 offset:1024
	ds_read_b128 v[202:205], v156 offset:2048
	ds_read_b128 v[206:209], v156 offset:3072
	ds_read_b128 v[210:213], v156 offset:4096
	ds_read_b128 v[214:217], v156 offset:5120
	ds_read_b128 v[218:221], v156 offset:6144
	ds_read_b128 v[222:225], v156 offset:7168
	global_load_lds_dwordx4 v[150:151], off
	v_lshl_add_u64 v[150:151], s[62:63], 0, v[142:143]
	s_add_i32 m0, s72, 0xe000
	s_nop 0
	global_load_lds_dwordx4 v[150:151], off
	s_waitcnt vmcnt(8)
	s_waitcnt lgkmcnt(0)
	s_barrier
	s_waitcnt lgkmcnt(0)
	v_mfma_f32_16x16x32_bf16 v[126:129], v[146:149], v[190:193], v[126:129]
	v_mfma_f32_16x16x32_bf16 v[126:129], v[158:161], v[194:197], v[126:129]
	v_mfma_f32_16x16x32_bf16 v[122:125], v[170:173], v[194:197], v[122:125]
	v_mfma_f32_16x16x32_bf16 v[122:125], v[166:169], v[190:193], v[122:125]
	v_mfma_f32_16x16x32_bf16 v[106:109], v[166:169], v[202:205], v[106:109]
	v_mfma_f32_16x16x32_bf16 v[106:109], v[170:173], v[206:209], v[106:109]
	v_mfma_f32_16x16x32_bf16 v[110:113], v[158:161], v[206:209], v[110:113]
	v_mfma_f32_16x16x32_bf16 v[110:113], v[146:149], v[202:205], v[110:113]
	v_mfma_f32_16x16x32_bf16 v[94:97], v[146:149], v[210:213], v[94:97]
	v_mfma_f32_16x16x32_bf16 v[94:97], v[158:161], v[214:217], v[94:97]
	v_mfma_f32_16x16x32_bf16 v[90:93], v[170:173], v[214:217], v[90:93]
	v_mfma_f32_16x16x32_bf16 v[90:93], v[166:169], v[210:213], v[90:93]
	v_mfma_f32_16x16x32_bf16 v[74:77], v[166:169], v[218:221], v[74:77]
	v_mfma_f32_16x16x32_bf16 v[74:77], v[170:173], v[222:225], v[74:77]
	v_mfma_f32_16x16x32_bf16 v[78:81], v[158:161], v[222:225], v[78:81]
	v_mfma_f32_16x16x32_bf16 v[78:81], v[146:149], v[218:221], v[78:81]
	v_mfma_f32_16x16x32_bf16 v[118:121], v[174:177], v[190:193], v[118:121]
	v_mfma_f32_16x16x32_bf16 v[118:121], v[178:181], v[194:197], v[118:121]
	v_mfma_f32_16x16x32_bf16 v[114:117], v[186:189], v[194:197], v[114:117]
	v_mfma_f32_16x16x32_bf16 v[114:117], v[182:185], v[190:193], v[114:117]
	v_mfma_f32_16x16x32_bf16 v[98:101], v[182:185], v[202:205], v[98:101]
	v_mfma_f32_16x16x32_bf16 v[98:101], v[186:189], v[206:209], v[98:101]
	v_mfma_f32_16x16x32_bf16 v[102:105], v[178:181], v[206:209], v[102:105]
	v_mfma_f32_16x16x32_bf16 v[102:105], v[174:177], v[202:205], v[102:105]
	v_mfma_f32_16x16x32_bf16 v[86:89], v[174:177], v[210:213], v[86:89]
	v_mfma_f32_16x16x32_bf16 v[86:89], v[178:181], v[214:217], v[86:89]
	v_mfma_f32_16x16x32_bf16 v[82:85], v[186:189], v[214:217], v[82:85]
	v_mfma_f32_16x16x32_bf16 v[82:85], v[182:185], v[210:213], v[82:85]
	v_mfma_f32_16x16x32_bf16 v[66:69], v[182:185], v[218:221], v[66:69]
	v_mfma_f32_16x16x32_bf16 v[66:69], v[186:189], v[222:225], v[66:69]
	v_mfma_f32_16x16x32_bf16 v[70:73], v[178:181], v[222:225], v[70:73]
	v_mfma_f32_16x16x32_bf16 v[70:73], v[174:177], v[218:221], v[70:73]
	s_barrier
	s_add_i32 s36, s82, s69
	v_lshl_add_u64 v[150:151], s[64:65], 0, v[132:133]
	s_mov_b32 m0, s36
	ds_read_b128 v[190:193], v156 offset:16384
	ds_read_b128 v[194:197], v156 offset:17408
	ds_read_b128 v[202:205], v156 offset:18432
	ds_read_b128 v[206:209], v156 offset:19456
	ds_read_b128 v[210:213], v156 offset:20480
	ds_read_b128 v[214:217], v156 offset:21504
	ds_read_b128 v[218:221], v156 offset:22528
	ds_read_b128 v[222:225], v156 offset:23552
	global_load_lds_dwordx4 v[150:151], off
	s_add_i32 m0, s36, 0x2000
	s_add_u32 s94, s64, 0x100000
	v_lshl_add_u64 v[198:199], s[64:65], 0, v[136:137]
	s_addc_u32 s95, s65, 0
	s_add_i32 s36, s83, s69
	global_load_lds_dwordx4 v[198:199], off
	v_lshl_add_u64 v[226:227], s[94:95], 0, v[132:133]
	s_mov_b32 m0, s36
	v_lshl_add_u64 v[228:229], s[66:67], 0, v[134:135]
	global_load_lds_dwordx4 v[226:227], off
	v_lshl_add_u64 v[226:227], s[94:95], 0, v[136:137]
	s_add_i32 m0, s36, 0x2000
	s_nop 0
	global_load_lds_dwordx4 v[226:227], off
	v_lshl_add_u64 v[226:227], s[66:67], 0, v[130:131]
	s_mov_b32 m0, s72
	s_nop 0
	global_load_lds_dwordx4 v[226:227], off
	s_mov_b32 m0, s73
	s_nop 0
	global_load_lds_dwordx4 v[228:229], off
	s_waitcnt vmcnt(8)
	s_waitcnt lgkmcnt(0)
	s_barrier
	s_waitcnt lgkmcnt(0)
	v_mfma_f32_16x16x32_bf16 v[62:65], v[146:149], v[190:193], v[62:65]
	v_mfma_f32_16x16x32_bf16 v[62:65], v[158:161], v[194:197], v[62:65]
	v_mfma_f32_16x16x32_bf16 v[58:61], v[170:173], v[194:197], v[58:61]
	v_mfma_f32_16x16x32_bf16 v[58:61], v[166:169], v[190:193], v[58:61]
	v_mfma_f32_16x16x32_bf16 v[42:45], v[166:169], v[202:205], v[42:45]
	v_mfma_f32_16x16x32_bf16 v[42:45], v[170:173], v[206:209], v[42:45]
	v_mfma_f32_16x16x32_bf16 v[46:49], v[158:161], v[206:209], v[46:49]
	v_mfma_f32_16x16x32_bf16 v[46:49], v[146:149], v[202:205], v[46:49]
	v_mfma_f32_16x16x32_bf16 v[30:33], v[146:149], v[210:213], v[30:33]
	v_mfma_f32_16x16x32_bf16 v[30:33], v[158:161], v[214:217], v[30:33]
	v_mfma_f32_16x16x32_bf16 v[26:29], v[170:173], v[214:217], v[26:29]
	v_mfma_f32_16x16x32_bf16 v[26:29], v[166:169], v[210:213], v[26:29]
	v_mfma_f32_16x16x32_bf16 v[10:13], v[166:169], v[218:221], v[10:13]
	v_mfma_f32_16x16x32_bf16 v[10:13], v[170:173], v[222:225], v[10:13]
	v_mfma_f32_16x16x32_bf16 v[14:17], v[158:161], v[222:225], v[14:17]
	v_mfma_f32_16x16x32_bf16 v[14:17], v[146:149], v[218:221], v[14:17]
	v_mfma_f32_16x16x32_bf16 v[54:57], v[174:177], v[190:193], v[54:57]
	v_mfma_f32_16x16x32_bf16 v[54:57], v[178:181], v[194:197], v[54:57]
	v_mfma_f32_16x16x32_bf16 v[50:53], v[186:189], v[194:197], v[50:53]
	v_mfma_f32_16x16x32_bf16 v[50:53], v[182:185], v[190:193], v[50:53]
	v_mfma_f32_16x16x32_bf16 v[34:37], v[182:185], v[202:205], v[34:37]
	v_mfma_f32_16x16x32_bf16 v[34:37], v[186:189], v[206:209], v[34:37]
	v_mfma_f32_16x16x32_bf16 v[38:41], v[178:181], v[206:209], v[38:41]
	v_mfma_f32_16x16x32_bf16 v[38:41], v[174:177], v[202:205], v[38:41]
	v_mfma_f32_16x16x32_bf16 v[22:25], v[174:177], v[210:213], v[22:25]
	v_mfma_f32_16x16x32_bf16 v[22:25], v[178:181], v[214:217], v[22:25]
	v_mfma_f32_16x16x32_bf16 v[18:21], v[186:189], v[214:217], v[18:21]
	v_mfma_f32_16x16x32_bf16 v[18:21], v[182:185], v[210:213], v[18:21]
	v_mfma_f32_16x16x32_bf16 v[2:5], v[182:185], v[218:221], v[2:5]
	v_mfma_f32_16x16x32_bf16 v[2:5], v[186:189], v[222:225], v[2:5]
	v_mfma_f32_16x16x32_bf16 v[6:9], v[178:181], v[222:225], v[6:9]
	v_mfma_f32_16x16x32_bf16 v[6:9], v[174:177], v[218:221], v[6:9]
	s_barrier
	s_add_i32 s36, 0, 0x18000
	v_add_u32_e32 v138, s36, v152
	s_add_i32 s37, 0, 0x1c000
	ds_read_b128 v[146:149], v138
	ds_read_b128 v[158:161], v138 offset:1024
	ds_read_b128 v[166:169], v138 offset:2048
	ds_read_b128 v[170:173], v138 offset:3072
	v_add_u32_e32 v138, s37, v152
	ds_read_b128 v[174:177], v138
	ds_read_b128 v[178:181], v138 offset:1024
	ds_read_b128 v[182:185], v138 offset:2048
	ds_read_b128 v[186:189], v138 offset:3072
	s_add_u32 s66, s66, 0x100000
	s_addc_u32 s67, s67, 0
	s_mov_b32 m0, s74
	v_lshl_add_u64 v[230:231], s[66:67], 0, v[130:131]
	ds_read_b128 v[190:193], v156 offset:32768
	ds_read_b128 v[194:197], v156 offset:33792
	ds_read_b128 v[202:205], v156 offset:34816
	ds_read_b128 v[206:209], v156 offset:35840
	ds_read_b128 v[210:213], v156 offset:36864
	ds_read_b128 v[214:217], v156 offset:37888
	ds_read_b128 v[218:221], v156 offset:38912
	ds_read_b128 v[222:225], v156 offset:39936
	global_load_lds_dwordx4 v[230:231], off
	v_lshl_add_u64 v[230:231], s[66:67], 0, v[134:135]
	s_mov_b32 m0, s75
	s_nop 0
	global_load_lds_dwordx4 v[230:231], off
	s_waitcnt vmcnt(8)
	s_waitcnt lgkmcnt(0)
	s_barrier
	s_waitcnt lgkmcnt(0)
	v_mfma_f32_16x16x32_bf16 v[126:129], v[146:149], v[190:193], v[126:129]
	v_mfma_f32_16x16x32_bf16 v[126:129], v[158:161], v[194:197], v[126:129]
	v_mfma_f32_16x16x32_bf16 v[122:125], v[170:173], v[194:197], v[122:125]
	v_mfma_f32_16x16x32_bf16 v[122:125], v[166:169], v[190:193], v[122:125]
	v_mfma_f32_16x16x32_bf16 v[106:109], v[166:169], v[202:205], v[106:109]
	v_mfma_f32_16x16x32_bf16 v[106:109], v[170:173], v[206:209], v[106:109]
	v_mfma_f32_16x16x32_bf16 v[110:113], v[158:161], v[206:209], v[110:113]
	v_mfma_f32_16x16x32_bf16 v[110:113], v[146:149], v[202:205], v[110:113]
	v_mfma_f32_16x16x32_bf16 v[94:97], v[146:149], v[210:213], v[94:97]
	v_mfma_f32_16x16x32_bf16 v[94:97], v[158:161], v[214:217], v[94:97]
	v_mfma_f32_16x16x32_bf16 v[90:93], v[170:173], v[214:217], v[90:93]
	v_mfma_f32_16x16x32_bf16 v[90:93], v[166:169], v[210:213], v[90:93]
	v_mfma_f32_16x16x32_bf16 v[74:77], v[166:169], v[218:221], v[74:77]
	v_mfma_f32_16x16x32_bf16 v[74:77], v[170:173], v[222:225], v[74:77]
	v_mfma_f32_16x16x32_bf16 v[78:81], v[158:161], v[222:225], v[78:81]
	v_mfma_f32_16x16x32_bf16 v[78:81], v[146:149], v[218:221], v[78:81]
	v_mfma_f32_16x16x32_bf16 v[118:121], v[174:177], v[190:193], v[118:121]
	v_mfma_f32_16x16x32_bf16 v[118:121], v[178:181], v[194:197], v[118:121]
	v_mfma_f32_16x16x32_bf16 v[114:117], v[186:189], v[194:197], v[114:117]
	v_mfma_f32_16x16x32_bf16 v[114:117], v[182:185], v[190:193], v[114:117]
	v_mfma_f32_16x16x32_bf16 v[98:101], v[182:185], v[202:205], v[98:101]
	v_mfma_f32_16x16x32_bf16 v[98:101], v[186:189], v[206:209], v[98:101]
	v_mfma_f32_16x16x32_bf16 v[102:105], v[178:181], v[206:209], v[102:105]
	v_mfma_f32_16x16x32_bf16 v[102:105], v[174:177], v[202:205], v[102:105]
	v_mfma_f32_16x16x32_bf16 v[86:89], v[174:177], v[210:213], v[86:89]
	v_mfma_f32_16x16x32_bf16 v[86:89], v[178:181], v[214:217], v[86:89]
	v_mfma_f32_16x16x32_bf16 v[82:85], v[186:189], v[214:217], v[82:85]
	v_mfma_f32_16x16x32_bf16 v[82:85], v[182:185], v[210:213], v[82:85]
	v_mfma_f32_16x16x32_bf16 v[66:69], v[182:185], v[218:221], v[66:69]
	v_mfma_f32_16x16x32_bf16 v[66:69], v[186:189], v[222:225], v[66:69]
	v_mfma_f32_16x16x32_bf16 v[70:73], v[178:181], v[222:225], v[70:73]
	v_mfma_f32_16x16x32_bf16 v[70:73], v[174:177], v[218:221], v[70:73]
	s_barrier
	s_add_i32 s36, s36, s69
	v_lshl_add_u64 v[150:151], v[150:151], 0, s[16:17]
	s_mov_b32 m0, s36
	ds_read_b128 v[190:193], v156 offset:49152
	ds_read_b128 v[194:197], v156 offset:50176
	ds_read_b128 v[202:205], v156 offset:51200
	ds_read_b128 v[206:209], v156 offset:52224
	ds_read_b128 v[210:213], v156 offset:53248
	ds_read_b128 v[214:217], v156 offset:54272
	ds_read_b128 v[218:221], v156 offset:55296
	ds_read_b128 v[222:225], v156 offset:56320
	global_load_lds_dwordx4 v[150:151], off
	s_add_i32 m0, s36, 0x2000
	s_add_u32 s64, s64, 0x100080
	v_lshl_add_u64 v[150:151], v[198:199], 0, s[16:17]
	s_addc_u32 s65, s65, 0
	s_add_i32 s36, s37, s69
	global_load_lds_dwordx4 v[150:151], off
	v_lshl_add_u64 v[150:151], s[64:65], 0, v[132:133]
	s_mov_b32 m0, s36
	s_nop 0
	global_load_lds_dwordx4 v[150:151], off
	v_lshl_add_u64 v[150:151], s[64:65], 0, v[136:137]
	s_add_i32 m0, s36, 0x2000
	s_nop 0
	global_load_lds_dwordx4 v[150:151], off
	v_lshl_add_u64 v[150:151], v[226:227], 0, s[16:17]
	s_mov_b32 m0, s78
	s_nop 0
	global_load_lds_dwordx4 v[150:151], off
	v_lshl_add_u64 v[150:151], v[228:229], 0, s[16:17]
	s_mov_b32 m0, s79
	s_nop 0
	global_load_lds_dwordx4 v[150:151], off
	s_waitcnt vmcnt(8)
	s_waitcnt lgkmcnt(0)
	s_barrier
	s_waitcnt lgkmcnt(0)
	v_mfma_f32_16x16x32_bf16 v[62:65], v[146:149], v[190:193], v[62:65]
	v_mfma_f32_16x16x32_bf16 v[62:65], v[158:161], v[194:197], v[62:65]
	v_mfma_f32_16x16x32_bf16 v[58:61], v[170:173], v[194:197], v[58:61]
	v_mfma_f32_16x16x32_bf16 v[58:61], v[166:169], v[190:193], v[58:61]
	v_mfma_f32_16x16x32_bf16 v[42:45], v[166:169], v[202:205], v[42:45]
	v_mfma_f32_16x16x32_bf16 v[42:45], v[170:173], v[206:209], v[42:45]
	v_mfma_f32_16x16x32_bf16 v[46:49], v[158:161], v[206:209], v[46:49]
	v_mfma_f32_16x16x32_bf16 v[46:49], v[146:149], v[202:205], v[46:49]
	v_mfma_f32_16x16x32_bf16 v[30:33], v[146:149], v[210:213], v[30:33]
	v_mfma_f32_16x16x32_bf16 v[30:33], v[158:161], v[214:217], v[30:33]
	v_mfma_f32_16x16x32_bf16 v[26:29], v[170:173], v[214:217], v[26:29]
	v_mfma_f32_16x16x32_bf16 v[26:29], v[166:169], v[210:213], v[26:29]
	v_mfma_f32_16x16x32_bf16 v[10:13], v[166:169], v[218:221], v[10:13]
	v_mfma_f32_16x16x32_bf16 v[10:13], v[170:173], v[222:225], v[10:13]
	v_mfma_f32_16x16x32_bf16 v[14:17], v[158:161], v[222:225], v[14:17]
	v_mfma_f32_16x16x32_bf16 v[14:17], v[146:149], v[218:221], v[14:17]
	v_mfma_f32_16x16x32_bf16 v[54:57], v[174:177], v[190:193], v[54:57]
	v_mfma_f32_16x16x32_bf16 v[54:57], v[178:181], v[194:197], v[54:57]
	v_mfma_f32_16x16x32_bf16 v[50:53], v[186:189], v[194:197], v[50:53]
	v_mfma_f32_16x16x32_bf16 v[50:53], v[182:185], v[190:193], v[50:53]
	v_mfma_f32_16x16x32_bf16 v[34:37], v[182:185], v[202:205], v[34:37]
	v_mfma_f32_16x16x32_bf16 v[34:37], v[186:189], v[206:209], v[34:37]
	v_mfma_f32_16x16x32_bf16 v[38:41], v[178:181], v[206:209], v[38:41]
	v_mfma_f32_16x16x32_bf16 v[38:41], v[174:177], v[202:205], v[38:41]
	v_mfma_f32_16x16x32_bf16 v[22:25], v[174:177], v[210:213], v[22:25]
	v_mfma_f32_16x16x32_bf16 v[22:25], v[178:181], v[214:217], v[22:25]
	v_mfma_f32_16x16x32_bf16 v[18:21], v[186:189], v[214:217], v[18:21]
	v_mfma_f32_16x16x32_bf16 v[18:21], v[182:185], v[210:213], v[18:21]
	v_mfma_f32_16x16x32_bf16 v[2:5], v[182:185], v[218:221], v[2:5]
	v_mfma_f32_16x16x32_bf16 v[2:5], v[186:189], v[222:225], v[2:5]
	v_mfma_f32_16x16x32_bf16 v[6:9], v[178:181], v[222:225], v[6:9]
	v_mfma_f32_16x16x32_bf16 v[6:9], v[174:177], v[218:221], v[6:9]
	s_barrier
	s_add_u32 s62, s62, 0x100
	s_addc_u32 s63, s63, 0
	s_add_u32 s61, s61, 0x100
	s_addc_u32 s92, s92, 0
	s_cmp_ge_i32 s93, s11
	s_mov_b32 s44, s93
	s_cbranch_scc0 .LBB0_1397
	s_and_b64 vcc, exec, s[18:19]
	s_cbranch_vccz .LBB0_1400

.LBB0_1631:
	ds_read_b128 v[166:169], v158
	ds_read_b128 v[170:173], v158 offset:1024
	ds_read_b128 v[174:177], v158 offset:2048
	ds_read_b128 v[178:181], v158 offset:3072
	ds_read_b128 v[182:185], v159
	ds_read_b128 v[186:189], v159 offset:1024
	ds_read_b128 v[190:193], v159 offset:2048
	ds_read_b128 v[194:197], v159 offset:3072
	s_add_u32 s36, s54, 0xfff00080
	s_addc_u32 s37, s55, -1
	s_cmp_eq_u32 s78, 60
	s_cselect_b32 s59, s21, s37
	s_cselect_b32 s58, s74, s36
	s_cselect_b32 s57, s19, s77
	s_cselect_b32 s56, s75, s76
	v_lshl_add_u64 v[198:199], s[54:55], 0, v[140:141]
	s_add_i32 m0, s53, 0xc000
	ds_read_b128 v[202:205], v160
	ds_read_b128 v[206:209], v160 offset:1024
	ds_read_b128 v[210:213], v160 offset:2048
	ds_read_b128 v[214:217], v160 offset:3072
	ds_read_b128 v[218:221], v160 offset:4096
	ds_read_b128 v[222:225], v160 offset:5120
	ds_read_b128 v[226:229], v160 offset:6144
	ds_read_b128 v[230:233], v160 offset:7168
	global_load_lds_dwordx4 v[198:199], off
	v_lshl_add_u64 v[198:199], s[54:55], 0, v[142:143]
	s_add_i32 m0, s53, 0xe000
	s_nop 0
	global_load_lds_dwordx4 v[198:199], off
	s_waitcnt vmcnt(8)
	s_waitcnt lgkmcnt(0)
	s_barrier
	s_waitcnt lgkmcnt(0)
	v_mfma_f32_16x16x32_bf16 v[126:129], v[166:169], v[202:205], v[126:129]
	v_mfma_f32_16x16x32_bf16 v[126:129], v[170:173], v[206:209], v[126:129]
	v_mfma_f32_16x16x32_bf16 v[122:125], v[178:181], v[206:209], v[122:125]
	v_mfma_f32_16x16x32_bf16 v[122:125], v[174:177], v[202:205], v[122:125]
	v_mfma_f32_16x16x32_bf16 v[110:113], v[174:177], v[210:213], v[110:113]
	v_mfma_f32_16x16x32_bf16 v[110:113], v[178:181], v[214:217], v[110:113]
	v_mfma_f32_16x16x32_bf16 v[118:121], v[170:173], v[214:217], v[118:121]
	v_mfma_f32_16x16x32_bf16 v[118:121], v[166:169], v[210:213], v[118:121]
	v_mfma_f32_16x16x32_bf16 v[102:105], v[166:169], v[218:221], v[102:105]
	v_mfma_f32_16x16x32_bf16 v[102:105], v[170:173], v[222:225], v[102:105]
	v_mfma_f32_16x16x32_bf16 v[94:97], v[178:181], v[222:225], v[94:97]
	v_mfma_f32_16x16x32_bf16 v[94:97], v[174:177], v[218:221], v[94:97]
	v_mfma_f32_16x16x32_bf16 v[78:81], v[174:177], v[226:229], v[78:81]
	v_mfma_f32_16x16x32_bf16 v[78:81], v[178:181], v[230:233], v[78:81]
	v_mfma_f32_16x16x32_bf16 v[86:89], v[170:173], v[230:233], v[86:89]
	v_mfma_f32_16x16x32_bf16 v[86:89], v[166:169], v[226:229], v[86:89]
	v_mfma_f32_16x16x32_bf16 v[114:117], v[182:185], v[202:205], v[114:117]
	v_mfma_f32_16x16x32_bf16 v[114:117], v[186:189], v[206:209], v[114:117]
	v_mfma_f32_16x16x32_bf16 v[106:109], v[194:197], v[206:209], v[106:109]
	v_mfma_f32_16x16x32_bf16 v[106:109], v[190:193], v[202:205], v[106:109]
	v_mfma_f32_16x16x32_bf16 v[90:93], v[190:193], v[210:213], v[90:93]
	v_mfma_f32_16x16x32_bf16 v[90:93], v[194:197], v[214:217], v[90:93]
	v_mfma_f32_16x16x32_bf16 v[98:101], v[186:189], v[214:217], v[98:101]
	v_mfma_f32_16x16x32_bf16 v[98:101], v[182:185], v[210:213], v[98:101]
	v_mfma_f32_16x16x32_bf16 v[82:85], v[182:185], v[218:221], v[82:85]
	v_mfma_f32_16x16x32_bf16 v[82:85], v[186:189], v[222:225], v[82:85]
	v_mfma_f32_16x16x32_bf16 v[74:77], v[194:197], v[222:225], v[74:77]
	v_mfma_f32_16x16x32_bf16 v[74:77], v[190:193], v[218:221], v[74:77]
	v_mfma_f32_16x16x32_bf16 v[66:69], v[190:193], v[226:229], v[66:69]
	v_mfma_f32_16x16x32_bf16 v[66:69], v[194:197], v[230:233], v[66:69]
	v_mfma_f32_16x16x32_bf16 v[70:73], v[186:189], v[230:233], v[70:73]
	v_mfma_f32_16x16x32_bf16 v[70:73], v[182:185], v[226:229], v[70:73]
	s_barrier
	s_add_i32 s36, s68, s38
	v_lshl_add_u64 v[198:199], s[56:57], 0, v[136:137]
	s_mov_b32 m0, s36
	ds_read_b128 v[202:205], v160 offset:16384
	ds_read_b128 v[206:209], v160 offset:17408
	ds_read_b128 v[210:213], v160 offset:18432
	ds_read_b128 v[214:217], v160 offset:19456
	ds_read_b128 v[218:221], v160 offset:20480
	ds_read_b128 v[222:225], v160 offset:21504
	ds_read_b128 v[226:229], v160 offset:22528
	ds_read_b128 v[230:233], v160 offset:23552
	global_load_lds_dwordx4 v[198:199], off
	s_add_i32 m0, s36, 0x2000
	s_add_u32 s80, s56, 0x100000
	v_lshl_add_u64 v[234:235], s[56:57], 0, v[132:133]
	s_addc_u32 s81, s57, 0
	s_add_i32 s36, s69, s38
	global_load_lds_dwordx4 v[234:235], off
	v_lshl_add_u64 v[236:237], s[80:81], 0, v[136:137]
	s_mov_b32 m0, s36
	v_lshl_add_u64 v[238:239], s[58:59], 0, v[134:135]
	global_load_lds_dwordx4 v[236:237], off
	v_lshl_add_u64 v[236:237], s[80:81], 0, v[132:133]
	s_add_i32 m0, s36, 0x2000
	s_nop 0
	global_load_lds_dwordx4 v[236:237], off
	v_lshl_add_u64 v[236:237], s[58:59], 0, v[138:139]
	s_mov_b32 m0, s53
	s_nop 0
	global_load_lds_dwordx4 v[236:237], off
	s_mov_b32 m0, s61
	s_nop 0
	global_load_lds_dwordx4 v[238:239], off
	s_waitcnt vmcnt(8)
	s_waitcnt lgkmcnt(0)
	s_barrier
	s_waitcnt lgkmcnt(0)
	v_mfma_f32_16x16x32_bf16 v[62:65], v[166:169], v[202:205], v[62:65]
	v_mfma_f32_16x16x32_bf16 v[62:65], v[170:173], v[206:209], v[62:65]
	v_mfma_f32_16x16x32_bf16 v[58:61], v[178:181], v[206:209], v[58:61]
	v_mfma_f32_16x16x32_bf16 v[58:61], v[174:177], v[202:205], v[58:61]
	v_mfma_f32_16x16x32_bf16 v[46:49], v[174:177], v[210:213], v[46:49]
	v_mfma_f32_16x16x32_bf16 v[46:49], v[178:181], v[214:217], v[46:49]
	v_mfma_f32_16x16x32_bf16 v[54:57], v[170:173], v[214:217], v[54:57]
	v_mfma_f32_16x16x32_bf16 v[54:57], v[166:169], v[210:213], v[54:57]
	v_mfma_f32_16x16x32_bf16 v[38:41], v[166:169], v[218:221], v[38:41]
	v_mfma_f32_16x16x32_bf16 v[38:41], v[170:173], v[222:225], v[38:41]
	v_mfma_f32_16x16x32_bf16 v[30:33], v[178:181], v[222:225], v[30:33]
	v_mfma_f32_16x16x32_bf16 v[30:33], v[174:177], v[218:221], v[30:33]
	v_mfma_f32_16x16x32_bf16 v[14:17], v[174:177], v[226:229], v[14:17]
	v_mfma_f32_16x16x32_bf16 v[14:17], v[178:181], v[230:233], v[14:17]
	v_mfma_f32_16x16x32_bf16 v[22:25], v[170:173], v[230:233], v[22:25]
	v_mfma_f32_16x16x32_bf16 v[22:25], v[166:169], v[226:229], v[22:25]
	v_mfma_f32_16x16x32_bf16 v[50:53], v[182:185], v[202:205], v[50:53]
	v_mfma_f32_16x16x32_bf16 v[50:53], v[186:189], v[206:209], v[50:53]
	v_mfma_f32_16x16x32_bf16 v[42:45], v[194:197], v[206:209], v[42:45]
	v_mfma_f32_16x16x32_bf16 v[42:45], v[190:193], v[202:205], v[42:45]
	v_mfma_f32_16x16x32_bf16 v[26:29], v[190:193], v[210:213], v[26:29]
	v_mfma_f32_16x16x32_bf16 v[26:29], v[194:197], v[214:217], v[26:29]
	v_mfma_f32_16x16x32_bf16 v[34:37], v[186:189], v[214:217], v[34:37]
	v_mfma_f32_16x16x32_bf16 v[34:37], v[182:185], v[210:213], v[34:37]
	v_mfma_f32_16x16x32_bf16 v[18:21], v[182:185], v[218:221], v[18:21]
	v_mfma_f32_16x16x32_bf16 v[18:21], v[186:189], v[222:225], v[18:21]
	v_mfma_f32_16x16x32_bf16 v[10:13], v[194:197], v[222:225], v[10:13]
	v_mfma_f32_16x16x32_bf16 v[10:13], v[190:193], v[218:221], v[10:13]
	v_mfma_f32_16x16x32_bf16 v[2:5], v[190:193], v[226:229], v[2:5]
	v_mfma_f32_16x16x32_bf16 v[2:5], v[194:197], v[230:233], v[2:5]
	v_mfma_f32_16x16x32_bf16 v[6:9], v[186:189], v[230:233], v[6:9]
	v_mfma_f32_16x16x32_bf16 v[6:9], v[182:185], v[226:229], v[6:9]
	s_barrier
	s_add_i32 s36, 0, 0x18000
	v_add_u32_e32 v161, s36, v156
	s_add_i32 s37, 0, 0x1c000
	ds_read_b128 v[166:169], v161
	ds_read_b128 v[170:173], v161 offset:1024
	ds_read_b128 v[174:177], v161 offset:2048
	ds_read_b128 v[178:181], v161 offset:3072
	v_add_u32_e32 v161, s37, v156
	ds_read_b128 v[182:185], v161
	ds_read_b128 v[186:189], v161 offset:1024
	ds_read_b128 v[190:193], v161 offset:2048
	ds_read_b128 v[194:197], v161 offset:3072
	s_add_u32 s58, s58, 0x100000
	s_addc_u32 s59, s59, 0
	s_mov_b32 m0, s62
	v_lshl_add_u64 v[240:241], s[58:59], 0, v[138:139]
	ds_read_b128 v[202:205], v160 offset:32768
	ds_read_b128 v[206:209], v160 offset:33792
	ds_read_b128 v[210:213], v160 offset:34816
	ds_read_b128 v[214:217], v160 offset:35840
	ds_read_b128 v[218:221], v160 offset:36864
	ds_read_b128 v[222:225], v160 offset:37888
	ds_read_b128 v[226:229], v160 offset:38912
	ds_read_b128 v[230:233], v160 offset:39936
	global_load_lds_dwordx4 v[240:241], off
	v_lshl_add_u64 v[240:241], s[58:59], 0, v[134:135]
	s_mov_b32 m0, s63
	s_nop 0
	global_load_lds_dwordx4 v[240:241], off
	s_waitcnt vmcnt(8)
	s_waitcnt lgkmcnt(0)
	s_barrier
	s_waitcnt lgkmcnt(0)
	v_mfma_f32_16x16x32_bf16 v[126:129], v[166:169], v[202:205], v[126:129]
	v_mfma_f32_16x16x32_bf16 v[126:129], v[170:173], v[206:209], v[126:129]
	v_mfma_f32_16x16x32_bf16 v[122:125], v[178:181], v[206:209], v[122:125]
	v_mfma_f32_16x16x32_bf16 v[122:125], v[174:177], v[202:205], v[122:125]
	v_mfma_f32_16x16x32_bf16 v[110:113], v[174:177], v[210:213], v[110:113]
	v_mfma_f32_16x16x32_bf16 v[110:113], v[178:181], v[214:217], v[110:113]
	v_mfma_f32_16x16x32_bf16 v[118:121], v[170:173], v[214:217], v[118:121]
	v_mfma_f32_16x16x32_bf16 v[118:121], v[166:169], v[210:213], v[118:121]
	v_mfma_f32_16x16x32_bf16 v[102:105], v[166:169], v[218:221], v[102:105]
	v_mfma_f32_16x16x32_bf16 v[102:105], v[170:173], v[222:225], v[102:105]
	v_mfma_f32_16x16x32_bf16 v[94:97], v[178:181], v[222:225], v[94:97]
	v_mfma_f32_16x16x32_bf16 v[94:97], v[174:177], v[218:221], v[94:97]
	v_mfma_f32_16x16x32_bf16 v[78:81], v[174:177], v[226:229], v[78:81]
	v_mfma_f32_16x16x32_bf16 v[78:81], v[178:181], v[230:233], v[78:81]
	v_mfma_f32_16x16x32_bf16 v[86:89], v[170:173], v[230:233], v[86:89]
	v_mfma_f32_16x16x32_bf16 v[86:89], v[166:169], v[226:229], v[86:89]
	v_mfma_f32_16x16x32_bf16 v[114:117], v[182:185], v[202:205], v[114:117]
	v_mfma_f32_16x16x32_bf16 v[114:117], v[186:189], v[206:209], v[114:117]
	v_mfma_f32_16x16x32_bf16 v[106:109], v[194:197], v[206:209], v[106:109]
	v_mfma_f32_16x16x32_bf16 v[106:109], v[190:193], v[202:205], v[106:109]
	v_mfma_f32_16x16x32_bf16 v[90:93], v[190:193], v[210:213], v[90:93]
	v_mfma_f32_16x16x32_bf16 v[90:93], v[194:197], v[214:217], v[90:93]
	v_mfma_f32_16x16x32_bf16 v[98:101], v[186:189], v[214:217], v[98:101]
	v_mfma_f32_16x16x32_bf16 v[98:101], v[182:185], v[210:213], v[98:101]
	v_mfma_f32_16x16x32_bf16 v[82:85], v[182:185], v[218:221], v[82:85]
	v_mfma_f32_16x16x32_bf16 v[82:85], v[186:189], v[222:225], v[82:85]
	v_mfma_f32_16x16x32_bf16 v[74:77], v[194:197], v[222:225], v[74:77]
	v_mfma_f32_16x16x32_bf16 v[74:77], v[190:193], v[218:221], v[74:77]
	v_mfma_f32_16x16x32_bf16 v[66:69], v[190:193], v[226:229], v[66:69]
	v_mfma_f32_16x16x32_bf16 v[66:69], v[194:197], v[230:233], v[66:69]
	v_mfma_f32_16x16x32_bf16 v[70:73], v[186:189], v[230:233], v[70:73]
	v_mfma_f32_16x16x32_bf16 v[70:73], v[182:185], v[226:229], v[70:73]
	s_barrier
	s_add_i32 s36, s36, s38
	v_lshl_add_u64 v[198:199], v[198:199], 0, s[14:15]
	s_mov_b32 m0, s36
	ds_read_b128 v[202:205], v160 offset:49152
	ds_read_b128 v[206:209], v160 offset:50176
	ds_read_b128 v[210:213], v160 offset:51200
	ds_read_b128 v[214:217], v160 offset:52224
	ds_read_b128 v[218:221], v160 offset:53248
	ds_read_b128 v[222:225], v160 offset:54272
	ds_read_b128 v[226:229], v160 offset:55296
	ds_read_b128 v[230:233], v160 offset:56320
	global_load_lds_dwordx4 v[198:199], off
	s_add_i32 m0, s36, 0x2000
	s_add_u32 s56, s56, 0x100080
	v_lshl_add_u64 v[198:199], v[234:235], 0, s[14:15]
	s_addc_u32 s57, s57, 0
	s_add_i32 s36, s37, s38
	global_load_lds_dwordx4 v[198:199], off
	v_lshl_add_u64 v[198:199], s[56:57], 0, v[136:137]
	s_mov_b32 m0, s36
	s_nop 0
	global_load_lds_dwordx4 v[198:199], off
	v_lshl_add_u64 v[198:199], s[56:57], 0, v[132:133]
	s_add_i32 m0, s36, 0x2000
	s_nop 0
	global_load_lds_dwordx4 v[198:199], off
	v_lshl_add_u64 v[198:199], v[236:237], 0, s[14:15]
	s_mov_b32 m0, s65
	s_nop 0
	global_load_lds_dwordx4 v[198:199], off
	v_lshl_add_u64 v[198:199], v[238:239], 0, s[14:15]
	s_mov_b32 m0, s66
	s_nop 0
	global_load_lds_dwordx4 v[198:199], off
	s_waitcnt vmcnt(8)
	s_waitcnt lgkmcnt(0)
	s_barrier
	s_waitcnt lgkmcnt(0)
	v_mfma_f32_16x16x32_bf16 v[62:65], v[166:169], v[202:205], v[62:65]
	v_mfma_f32_16x16x32_bf16 v[62:65], v[170:173], v[206:209], v[62:65]
	v_mfma_f32_16x16x32_bf16 v[58:61], v[178:181], v[206:209], v[58:61]
	v_mfma_f32_16x16x32_bf16 v[58:61], v[174:177], v[202:205], v[58:61]
	v_mfma_f32_16x16x32_bf16 v[46:49], v[174:177], v[210:213], v[46:49]
	v_mfma_f32_16x16x32_bf16 v[46:49], v[178:181], v[214:217], v[46:49]
	v_mfma_f32_16x16x32_bf16 v[54:57], v[170:173], v[214:217], v[54:57]
	v_mfma_f32_16x16x32_bf16 v[54:57], v[166:169], v[210:213], v[54:57]
	v_mfma_f32_16x16x32_bf16 v[38:41], v[166:169], v[218:221], v[38:41]
	v_mfma_f32_16x16x32_bf16 v[38:41], v[170:173], v[222:225], v[38:41]
	v_mfma_f32_16x16x32_bf16 v[30:33], v[178:181], v[222:225], v[30:33]
	v_mfma_f32_16x16x32_bf16 v[30:33], v[174:177], v[218:221], v[30:33]
	v_mfma_f32_16x16x32_bf16 v[14:17], v[174:177], v[226:229], v[14:17]
	v_mfma_f32_16x16x32_bf16 v[14:17], v[178:181], v[230:233], v[14:17]
	v_mfma_f32_16x16x32_bf16 v[22:25], v[170:173], v[230:233], v[22:25]
	v_mfma_f32_16x16x32_bf16 v[22:25], v[166:169], v[226:229], v[22:25]
	v_mfma_f32_16x16x32_bf16 v[50:53], v[182:185], v[202:205], v[50:53]
	v_mfma_f32_16x16x32_bf16 v[50:53], v[186:189], v[206:209], v[50:53]
	v_mfma_f32_16x16x32_bf16 v[42:45], v[194:197], v[206:209], v[42:45]
	v_mfma_f32_16x16x32_bf16 v[42:45], v[190:193], v[202:205], v[42:45]
	v_mfma_f32_16x16x32_bf16 v[26:29], v[190:193], v[210:213], v[26:29]
	v_mfma_f32_16x16x32_bf16 v[26:29], v[194:197], v[214:217], v[26:29]
	v_mfma_f32_16x16x32_bf16 v[34:37], v[186:189], v[214:217], v[34:37]
	v_mfma_f32_16x16x32_bf16 v[34:37], v[182:185], v[210:213], v[34:37]
	v_mfma_f32_16x16x32_bf16 v[18:21], v[182:185], v[218:221], v[18:21]
	v_mfma_f32_16x16x32_bf16 v[18:21], v[186:189], v[222:225], v[18:21]
	v_mfma_f32_16x16x32_bf16 v[10:13], v[194:197], v[222:225], v[10:13]
	v_mfma_f32_16x16x32_bf16 v[10:13], v[190:193], v[218:221], v[10:13]
	v_mfma_f32_16x16x32_bf16 v[2:5], v[190:193], v[226:229], v[2:5]
	v_mfma_f32_16x16x32_bf16 v[2:5], v[194:197], v[230:233], v[2:5]
	v_mfma_f32_16x16x32_bf16 v[6:9], v[186:189], v[230:233], v[6:9]
	v_mfma_f32_16x16x32_bf16 v[6:9], v[182:185], v[226:229], v[6:9]
	s_barrier
	s_add_i32 s78, s78, 2
	s_add_u32 s54, s54, 0x100
	s_addc_u32 s55, s55, 0
	s_add_u32 s76, s76, 0x100
	s_addc_u32 s77, s77, 0
	s_cmp_gt_u32 s78, 61
	s_cbranch_scc0 .LBB0_1631
	s_and_b64 vcc, exec, s[16:17]
	s_cbranch_vccz .LBB0_1634
	s_barrier

.LBB0_1649:
	s_add_u32 s36, s56, s44
	s_addc_u32 s37, s57, 0
	s_add_u32 s64, s36, 0x100
	s_addc_u32 s65, s37, 0
	s_and_b64 s[62:63], s[60:61], exec
	s_cselect_b32 s65, s21, s65
	s_cselect_b32 s64, s87, s64
	s_add_u32 s44, s54, s44
	s_addc_u32 s62, s55, 0
	s_add_u32 s44, s44, 0x100
	s_addc_u32 s62, s62, 0
	s_and_b64 s[60:61], s[60:61], exec
	s_cselect_b32 s67, s19, s62
	s_cselect_b32 s66, s89, s44
	s_add_u32 s70, s36, 0x10080
	s_addc_u32 s71, s37, 0
	s_add_i32 vcc_lo, s84, s39
	ds_read_b128 v[158:161], v147
	ds_read_b128 v[166:169], v147 offset:1024
	ds_read_b128 v[170:173], v147 offset:2048
	ds_read_b128 v[174:177], v147 offset:3072
	ds_read_b128 v[178:181], v155
	ds_read_b128 v[182:185], v155 offset:1024
	ds_read_b128 v[186:189], v155 offset:2048
	ds_read_b128 v[190:193], v155 offset:3072
	s_add_i32 m0, s53, 0xc000
	s_add_i32 vcc_hi, s53, 0xe000
	s_add_i32 s95, vcc_lo, 0x2000
	s_add_u32 s68, s66, 0x10000
	s_addc_u32 s69, s67, 0
	s_add_i32 s97, s85, s39
	s_add_i32 s96, s97, 0x2000
	s_add_i32 s94, 0, 0x18000
	s_add_i32 s93, 0, 0x1c000
	s_add_u32 s62, s64, 0x10000
	s_addc_u32 s63, s65, 0
	s_add_i32 s92, s94, s39
	s_add_i32 s90, s92, 0x2000
	s_add_u32 s60, s66, 0x10080
	s_addc_u32 s61, s67, 0
	s_add_i32 s91, s93, s39
	s_add_i32 s44, s91, 0x2000
	v_lshl_add_u64 v[198:199], s[70:71], 0, v[138:139]
	ds_read_b128 v[194:197], v156
	ds_read_b128 v[202:205], v156 offset:1024
	ds_read_b128 v[206:209], v156 offset:2048
	ds_read_b128 v[210:213], v156 offset:3072
	ds_read_b128 v[214:217], v156 offset:4096
	ds_read_b128 v[218:221], v156 offset:5120
	ds_read_b128 v[222:225], v156 offset:6144
	ds_read_b128 v[226:229], v156 offset:7168
	global_load_lds_dwordx4 v[198:199], off
	v_lshl_add_u64 v[198:199], s[70:71], 0, v[134:135]
	s_mov_b32 m0, vcc_hi
	s_nop 0
	global_load_lds_dwordx4 v[198:199], off
	s_waitcnt vmcnt(8)
	s_waitcnt lgkmcnt(0)
	s_barrier
	s_waitcnt lgkmcnt(0)
	v_mfma_f32_16x16x32_bf16 v[126:129], v[158:161], v[194:197], v[126:129]
	v_mfma_f32_16x16x32_bf16 v[126:129], v[166:169], v[202:205], v[126:129]
	v_mfma_f32_16x16x32_bf16 v[122:125], v[174:177], v[202:205], v[122:125]
	v_mfma_f32_16x16x32_bf16 v[122:125], v[170:173], v[194:197], v[122:125]
	v_mfma_f32_16x16x32_bf16 v[110:113], v[170:173], v[206:209], v[110:113]
	v_mfma_f32_16x16x32_bf16 v[110:113], v[174:177], v[210:213], v[110:113]
	v_mfma_f32_16x16x32_bf16 v[118:121], v[166:169], v[210:213], v[118:121]
	v_mfma_f32_16x16x32_bf16 v[118:121], v[158:161], v[206:209], v[118:121]
	v_mfma_f32_16x16x32_bf16 v[102:105], v[158:161], v[214:217], v[102:105]
	v_mfma_f32_16x16x32_bf16 v[102:105], v[166:169], v[218:221], v[102:105]
	v_mfma_f32_16x16x32_bf16 v[94:97], v[174:177], v[218:221], v[94:97]
	v_mfma_f32_16x16x32_bf16 v[94:97], v[170:173], v[214:217], v[94:97]
	v_mfma_f32_16x16x32_bf16 v[78:81], v[170:173], v[222:225], v[78:81]
	v_mfma_f32_16x16x32_bf16 v[78:81], v[174:177], v[226:229], v[78:81]
	v_mfma_f32_16x16x32_bf16 v[86:89], v[166:169], v[226:229], v[86:89]
	v_mfma_f32_16x16x32_bf16 v[86:89], v[158:161], v[222:225], v[86:89]
	v_mfma_f32_16x16x32_bf16 v[114:117], v[178:181], v[194:197], v[114:117]
	v_mfma_f32_16x16x32_bf16 v[114:117], v[182:185], v[202:205], v[114:117]
	v_mfma_f32_16x16x32_bf16 v[106:109], v[190:193], v[202:205], v[106:109]
	v_mfma_f32_16x16x32_bf16 v[106:109], v[186:189], v[194:197], v[106:109]
	v_mfma_f32_16x16x32_bf16 v[90:93], v[186:189], v[206:209], v[90:93]
	v_mfma_f32_16x16x32_bf16 v[90:93], v[190:193], v[210:213], v[90:93]
	v_mfma_f32_16x16x32_bf16 v[98:101], v[182:185], v[210:213], v[98:101]
	v_mfma_f32_16x16x32_bf16 v[98:101], v[178:181], v[206:209], v[98:101]
	v_mfma_f32_16x16x32_bf16 v[82:85], v[178:181], v[214:217], v[82:85]
	v_mfma_f32_16x16x32_bf16 v[82:85], v[182:185], v[218:221], v[82:85]
	v_mfma_f32_16x16x32_bf16 v[74:77], v[190:193], v[218:221], v[74:77]
	v_mfma_f32_16x16x32_bf16 v[74:77], v[186:189], v[214:217], v[74:77]
	v_mfma_f32_16x16x32_bf16 v[66:69], v[186:189], v[222:225], v[66:69]
	v_mfma_f32_16x16x32_bf16 v[66:69], v[190:193], v[226:229], v[66:69]
	v_mfma_f32_16x16x32_bf16 v[70:73], v[182:185], v[226:229], v[70:73]
	v_mfma_f32_16x16x32_bf16 v[70:73], v[178:181], v[222:225], v[70:73]
	s_barrier
	s_mov_b32 m0, vcc_lo
	v_lshl_add_u64 v[198:199], s[66:67], 0, v[136:137]
	ds_read_b128 v[194:197], v156 offset:16384
	ds_read_b128 v[202:205], v156 offset:17408
	ds_read_b128 v[206:209], v156 offset:18432
	ds_read_b128 v[210:213], v156 offset:19456
	ds_read_b128 v[214:217], v156 offset:20480
	ds_read_b128 v[218:221], v156 offset:21504
	ds_read_b128 v[222:225], v156 offset:22528
	ds_read_b128 v[226:229], v156 offset:23552
	global_load_lds_dwordx4 v[198:199], off
	v_lshl_add_u64 v[230:231], s[66:67], 0, v[132:133]
	s_mov_b32 m0, s95
	v_lshl_add_u64 v[232:233], s[68:69], 0, v[136:137]
	global_load_lds_dwordx4 v[230:231], off
	s_mov_b32 m0, s97
	v_lshl_add_u64 v[234:235], s[64:65], 0, v[134:135]
	global_load_lds_dwordx4 v[232:233], off
	v_lshl_add_u64 v[232:233], s[68:69], 0, v[132:133]
	s_mov_b32 m0, s96
	s_nop 0
	global_load_lds_dwordx4 v[232:233], off
	v_lshl_add_u64 v[232:233], s[64:65], 0, v[138:139]
	s_mov_b32 m0, s53
	s_nop 0
	global_load_lds_dwordx4 v[232:233], off
	s_mov_b32 m0, s75
	s_nop 0
	global_load_lds_dwordx4 v[234:235], off
	s_waitcnt vmcnt(8)
	s_waitcnt lgkmcnt(0)
	s_barrier
	s_waitcnt lgkmcnt(0)
	v_mfma_f32_16x16x32_bf16 v[62:65], v[158:161], v[194:197], v[62:65]
	v_mfma_f32_16x16x32_bf16 v[62:65], v[166:169], v[202:205], v[62:65]
	v_mfma_f32_16x16x32_bf16 v[58:61], v[174:177], v[202:205], v[58:61]
	v_mfma_f32_16x16x32_bf16 v[58:61], v[170:173], v[194:197], v[58:61]
	v_mfma_f32_16x16x32_bf16 v[46:49], v[170:173], v[206:209], v[46:49]
	v_mfma_f32_16x16x32_bf16 v[46:49], v[174:177], v[210:213], v[46:49]
	v_mfma_f32_16x16x32_bf16 v[54:57], v[166:169], v[210:213], v[54:57]
	v_mfma_f32_16x16x32_bf16 v[54:57], v[158:161], v[206:209], v[54:57]
	v_mfma_f32_16x16x32_bf16 v[38:41], v[158:161], v[214:217], v[38:41]
	v_mfma_f32_16x16x32_bf16 v[38:41], v[166:169], v[218:221], v[38:41]
	v_mfma_f32_16x16x32_bf16 v[30:33], v[174:177], v[218:221], v[30:33]
	v_mfma_f32_16x16x32_bf16 v[30:33], v[170:173], v[214:217], v[30:33]
	v_mfma_f32_16x16x32_bf16 v[14:17], v[170:173], v[222:225], v[14:17]
	v_mfma_f32_16x16x32_bf16 v[14:17], v[174:177], v[226:229], v[14:17]
	v_mfma_f32_16x16x32_bf16 v[22:25], v[166:169], v[226:229], v[22:25]
	v_mfma_f32_16x16x32_bf16 v[22:25], v[158:161], v[222:225], v[22:25]
	v_mfma_f32_16x16x32_bf16 v[50:53], v[178:181], v[194:197], v[50:53]
	v_mfma_f32_16x16x32_bf16 v[50:53], v[182:185], v[202:205], v[50:53]
	v_mfma_f32_16x16x32_bf16 v[42:45], v[190:193], v[202:205], v[42:45]
	v_mfma_f32_16x16x32_bf16 v[42:45], v[186:189], v[194:197], v[42:45]
	v_mfma_f32_16x16x32_bf16 v[26:29], v[186:189], v[206:209], v[26:29]
	v_mfma_f32_16x16x32_bf16 v[26:29], v[190:193], v[210:213], v[26:29]
	v_mfma_f32_16x16x32_bf16 v[34:37], v[182:185], v[210:213], v[34:37]
	v_mfma_f32_16x16x32_bf16 v[34:37], v[178:181], v[206:209], v[34:37]
	v_mfma_f32_16x16x32_bf16 v[18:21], v[178:181], v[214:217], v[18:21]
	v_mfma_f32_16x16x32_bf16 v[18:21], v[182:185], v[218:221], v[18:21]
	v_mfma_f32_16x16x32_bf16 v[10:13], v[190:193], v[218:221], v[10:13]
	v_mfma_f32_16x16x32_bf16 v[10:13], v[186:189], v[214:217], v[10:13]
	v_mfma_f32_16x16x32_bf16 v[2:5], v[186:189], v[222:225], v[2:5]
	v_mfma_f32_16x16x32_bf16 v[2:5], v[190:193], v[226:229], v[2:5]
	v_mfma_f32_16x16x32_bf16 v[6:9], v[182:185], v[226:229], v[6:9]
	v_mfma_f32_16x16x32_bf16 v[6:9], v[178:181], v[222:225], v[6:9]
	s_barrier
	v_add_u32_e32 v157, s94, v145
	ds_read_b128 v[158:161], v157
	ds_read_b128 v[166:169], v157 offset:1024
	ds_read_b128 v[170:173], v157 offset:2048
	ds_read_b128 v[174:177], v157 offset:3072
	v_add_u32_e32 v157, s93, v145
	ds_read_b128 v[178:181], v157
	ds_read_b128 v[182:185], v157 offset:1024
	ds_read_b128 v[186:189], v157 offset:2048
	ds_read_b128 v[190:193], v157 offset:3072
	s_mov_b32 m0, s76
	v_lshl_add_u64 v[236:237], s[62:63], 0, v[138:139]
	ds_read_b128 v[194:197], v156 offset:32768
	ds_read_b128 v[202:205], v156 offset:33792
	ds_read_b128 v[206:209], v156 offset:34816
	ds_read_b128 v[210:213], v156 offset:35840
	ds_read_b128 v[214:217], v156 offset:36864
	ds_read_b128 v[218:221], v156 offset:37888
	ds_read_b128 v[222:225], v156 offset:38912
	ds_read_b128 v[226:229], v156 offset:39936
	global_load_lds_dwordx4 v[236:237], off
	v_lshl_add_u64 v[236:237], s[62:63], 0, v[134:135]
	s_mov_b32 m0, s77
	s_nop 0
	global_load_lds_dwordx4 v[236:237], off
	s_waitcnt vmcnt(8)
	s_waitcnt lgkmcnt(0)
	s_barrier
	s_waitcnt lgkmcnt(0)
	v_mfma_f32_16x16x32_bf16 v[126:129], v[158:161], v[194:197], v[126:129]
	v_mfma_f32_16x16x32_bf16 v[126:129], v[166:169], v[202:205], v[126:129]
	v_mfma_f32_16x16x32_bf16 v[122:125], v[174:177], v[202:205], v[122:125]
	v_mfma_f32_16x16x32_bf16 v[122:125], v[170:173], v[194:197], v[122:125]
	v_mfma_f32_16x16x32_bf16 v[110:113], v[170:173], v[206:209], v[110:113]
	v_mfma_f32_16x16x32_bf16 v[110:113], v[174:177], v[210:213], v[110:113]
	v_mfma_f32_16x16x32_bf16 v[118:121], v[166:169], v[210:213], v[118:121]
	v_mfma_f32_16x16x32_bf16 v[118:121], v[158:161], v[206:209], v[118:121]
	v_mfma_f32_16x16x32_bf16 v[102:105], v[158:161], v[214:217], v[102:105]
	v_mfma_f32_16x16x32_bf16 v[102:105], v[166:169], v[218:221], v[102:105]
	v_mfma_f32_16x16x32_bf16 v[94:97], v[174:177], v[218:221], v[94:97]
	v_mfma_f32_16x16x32_bf16 v[94:97], v[170:173], v[214:217], v[94:97]
	v_mfma_f32_16x16x32_bf16 v[78:81], v[170:173], v[222:225], v[78:81]
	v_mfma_f32_16x16x32_bf16 v[78:81], v[174:177], v[226:229], v[78:81]
	v_mfma_f32_16x16x32_bf16 v[86:89], v[166:169], v[226:229], v[86:89]
	v_mfma_f32_16x16x32_bf16 v[86:89], v[158:161], v[222:225], v[86:89]
	v_mfma_f32_16x16x32_bf16 v[114:117], v[178:181], v[194:197], v[114:117]
	v_mfma_f32_16x16x32_bf16 v[114:117], v[182:185], v[202:205], v[114:117]
	v_mfma_f32_16x16x32_bf16 v[106:109], v[190:193], v[202:205], v[106:109]
	v_mfma_f32_16x16x32_bf16 v[106:109], v[186:189], v[194:197], v[106:109]
	v_mfma_f32_16x16x32_bf16 v[90:93], v[186:189], v[206:209], v[90:93]
	v_mfma_f32_16x16x32_bf16 v[90:93], v[190:193], v[210:213], v[90:93]
	v_mfma_f32_16x16x32_bf16 v[98:101], v[182:185], v[210:213], v[98:101]
	v_mfma_f32_16x16x32_bf16 v[98:101], v[178:181], v[206:209], v[98:101]
	v_mfma_f32_16x16x32_bf16 v[82:85], v[178:181], v[214:217], v[82:85]
	v_mfma_f32_16x16x32_bf16 v[82:85], v[182:185], v[218:221], v[82:85]
	v_mfma_f32_16x16x32_bf16 v[74:77], v[190:193], v[218:221], v[74:77]
	v_mfma_f32_16x16x32_bf16 v[74:77], v[186:189], v[214:217], v[74:77]
	v_mfma_f32_16x16x32_bf16 v[66:69], v[186:189], v[222:225], v[66:69]
	v_mfma_f32_16x16x32_bf16 v[66:69], v[190:193], v[226:229], v[66:69]
	v_mfma_f32_16x16x32_bf16 v[70:73], v[182:185], v[226:229], v[70:73]
	v_mfma_f32_16x16x32_bf16 v[70:73], v[178:181], v[222:225], v[70:73]
	s_barrier
	s_mov_b32 m0, s92
	v_lshl_add_u64 v[198:199], v[198:199], 0, s[14:15]
	ds_read_b128 v[194:197], v156 offset:49152
	ds_read_b128 v[202:205], v156 offset:50176
	ds_read_b128 v[206:209], v156 offset:51200
	ds_read_b128 v[210:213], v156 offset:52224
	ds_read_b128 v[214:217], v156 offset:53248
	ds_read_b128 v[218:221], v156 offset:54272
	ds_read_b128 v[222:225], v156 offset:55296
	ds_read_b128 v[226:229], v156 offset:56320
	global_load_lds_dwordx4 v[198:199], off
	v_lshl_add_u64 v[198:199], v[230:231], 0, s[14:15]
	s_mov_b32 m0, s90
	s_nop 0
	global_load_lds_dwordx4 v[198:199], off
	v_lshl_add_u64 v[198:199], s[60:61], 0, v[136:137]
	s_mov_b32 m0, s91
	s_nop 0
	global_load_lds_dwordx4 v[198:199], off
	v_lshl_add_u64 v[198:199], s[60:61], 0, v[132:133]
	s_mov_b32 m0, s44
	s_nop 0
	global_load_lds_dwordx4 v[198:199], off
	v_lshl_add_u64 v[198:199], v[232:233], 0, s[14:15]
	s_mov_b32 m0, s80
	s_nop 0
	global_load_lds_dwordx4 v[198:199], off
	v_lshl_add_u64 v[198:199], v[234:235], 0, s[14:15]
	s_mov_b32 m0, s81
	s_nop 0
	global_load_lds_dwordx4 v[198:199], off
	s_waitcnt vmcnt(8)
	s_waitcnt lgkmcnt(0)
	s_barrier
	s_waitcnt lgkmcnt(0)
	v_mfma_f32_16x16x32_bf16 v[62:65], v[158:161], v[194:197], v[62:65]
	v_mfma_f32_16x16x32_bf16 v[62:65], v[166:169], v[202:205], v[62:65]
	v_mfma_f32_16x16x32_bf16 v[58:61], v[174:177], v[202:205], v[58:61]
	v_mfma_f32_16x16x32_bf16 v[58:61], v[170:173], v[194:197], v[58:61]
	v_mfma_f32_16x16x32_bf16 v[46:49], v[170:173], v[206:209], v[46:49]
	v_mfma_f32_16x16x32_bf16 v[46:49], v[174:177], v[210:213], v[46:49]
	v_mfma_f32_16x16x32_bf16 v[54:57], v[166:169], v[210:213], v[54:57]
	v_mfma_f32_16x16x32_bf16 v[54:57], v[158:161], v[206:209], v[54:57]
	v_mfma_f32_16x16x32_bf16 v[38:41], v[158:161], v[214:217], v[38:41]
	v_mfma_f32_16x16x32_bf16 v[38:41], v[166:169], v[218:221], v[38:41]
	v_mfma_f32_16x16x32_bf16 v[30:33], v[174:177], v[218:221], v[30:33]
	v_mfma_f32_16x16x32_bf16 v[30:33], v[170:173], v[214:217], v[30:33]
	v_mfma_f32_16x16x32_bf16 v[14:17], v[170:173], v[222:225], v[14:17]
	v_mfma_f32_16x16x32_bf16 v[14:17], v[174:177], v[226:229], v[14:17]
	v_mfma_f32_16x16x32_bf16 v[22:25], v[166:169], v[226:229], v[22:25]
	v_mfma_f32_16x16x32_bf16 v[22:25], v[158:161], v[222:225], v[22:25]
	v_mfma_f32_16x16x32_bf16 v[50:53], v[178:181], v[194:197], v[50:53]
	v_mfma_f32_16x16x32_bf16 v[50:53], v[182:185], v[202:205], v[50:53]
	v_mfma_f32_16x16x32_bf16 v[42:45], v[190:193], v[202:205], v[42:45]
	v_mfma_f32_16x16x32_bf16 v[42:45], v[186:189], v[194:197], v[42:45]
	v_mfma_f32_16x16x32_bf16 v[26:29], v[186:189], v[206:209], v[26:29]
	v_mfma_f32_16x16x32_bf16 v[26:29], v[190:193], v[210:213], v[26:29]
	v_mfma_f32_16x16x32_bf16 v[34:37], v[182:185], v[210:213], v[34:37]
	v_mfma_f32_16x16x32_bf16 v[34:37], v[178:181], v[206:209], v[34:37]
	v_mfma_f32_16x16x32_bf16 v[18:21], v[178:181], v[214:217], v[18:21]
	v_mfma_f32_16x16x32_bf16 v[18:21], v[182:185], v[218:221], v[18:21]
	v_mfma_f32_16x16x32_bf16 v[10:13], v[190:193], v[218:221], v[10:13]
	v_mfma_f32_16x16x32_bf16 v[10:13], v[186:189], v[214:217], v[10:13]
	v_mfma_f32_16x16x32_bf16 v[2:5], v[186:189], v[222:225], v[2:5]
	v_mfma_f32_16x16x32_bf16 v[2:5], v[190:193], v[226:229], v[2:5]
	v_mfma_f32_16x16x32_bf16 v[6:9], v[182:185], v[226:229], v[6:9]
	v_mfma_f32_16x16x32_bf16 v[6:9], v[178:181], v[222:225], v[6:9]
	s_barrier
	s_movk_i32 s44, 0x100
	s_andn2_b64 vcc, exec, s[58:59]
	s_mov_b64 s[60:61], -1
	s_mov_b64 s[58:59], 0
	s_cbranch_vccz .LBB0_1649
	s_and_b64 vcc, exec, s[16:17]
	s_cbranch_vccz .LBB0_1652
	s_barrier

.LBB0_1667:
	s_add_u32 s36, s56, s44
	s_addc_u32 s37, s57, 0
	s_add_u32 s64, s36, 0x100
	s_addc_u32 s65, s37, 0
	s_and_b64 s[62:63], s[60:61], exec
	s_cselect_b32 s65, s21, s65
	s_cselect_b32 s64, s86, s64
	s_add_u32 s44, s54, s44
	s_addc_u32 s62, s55, 0
	s_add_u32 s44, s44, 0x100
	s_addc_u32 s62, s62, 0
	s_and_b64 s[60:61], s[60:61], exec
	s_cselect_b32 s67, s19, s62
	s_cselect_b32 s66, s87, s44
	s_add_u32 s70, s36, 0x10080
	s_addc_u32 s71, s37, 0
	s_add_i32 s97, s82, s38
	ds_read_b128 v[150:153], v146
	ds_read_b128 v[154:157], v146 offset:1024
	ds_read_b128 v[158:161], v146 offset:2048
	ds_read_b128 v[166:169], v146 offset:3072
	ds_read_b128 v[170:173], v147
	ds_read_b128 v[174:177], v147 offset:1024
	ds_read_b128 v[178:181], v147 offset:2048
	ds_read_b128 v[182:185], v147 offset:3072
	s_add_i32 m0, s53, 0xc000
	s_add_i32 vcc_lo, s53, 0xe000
	s_add_i32 s94, s97, 0x2000
	s_add_u32 s68, s66, 0x10000
	s_addc_u32 s69, s67, 0
	s_add_i32 s96, s83, s38
	s_add_i32 s95, s96, 0x2000
	s_add_i32 s93, 0, 0x18000
	s_add_i32 s92, 0, 0x1c000
	s_add_u32 s62, s64, 0x10000
	s_addc_u32 s63, s65, 0
	s_add_i32 s91, s93, s38
	s_add_i32 s89, s91, 0x2000
	s_add_u32 s60, s66, 0x10080
	s_addc_u32 s61, s67, 0
	s_add_i32 s90, s92, s38
	s_add_i32 s44, s90, 0x2000
	v_lshl_add_u64 v[198:199], s[70:71], 0, v[138:139]
	ds_read_b128 v[186:189], v148
	ds_read_b128 v[190:193], v148 offset:1024
	ds_read_b128 v[194:197], v148 offset:2048
	ds_read_b128 v[202:205], v148 offset:3072
	ds_read_b128 v[206:209], v148 offset:4096
	ds_read_b128 v[210:213], v148 offset:5120
	ds_read_b128 v[214:217], v148 offset:6144
	ds_read_b128 v[218:221], v148 offset:7168
	global_load_lds_dwordx4 v[198:199], off
	v_lshl_add_u64 v[198:199], s[70:71], 0, v[134:135]
	s_mov_b32 m0, vcc_lo
	s_nop 0
	global_load_lds_dwordx4 v[198:199], off
	s_waitcnt vmcnt(8)
	s_waitcnt lgkmcnt(0)
	s_barrier
	s_waitcnt lgkmcnt(0)
	v_mfma_f32_16x16x32_bf16 v[126:129], v[150:153], v[186:189], v[126:129]
	v_mfma_f32_16x16x32_bf16 v[126:129], v[154:157], v[190:193], v[126:129]
	v_mfma_f32_16x16x32_bf16 v[122:125], v[166:169], v[190:193], v[122:125]
	v_mfma_f32_16x16x32_bf16 v[122:125], v[158:161], v[186:189], v[122:125]
	v_mfma_f32_16x16x32_bf16 v[110:113], v[158:161], v[194:197], v[110:113]
	v_mfma_f32_16x16x32_bf16 v[110:113], v[166:169], v[202:205], v[110:113]
	v_mfma_f32_16x16x32_bf16 v[118:121], v[154:157], v[202:205], v[118:121]
	v_mfma_f32_16x16x32_bf16 v[118:121], v[150:153], v[194:197], v[118:121]
	v_mfma_f32_16x16x32_bf16 v[102:105], v[150:153], v[206:209], v[102:105]
	v_mfma_f32_16x16x32_bf16 v[102:105], v[154:157], v[210:213], v[102:105]
	v_mfma_f32_16x16x32_bf16 v[94:97], v[166:169], v[210:213], v[94:97]
	v_mfma_f32_16x16x32_bf16 v[94:97], v[158:161], v[206:209], v[94:97]
	v_mfma_f32_16x16x32_bf16 v[78:81], v[158:161], v[214:217], v[78:81]
	v_mfma_f32_16x16x32_bf16 v[78:81], v[166:169], v[218:221], v[78:81]
	v_mfma_f32_16x16x32_bf16 v[86:89], v[154:157], v[218:221], v[86:89]
	v_mfma_f32_16x16x32_bf16 v[86:89], v[150:153], v[214:217], v[86:89]
	v_mfma_f32_16x16x32_bf16 v[114:117], v[170:173], v[186:189], v[114:117]
	v_mfma_f32_16x16x32_bf16 v[114:117], v[174:177], v[190:193], v[114:117]
	v_mfma_f32_16x16x32_bf16 v[106:109], v[182:185], v[190:193], v[106:109]
	v_mfma_f32_16x16x32_bf16 v[106:109], v[178:181], v[186:189], v[106:109]
	v_mfma_f32_16x16x32_bf16 v[90:93], v[178:181], v[194:197], v[90:93]
	v_mfma_f32_16x16x32_bf16 v[90:93], v[182:185], v[202:205], v[90:93]
	v_mfma_f32_16x16x32_bf16 v[98:101], v[174:177], v[202:205], v[98:101]
	v_mfma_f32_16x16x32_bf16 v[98:101], v[170:173], v[194:197], v[98:101]
	v_mfma_f32_16x16x32_bf16 v[82:85], v[170:173], v[206:209], v[82:85]
	v_mfma_f32_16x16x32_bf16 v[82:85], v[174:177], v[210:213], v[82:85]
	v_mfma_f32_16x16x32_bf16 v[74:77], v[182:185], v[210:213], v[74:77]
	v_mfma_f32_16x16x32_bf16 v[74:77], v[178:181], v[206:209], v[74:77]
	v_mfma_f32_16x16x32_bf16 v[66:69], v[178:181], v[214:217], v[66:69]
	v_mfma_f32_16x16x32_bf16 v[66:69], v[182:185], v[218:221], v[66:69]
	v_mfma_f32_16x16x32_bf16 v[70:73], v[174:177], v[218:221], v[70:73]
	v_mfma_f32_16x16x32_bf16 v[70:73], v[170:173], v[214:217], v[70:73]
	s_barrier
	s_mov_b32 m0, s97
	v_lshl_add_u64 v[198:199], s[66:67], 0, v[136:137]
	ds_read_b128 v[186:189], v148 offset:16384
	ds_read_b128 v[190:193], v148 offset:17408
	ds_read_b128 v[194:197], v148 offset:18432
	ds_read_b128 v[202:205], v148 offset:19456
	ds_read_b128 v[206:209], v148 offset:20480
	ds_read_b128 v[210:213], v148 offset:21504
	ds_read_b128 v[214:217], v148 offset:22528
	ds_read_b128 v[218:221], v148 offset:23552
	global_load_lds_dwordx4 v[198:199], off
	v_lshl_add_u64 v[222:223], s[66:67], 0, v[132:133]
	s_mov_b32 m0, s94
	v_lshl_add_u64 v[224:225], s[68:69], 0, v[136:137]
	global_load_lds_dwordx4 v[222:223], off
	s_mov_b32 m0, s96
	v_lshl_add_u64 v[226:227], s[64:65], 0, v[134:135]
	global_load_lds_dwordx4 v[224:225], off
	v_lshl_add_u64 v[224:225], s[68:69], 0, v[132:133]
	s_mov_b32 m0, s95
	s_nop 0
	global_load_lds_dwordx4 v[224:225], off
	v_lshl_add_u64 v[224:225], s[64:65], 0, v[138:139]
	s_mov_b32 m0, s53
	s_nop 0
	global_load_lds_dwordx4 v[224:225], off
	s_mov_b32 m0, s75
	s_nop 0
	global_load_lds_dwordx4 v[226:227], off
	s_waitcnt vmcnt(8)
	s_waitcnt lgkmcnt(0)
	s_barrier
	s_waitcnt lgkmcnt(0)
	v_mfma_f32_16x16x32_bf16 v[62:65], v[150:153], v[186:189], v[62:65]
	v_mfma_f32_16x16x32_bf16 v[62:65], v[154:157], v[190:193], v[62:65]
	v_mfma_f32_16x16x32_bf16 v[58:61], v[166:169], v[190:193], v[58:61]
	v_mfma_f32_16x16x32_bf16 v[58:61], v[158:161], v[186:189], v[58:61]
	v_mfma_f32_16x16x32_bf16 v[46:49], v[158:161], v[194:197], v[46:49]
	v_mfma_f32_16x16x32_bf16 v[46:49], v[166:169], v[202:205], v[46:49]
	v_mfma_f32_16x16x32_bf16 v[54:57], v[154:157], v[202:205], v[54:57]
	v_mfma_f32_16x16x32_bf16 v[54:57], v[150:153], v[194:197], v[54:57]
	v_mfma_f32_16x16x32_bf16 v[38:41], v[150:153], v[206:209], v[38:41]
	v_mfma_f32_16x16x32_bf16 v[38:41], v[154:157], v[210:213], v[38:41]
	v_mfma_f32_16x16x32_bf16 v[30:33], v[166:169], v[210:213], v[30:33]
	v_mfma_f32_16x16x32_bf16 v[30:33], v[158:161], v[206:209], v[30:33]
	v_mfma_f32_16x16x32_bf16 v[14:17], v[158:161], v[214:217], v[14:17]
	v_mfma_f32_16x16x32_bf16 v[14:17], v[166:169], v[218:221], v[14:17]
	v_mfma_f32_16x16x32_bf16 v[22:25], v[154:157], v[218:221], v[22:25]
	v_mfma_f32_16x16x32_bf16 v[22:25], v[150:153], v[214:217], v[22:25]
	v_mfma_f32_16x16x32_bf16 v[50:53], v[170:173], v[186:189], v[50:53]
	v_mfma_f32_16x16x32_bf16 v[50:53], v[174:177], v[190:193], v[50:53]
	v_mfma_f32_16x16x32_bf16 v[42:45], v[182:185], v[190:193], v[42:45]
	v_mfma_f32_16x16x32_bf16 v[42:45], v[178:181], v[186:189], v[42:45]
	v_mfma_f32_16x16x32_bf16 v[26:29], v[178:181], v[194:197], v[26:29]
	v_mfma_f32_16x16x32_bf16 v[26:29], v[182:185], v[202:205], v[26:29]
	v_mfma_f32_16x16x32_bf16 v[34:37], v[174:177], v[202:205], v[34:37]
	v_mfma_f32_16x16x32_bf16 v[34:37], v[170:173], v[194:197], v[34:37]
	v_mfma_f32_16x16x32_bf16 v[18:21], v[170:173], v[206:209], v[18:21]
	v_mfma_f32_16x16x32_bf16 v[18:21], v[174:177], v[210:213], v[18:21]
	v_mfma_f32_16x16x32_bf16 v[10:13], v[182:185], v[210:213], v[10:13]
	v_mfma_f32_16x16x32_bf16 v[10:13], v[178:181], v[206:209], v[10:13]
	v_mfma_f32_16x16x32_bf16 v[2:5], v[178:181], v[214:217], v[2:5]
	v_mfma_f32_16x16x32_bf16 v[2:5], v[182:185], v[218:221], v[2:5]
	v_mfma_f32_16x16x32_bf16 v[6:9], v[174:177], v[218:221], v[6:9]
	v_mfma_f32_16x16x32_bf16 v[6:9], v[170:173], v[214:217], v[6:9]
	s_barrier
	v_add_u32_e32 v149, s93, v145
	ds_read_b128 v[150:153], v149
	ds_read_b128 v[154:157], v149 offset:1024
	ds_read_b128 v[158:161], v149 offset:2048
	ds_read_b128 v[166:169], v149 offset:3072
	v_add_u32_e32 v149, s92, v145
	ds_read_b128 v[170:173], v149
	ds_read_b128 v[174:177], v149 offset:1024
	ds_read_b128 v[178:181], v149 offset:2048
	ds_read_b128 v[182:185], v149 offset:3072
	s_mov_b32 m0, s76
	v_lshl_add_u64 v[228:229], s[62:63], 0, v[138:139]
	ds_read_b128 v[186:189], v148 offset:32768
	ds_read_b128 v[190:193], v148 offset:33792
	ds_read_b128 v[194:197], v148 offset:34816
	ds_read_b128 v[202:205], v148 offset:35840
	ds_read_b128 v[206:209], v148 offset:36864
	ds_read_b128 v[210:213], v148 offset:37888
	ds_read_b128 v[214:217], v148 offset:38912
	ds_read_b128 v[218:221], v148 offset:39936
	global_load_lds_dwordx4 v[228:229], off
	v_lshl_add_u64 v[228:229], s[62:63], 0, v[134:135]
	s_mov_b32 m0, s77
	s_nop 0
	global_load_lds_dwordx4 v[228:229], off
	s_waitcnt vmcnt(8)
	s_waitcnt lgkmcnt(0)
	s_barrier
	s_waitcnt lgkmcnt(0)
	v_mfma_f32_16x16x32_bf16 v[126:129], v[150:153], v[186:189], v[126:129]
	v_mfma_f32_16x16x32_bf16 v[126:129], v[154:157], v[190:193], v[126:129]
	v_mfma_f32_16x16x32_bf16 v[122:125], v[166:169], v[190:193], v[122:125]
	v_mfma_f32_16x16x32_bf16 v[122:125], v[158:161], v[186:189], v[122:125]
	v_mfma_f32_16x16x32_bf16 v[110:113], v[158:161], v[194:197], v[110:113]
	v_mfma_f32_16x16x32_bf16 v[110:113], v[166:169], v[202:205], v[110:113]
	v_mfma_f32_16x16x32_bf16 v[118:121], v[154:157], v[202:205], v[118:121]
	v_mfma_f32_16x16x32_bf16 v[118:121], v[150:153], v[194:197], v[118:121]
	v_mfma_f32_16x16x32_bf16 v[102:105], v[150:153], v[206:209], v[102:105]
	v_mfma_f32_16x16x32_bf16 v[102:105], v[154:157], v[210:213], v[102:105]
	v_mfma_f32_16x16x32_bf16 v[94:97], v[166:169], v[210:213], v[94:97]
	v_mfma_f32_16x16x32_bf16 v[94:97], v[158:161], v[206:209], v[94:97]
	v_mfma_f32_16x16x32_bf16 v[78:81], v[158:161], v[214:217], v[78:81]
	v_mfma_f32_16x16x32_bf16 v[78:81], v[166:169], v[218:221], v[78:81]
	v_mfma_f32_16x16x32_bf16 v[86:89], v[154:157], v[218:221], v[86:89]
	v_mfma_f32_16x16x32_bf16 v[86:89], v[150:153], v[214:217], v[86:89]
	v_mfma_f32_16x16x32_bf16 v[114:117], v[170:173], v[186:189], v[114:117]
	v_mfma_f32_16x16x32_bf16 v[114:117], v[174:177], v[190:193], v[114:117]
	v_mfma_f32_16x16x32_bf16 v[106:109], v[182:185], v[190:193], v[106:109]
	v_mfma_f32_16x16x32_bf16 v[106:109], v[178:181], v[186:189], v[106:109]
	v_mfma_f32_16x16x32_bf16 v[90:93], v[178:181], v[194:197], v[90:93]
	v_mfma_f32_16x16x32_bf16 v[90:93], v[182:185], v[202:205], v[90:93]
	v_mfma_f32_16x16x32_bf16 v[98:101], v[174:177], v[202:205], v[98:101]
	v_mfma_f32_16x16x32_bf16 v[98:101], v[170:173], v[194:197], v[98:101]
	v_mfma_f32_16x16x32_bf16 v[82:85], v[170:173], v[206:209], v[82:85]
	v_mfma_f32_16x16x32_bf16 v[82:85], v[174:177], v[210:213], v[82:85]
	v_mfma_f32_16x16x32_bf16 v[74:77], v[182:185], v[210:213], v[74:77]
	v_mfma_f32_16x16x32_bf16 v[74:77], v[178:181], v[206:209], v[74:77]
	v_mfma_f32_16x16x32_bf16 v[66:69], v[178:181], v[214:217], v[66:69]
	v_mfma_f32_16x16x32_bf16 v[66:69], v[182:185], v[218:221], v[66:69]
	v_mfma_f32_16x16x32_bf16 v[70:73], v[174:177], v[218:221], v[70:73]
	v_mfma_f32_16x16x32_bf16 v[70:73], v[170:173], v[214:217], v[70:73]
	s_barrier
	s_mov_b32 m0, s91
	v_lshl_add_u64 v[198:199], v[198:199], 0, s[14:15]
	ds_read_b128 v[186:189], v148 offset:49152
	ds_read_b128 v[190:193], v148 offset:50176
	ds_read_b128 v[194:197], v148 offset:51200
	ds_read_b128 v[202:205], v148 offset:52224
	ds_read_b128 v[206:209], v148 offset:53248
	ds_read_b128 v[210:213], v148 offset:54272
	ds_read_b128 v[214:217], v148 offset:55296
	ds_read_b128 v[218:221], v148 offset:56320
	global_load_lds_dwordx4 v[198:199], off
	v_lshl_add_u64 v[198:199], v[222:223], 0, s[14:15]
	s_mov_b32 m0, s89
	s_nop 0
	global_load_lds_dwordx4 v[198:199], off
	v_lshl_add_u64 v[198:199], s[60:61], 0, v[136:137]
	s_mov_b32 m0, s90
	s_nop 0
	global_load_lds_dwordx4 v[198:199], off
	v_lshl_add_u64 v[198:199], s[60:61], 0, v[132:133]
	s_mov_b32 m0, s44
	s_nop 0
	global_load_lds_dwordx4 v[198:199], off
	v_lshl_add_u64 v[198:199], v[224:225], 0, s[14:15]
	s_mov_b32 m0, s79
	s_nop 0
	global_load_lds_dwordx4 v[198:199], off
	v_lshl_add_u64 v[198:199], v[226:227], 0, s[14:15]
	s_mov_b32 m0, s80
	s_nop 0
	global_load_lds_dwordx4 v[198:199], off
	s_waitcnt vmcnt(8)
	s_waitcnt lgkmcnt(0)
	s_barrier
	s_waitcnt lgkmcnt(0)
	v_mfma_f32_16x16x32_bf16 v[62:65], v[150:153], v[186:189], v[62:65]
	v_mfma_f32_16x16x32_bf16 v[62:65], v[154:157], v[190:193], v[62:65]
	v_mfma_f32_16x16x32_bf16 v[58:61], v[166:169], v[190:193], v[58:61]
	v_mfma_f32_16x16x32_bf16 v[58:61], v[158:161], v[186:189], v[58:61]
	v_mfma_f32_16x16x32_bf16 v[46:49], v[158:161], v[194:197], v[46:49]
	v_mfma_f32_16x16x32_bf16 v[46:49], v[166:169], v[202:205], v[46:49]
	v_mfma_f32_16x16x32_bf16 v[54:57], v[154:157], v[202:205], v[54:57]
	v_mfma_f32_16x16x32_bf16 v[54:57], v[150:153], v[194:197], v[54:57]
	v_mfma_f32_16x16x32_bf16 v[38:41], v[150:153], v[206:209], v[38:41]
	v_mfma_f32_16x16x32_bf16 v[38:41], v[154:157], v[210:213], v[38:41]
	v_mfma_f32_16x16x32_bf16 v[30:33], v[166:169], v[210:213], v[30:33]
	v_mfma_f32_16x16x32_bf16 v[30:33], v[158:161], v[206:209], v[30:33]
	v_mfma_f32_16x16x32_bf16 v[14:17], v[158:161], v[214:217], v[14:17]
	v_mfma_f32_16x16x32_bf16 v[14:17], v[166:169], v[218:221], v[14:17]
	v_mfma_f32_16x16x32_bf16 v[22:25], v[154:157], v[218:221], v[22:25]
	v_mfma_f32_16x16x32_bf16 v[22:25], v[150:153], v[214:217], v[22:25]
	v_mfma_f32_16x16x32_bf16 v[50:53], v[170:173], v[186:189], v[50:53]
	v_mfma_f32_16x16x32_bf16 v[50:53], v[174:177], v[190:193], v[50:53]
	v_mfma_f32_16x16x32_bf16 v[42:45], v[182:185], v[190:193], v[42:45]
	v_mfma_f32_16x16x32_bf16 v[42:45], v[178:181], v[186:189], v[42:45]
	v_mfma_f32_16x16x32_bf16 v[26:29], v[178:181], v[194:197], v[26:29]
	v_mfma_f32_16x16x32_bf16 v[26:29], v[182:185], v[202:205], v[26:29]
	v_mfma_f32_16x16x32_bf16 v[34:37], v[174:177], v[202:205], v[34:37]
	v_mfma_f32_16x16x32_bf16 v[34:37], v[170:173], v[194:197], v[34:37]
	v_mfma_f32_16x16x32_bf16 v[18:21], v[170:173], v[206:209], v[18:21]
	v_mfma_f32_16x16x32_bf16 v[18:21], v[174:177], v[210:213], v[18:21]
	v_mfma_f32_16x16x32_bf16 v[10:13], v[182:185], v[210:213], v[10:13]
	v_mfma_f32_16x16x32_bf16 v[10:13], v[178:181], v[206:209], v[10:13]
	v_mfma_f32_16x16x32_bf16 v[2:5], v[178:181], v[214:217], v[2:5]
	v_mfma_f32_16x16x32_bf16 v[2:5], v[182:185], v[218:221], v[2:5]
	v_mfma_f32_16x16x32_bf16 v[6:9], v[174:177], v[218:221], v[6:9]
	v_mfma_f32_16x16x32_bf16 v[6:9], v[170:173], v[214:217], v[6:9]
	s_barrier
	s_movk_i32 s44, 0x100
	s_andn2_b64 vcc, exec, s[58:59]
	s_mov_b64 s[60:61], -1
	s_mov_b64 s[58:59], 0
	s_cbranch_vccz .LBB0_1667
	s_and_b64 vcc, exec, s[16:17]
	s_cbranch_vccz .LBB0_1670
	s_barrier

.LBB0_1685:
	ds_read_b128 v[156:159], v153
	ds_read_b128 v[166:169], v153 offset:1024
	ds_read_b128 v[170:173], v153 offset:2048
	ds_read_b128 v[174:177], v153 offset:3072
	ds_read_b128 v[178:181], v154
	ds_read_b128 v[182:185], v154 offset:1024
	ds_read_b128 v[186:189], v154 offset:2048
	ds_read_b128 v[190:193], v154 offset:3072
	s_add_u32 s36, s56, 0xfff00080
	s_addc_u32 s37, s57, -1
	s_cmp_eq_u32 s78, 60
	s_cselect_b32 s61, s25, s37
	s_cselect_b32 s60, s74, s36
	s_cselect_b32 s59, s21, s77
	s_cselect_b32 s58, s75, s76
	v_lshl_add_u64 v[160:161], s[56:57], 0, v[140:141]
	s_add_i32 m0, s55, 0xc000
	ds_read_b128 v[194:197], v155
	ds_read_b128 v[202:205], v155 offset:1024
	ds_read_b128 v[206:209], v155 offset:2048
	ds_read_b128 v[210:213], v155 offset:3072
	ds_read_b128 v[214:217], v155 offset:4096
	ds_read_b128 v[218:221], v155 offset:5120
	ds_read_b128 v[222:225], v155 offset:6144
	ds_read_b128 v[226:229], v155 offset:7168
	global_load_lds_dwordx4 v[160:161], off
	v_lshl_add_u64 v[160:161], s[56:57], 0, v[142:143]
	s_add_i32 m0, s55, 0xe000
	s_nop 0
	global_load_lds_dwordx4 v[160:161], off
	s_waitcnt vmcnt(8)
	s_waitcnt lgkmcnt(0)
	s_barrier
	s_waitcnt lgkmcnt(0)
	v_mfma_f32_16x16x32_bf16 v[126:129], v[156:159], v[194:197], v[126:129]
	v_mfma_f32_16x16x32_bf16 v[126:129], v[166:169], v[202:205], v[126:129]
	v_mfma_f32_16x16x32_bf16 v[122:125], v[174:177], v[202:205], v[122:125]
	v_mfma_f32_16x16x32_bf16 v[122:125], v[170:173], v[194:197], v[122:125]
	v_mfma_f32_16x16x32_bf16 v[110:113], v[170:173], v[206:209], v[110:113]
	v_mfma_f32_16x16x32_bf16 v[110:113], v[174:177], v[210:213], v[110:113]
	v_mfma_f32_16x16x32_bf16 v[118:121], v[166:169], v[210:213], v[118:121]
	v_mfma_f32_16x16x32_bf16 v[118:121], v[156:159], v[206:209], v[118:121]
	v_mfma_f32_16x16x32_bf16 v[102:105], v[156:159], v[214:217], v[102:105]
	v_mfma_f32_16x16x32_bf16 v[102:105], v[166:169], v[218:221], v[102:105]
	v_mfma_f32_16x16x32_bf16 v[94:97], v[174:177], v[218:221], v[94:97]
	v_mfma_f32_16x16x32_bf16 v[94:97], v[170:173], v[214:217], v[94:97]
	v_mfma_f32_16x16x32_bf16 v[78:81], v[170:173], v[222:225], v[78:81]
	v_mfma_f32_16x16x32_bf16 v[78:81], v[174:177], v[226:229], v[78:81]
	v_mfma_f32_16x16x32_bf16 v[86:89], v[166:169], v[226:229], v[86:89]
	v_mfma_f32_16x16x32_bf16 v[86:89], v[156:159], v[222:225], v[86:89]
	v_mfma_f32_16x16x32_bf16 v[114:117], v[178:181], v[194:197], v[114:117]
	v_mfma_f32_16x16x32_bf16 v[114:117], v[182:185], v[202:205], v[114:117]
	v_mfma_f32_16x16x32_bf16 v[106:109], v[190:193], v[202:205], v[106:109]
	v_mfma_f32_16x16x32_bf16 v[106:109], v[186:189], v[194:197], v[106:109]
	v_mfma_f32_16x16x32_bf16 v[90:93], v[186:189], v[206:209], v[90:93]
	v_mfma_f32_16x16x32_bf16 v[90:93], v[190:193], v[210:213], v[90:93]
	v_mfma_f32_16x16x32_bf16 v[98:101], v[182:185], v[210:213], v[98:101]
	v_mfma_f32_16x16x32_bf16 v[98:101], v[178:181], v[206:209], v[98:101]
	v_mfma_f32_16x16x32_bf16 v[82:85], v[178:181], v[214:217], v[82:85]
	v_mfma_f32_16x16x32_bf16 v[82:85], v[182:185], v[218:221], v[82:85]
	v_mfma_f32_16x16x32_bf16 v[74:77], v[190:193], v[218:221], v[74:77]
	v_mfma_f32_16x16x32_bf16 v[74:77], v[186:189], v[214:217], v[74:77]
	v_mfma_f32_16x16x32_bf16 v[66:69], v[186:189], v[222:225], v[66:69]
	v_mfma_f32_16x16x32_bf16 v[66:69], v[190:193], v[226:229], v[66:69]
	v_mfma_f32_16x16x32_bf16 v[70:73], v[182:185], v[226:229], v[70:73]
	v_mfma_f32_16x16x32_bf16 v[70:73], v[178:181], v[222:225], v[70:73]
	s_barrier
	s_add_i32 s36, s68, s38
	v_lshl_add_u64 v[160:161], s[58:59], 0, v[136:137]
	s_mov_b32 m0, s36
	ds_read_b128 v[194:197], v155 offset:16384
	ds_read_b128 v[202:205], v155 offset:17408
	ds_read_b128 v[206:209], v155 offset:18432
	ds_read_b128 v[210:213], v155 offset:19456
	ds_read_b128 v[214:217], v155 offset:20480
	ds_read_b128 v[218:221], v155 offset:21504
	ds_read_b128 v[222:225], v155 offset:22528
	ds_read_b128 v[226:229], v155 offset:23552
	global_load_lds_dwordx4 v[160:161], off
	s_add_i32 m0, s36, 0x2000
	s_add_u32 s80, s58, 0x100000
	v_lshl_add_u64 v[198:199], s[58:59], 0, v[132:133]
	s_addc_u32 s81, s59, 0
	s_add_i32 s36, s69, s38
	global_load_lds_dwordx4 v[198:199], off
	v_lshl_add_u64 v[230:231], s[80:81], 0, v[136:137]
	s_mov_b32 m0, s36
	v_lshl_add_u64 v[232:233], s[60:61], 0, v[134:135]
	global_load_lds_dwordx4 v[230:231], off
	v_lshl_add_u64 v[230:231], s[80:81], 0, v[132:133]
	s_add_i32 m0, s36, 0x2000
	s_nop 0
	global_load_lds_dwordx4 v[230:231], off
	v_lshl_add_u64 v[230:231], s[60:61], 0, v[138:139]
	s_mov_b32 m0, s55
	s_nop 0
	global_load_lds_dwordx4 v[230:231], off
	s_mov_b32 m0, s63
	s_nop 0
	global_load_lds_dwordx4 v[232:233], off
	s_waitcnt vmcnt(8)
	s_waitcnt lgkmcnt(0)
	s_barrier
	s_waitcnt lgkmcnt(0)
	v_mfma_f32_16x16x32_bf16 v[62:65], v[156:159], v[194:197], v[62:65]
	v_mfma_f32_16x16x32_bf16 v[62:65], v[166:169], v[202:205], v[62:65]
	v_mfma_f32_16x16x32_bf16 v[58:61], v[174:177], v[202:205], v[58:61]
	v_mfma_f32_16x16x32_bf16 v[58:61], v[170:173], v[194:197], v[58:61]
	v_mfma_f32_16x16x32_bf16 v[46:49], v[170:173], v[206:209], v[46:49]
	v_mfma_f32_16x16x32_bf16 v[46:49], v[174:177], v[210:213], v[46:49]
	v_mfma_f32_16x16x32_bf16 v[54:57], v[166:169], v[210:213], v[54:57]
	v_mfma_f32_16x16x32_bf16 v[54:57], v[156:159], v[206:209], v[54:57]
	v_mfma_f32_16x16x32_bf16 v[38:41], v[156:159], v[214:217], v[38:41]
	v_mfma_f32_16x16x32_bf16 v[38:41], v[166:169], v[218:221], v[38:41]
	v_mfma_f32_16x16x32_bf16 v[30:33], v[174:177], v[218:221], v[30:33]
	v_mfma_f32_16x16x32_bf16 v[30:33], v[170:173], v[214:217], v[30:33]
	v_mfma_f32_16x16x32_bf16 v[14:17], v[170:173], v[222:225], v[14:17]
	v_mfma_f32_16x16x32_bf16 v[14:17], v[174:177], v[226:229], v[14:17]
	v_mfma_f32_16x16x32_bf16 v[22:25], v[166:169], v[226:229], v[22:25]
	v_mfma_f32_16x16x32_bf16 v[22:25], v[156:159], v[222:225], v[22:25]
	v_mfma_f32_16x16x32_bf16 v[50:53], v[178:181], v[194:197], v[50:53]
	v_mfma_f32_16x16x32_bf16 v[50:53], v[182:185], v[202:205], v[50:53]
	v_mfma_f32_16x16x32_bf16 v[42:45], v[190:193], v[202:205], v[42:45]
	v_mfma_f32_16x16x32_bf16 v[42:45], v[186:189], v[194:197], v[42:45]
	v_mfma_f32_16x16x32_bf16 v[26:29], v[186:189], v[206:209], v[26:29]
	v_mfma_f32_16x16x32_bf16 v[26:29], v[190:193], v[210:213], v[26:29]
	v_mfma_f32_16x16x32_bf16 v[34:37], v[182:185], v[210:213], v[34:37]
	v_mfma_f32_16x16x32_bf16 v[34:37], v[178:181], v[206:209], v[34:37]
	v_mfma_f32_16x16x32_bf16 v[18:21], v[178:181], v[214:217], v[18:21]
	v_mfma_f32_16x16x32_bf16 v[18:21], v[182:185], v[218:221], v[18:21]
	v_mfma_f32_16x16x32_bf16 v[10:13], v[190:193], v[218:221], v[10:13]
	v_mfma_f32_16x16x32_bf16 v[10:13], v[186:189], v[214:217], v[10:13]
	v_mfma_f32_16x16x32_bf16 v[2:5], v[186:189], v[222:225], v[2:5]
	v_mfma_f32_16x16x32_bf16 v[2:5], v[190:193], v[226:229], v[2:5]
	v_mfma_f32_16x16x32_bf16 v[6:9], v[182:185], v[226:229], v[6:9]
	v_mfma_f32_16x16x32_bf16 v[6:9], v[178:181], v[222:225], v[6:9]
	s_barrier
	s_add_i32 s36, 0, 0x18000
	v_add_u32_e32 v165, s36, v151
	s_add_i32 s37, 0, 0x1c000
	ds_read_b128 v[156:159], v165
	ds_read_b128 v[166:169], v165 offset:1024
	ds_read_b128 v[170:173], v165 offset:2048
	ds_read_b128 v[174:177], v165 offset:3072
	v_add_u32_e32 v165, s37, v151
	ds_read_b128 v[178:181], v165
	ds_read_b128 v[182:185], v165 offset:1024
	ds_read_b128 v[186:189], v165 offset:2048
	ds_read_b128 v[190:193], v165 offset:3072
	s_add_u32 s60, s60, 0x100000
	s_addc_u32 s61, s61, 0
	s_mov_b32 m0, s64
	v_lshl_add_u64 v[234:235], s[60:61], 0, v[138:139]
	ds_read_b128 v[194:197], v155 offset:32768
	ds_read_b128 v[202:205], v155 offset:33792
	ds_read_b128 v[206:209], v155 offset:34816
	ds_read_b128 v[210:213], v155 offset:35840
	ds_read_b128 v[214:217], v155 offset:36864
	ds_read_b128 v[218:221], v155 offset:37888
	ds_read_b128 v[222:225], v155 offset:38912
	ds_read_b128 v[226:229], v155 offset:39936
	global_load_lds_dwordx4 v[234:235], off
	v_lshl_add_u64 v[234:235], s[60:61], 0, v[134:135]
	s_mov_b32 m0, s65
	s_nop 0
	global_load_lds_dwordx4 v[234:235], off
	s_waitcnt vmcnt(8)
	s_waitcnt lgkmcnt(0)
	s_barrier
	s_waitcnt lgkmcnt(0)
	v_mfma_f32_16x16x32_bf16 v[126:129], v[156:159], v[194:197], v[126:129]
	v_mfma_f32_16x16x32_bf16 v[126:129], v[166:169], v[202:205], v[126:129]
	v_mfma_f32_16x16x32_bf16 v[122:125], v[174:177], v[202:205], v[122:125]
	v_mfma_f32_16x16x32_bf16 v[122:125], v[170:173], v[194:197], v[122:125]
	v_mfma_f32_16x16x32_bf16 v[110:113], v[170:173], v[206:209], v[110:113]
	v_mfma_f32_16x16x32_bf16 v[110:113], v[174:177], v[210:213], v[110:113]
	v_mfma_f32_16x16x32_bf16 v[118:121], v[166:169], v[210:213], v[118:121]
	v_mfma_f32_16x16x32_bf16 v[118:121], v[156:159], v[206:209], v[118:121]
	v_mfma_f32_16x16x32_bf16 v[102:105], v[156:159], v[214:217], v[102:105]
	v_mfma_f32_16x16x32_bf16 v[102:105], v[166:169], v[218:221], v[102:105]
	v_mfma_f32_16x16x32_bf16 v[94:97], v[174:177], v[218:221], v[94:97]
	v_mfma_f32_16x16x32_bf16 v[94:97], v[170:173], v[214:217], v[94:97]
	v_mfma_f32_16x16x32_bf16 v[78:81], v[170:173], v[222:225], v[78:81]
	v_mfma_f32_16x16x32_bf16 v[78:81], v[174:177], v[226:229], v[78:81]
	v_mfma_f32_16x16x32_bf16 v[86:89], v[166:169], v[226:229], v[86:89]
	v_mfma_f32_16x16x32_bf16 v[86:89], v[156:159], v[222:225], v[86:89]
	v_mfma_f32_16x16x32_bf16 v[114:117], v[178:181], v[194:197], v[114:117]
	v_mfma_f32_16x16x32_bf16 v[114:117], v[182:185], v[202:205], v[114:117]
	v_mfma_f32_16x16x32_bf16 v[106:109], v[190:193], v[202:205], v[106:109]
	v_mfma_f32_16x16x32_bf16 v[106:109], v[186:189], v[194:197], v[106:109]
	v_mfma_f32_16x16x32_bf16 v[90:93], v[186:189], v[206:209], v[90:93]
	v_mfma_f32_16x16x32_bf16 v[90:93], v[190:193], v[210:213], v[90:93]
	v_mfma_f32_16x16x32_bf16 v[98:101], v[182:185], v[210:213], v[98:101]
	v_mfma_f32_16x16x32_bf16 v[98:101], v[178:181], v[206:209], v[98:101]
	v_mfma_f32_16x16x32_bf16 v[82:85], v[178:181], v[214:217], v[82:85]
	v_mfma_f32_16x16x32_bf16 v[82:85], v[182:185], v[218:221], v[82:85]
	v_mfma_f32_16x16x32_bf16 v[74:77], v[190:193], v[218:221], v[74:77]
	v_mfma_f32_16x16x32_bf16 v[74:77], v[186:189], v[214:217], v[74:77]
	v_mfma_f32_16x16x32_bf16 v[66:69], v[186:189], v[222:225], v[66:69]
	v_mfma_f32_16x16x32_bf16 v[66:69], v[190:193], v[226:229], v[66:69]
	v_mfma_f32_16x16x32_bf16 v[70:73], v[182:185], v[226:229], v[70:73]
	v_mfma_f32_16x16x32_bf16 v[70:73], v[178:181], v[222:225], v[70:73]
	s_barrier
	s_add_i32 s36, s36, s38
	v_lshl_add_u64 v[160:161], v[160:161], 0, s[16:17]
	s_mov_b32 m0, s36
	ds_read_b128 v[194:197], v155 offset:49152
	ds_read_b128 v[202:205], v155 offset:50176
	ds_read_b128 v[206:209], v155 offset:51200
	ds_read_b128 v[210:213], v155 offset:52224
	ds_read_b128 v[214:217], v155 offset:53248
	ds_read_b128 v[218:221], v155 offset:54272
	ds_read_b128 v[222:225], v155 offset:55296
	ds_read_b128 v[226:229], v155 offset:56320
	global_load_lds_dwordx4 v[160:161], off
	s_add_i32 m0, s36, 0x2000
	s_add_u32 s58, s58, 0x100080
	v_lshl_add_u64 v[160:161], v[198:199], 0, s[16:17]
	s_addc_u32 s59, s59, 0
	s_add_i32 s36, s37, s38
	global_load_lds_dwordx4 v[160:161], off
	v_lshl_add_u64 v[160:161], s[58:59], 0, v[136:137]
	s_mov_b32 m0, s36
	s_nop 0
	global_load_lds_dwordx4 v[160:161], off
	v_lshl_add_u64 v[160:161], s[58:59], 0, v[132:133]
	s_add_i32 m0, s36, 0x2000
	s_nop 0
	global_load_lds_dwordx4 v[160:161], off
	v_lshl_add_u64 v[160:161], v[230:231], 0, s[16:17]
	s_mov_b32 m0, s66
	s_nop 0
	global_load_lds_dwordx4 v[160:161], off
	v_lshl_add_u64 v[160:161], v[232:233], 0, s[16:17]
	s_mov_b32 m0, s67
	s_nop 0
	global_load_lds_dwordx4 v[160:161], off
	s_waitcnt vmcnt(8)
	s_waitcnt lgkmcnt(0)
	s_barrier
	s_waitcnt lgkmcnt(0)
	v_mfma_f32_16x16x32_bf16 v[62:65], v[156:159], v[194:197], v[62:65]
	v_mfma_f32_16x16x32_bf16 v[62:65], v[166:169], v[202:205], v[62:65]
	v_mfma_f32_16x16x32_bf16 v[58:61], v[174:177], v[202:205], v[58:61]
	v_mfma_f32_16x16x32_bf16 v[58:61], v[170:173], v[194:197], v[58:61]
	v_mfma_f32_16x16x32_bf16 v[46:49], v[170:173], v[206:209], v[46:49]
	v_mfma_f32_16x16x32_bf16 v[46:49], v[174:177], v[210:213], v[46:49]
	v_mfma_f32_16x16x32_bf16 v[54:57], v[166:169], v[210:213], v[54:57]
	v_mfma_f32_16x16x32_bf16 v[54:57], v[156:159], v[206:209], v[54:57]
	v_mfma_f32_16x16x32_bf16 v[38:41], v[156:159], v[214:217], v[38:41]
	v_mfma_f32_16x16x32_bf16 v[38:41], v[166:169], v[218:221], v[38:41]
	v_mfma_f32_16x16x32_bf16 v[30:33], v[174:177], v[218:221], v[30:33]
	v_mfma_f32_16x16x32_bf16 v[30:33], v[170:173], v[214:217], v[30:33]
	v_mfma_f32_16x16x32_bf16 v[14:17], v[170:173], v[222:225], v[14:17]
	v_mfma_f32_16x16x32_bf16 v[14:17], v[174:177], v[226:229], v[14:17]
	v_mfma_f32_16x16x32_bf16 v[22:25], v[166:169], v[226:229], v[22:25]
	v_mfma_f32_16x16x32_bf16 v[22:25], v[156:159], v[222:225], v[22:25]
	v_mfma_f32_16x16x32_bf16 v[50:53], v[178:181], v[194:197], v[50:53]
	v_mfma_f32_16x16x32_bf16 v[50:53], v[182:185], v[202:205], v[50:53]
	v_mfma_f32_16x16x32_bf16 v[42:45], v[190:193], v[202:205], v[42:45]
	v_mfma_f32_16x16x32_bf16 v[42:45], v[186:189], v[194:197], v[42:45]
	v_mfma_f32_16x16x32_bf16 v[26:29], v[186:189], v[206:209], v[26:29]
	v_mfma_f32_16x16x32_bf16 v[26:29], v[190:193], v[210:213], v[26:29]
	v_mfma_f32_16x16x32_bf16 v[34:37], v[182:185], v[210:213], v[34:37]
	v_mfma_f32_16x16x32_bf16 v[34:37], v[178:181], v[206:209], v[34:37]
	v_mfma_f32_16x16x32_bf16 v[18:21], v[178:181], v[214:217], v[18:21]
	v_mfma_f32_16x16x32_bf16 v[18:21], v[182:185], v[218:221], v[18:21]
	v_mfma_f32_16x16x32_bf16 v[10:13], v[190:193], v[218:221], v[10:13]
	v_mfma_f32_16x16x32_bf16 v[10:13], v[186:189], v[214:217], v[10:13]
	v_mfma_f32_16x16x32_bf16 v[2:5], v[186:189], v[222:225], v[2:5]
	v_mfma_f32_16x16x32_bf16 v[2:5], v[190:193], v[226:229], v[2:5]
	v_mfma_f32_16x16x32_bf16 v[6:9], v[182:185], v[226:229], v[6:9]
	v_mfma_f32_16x16x32_bf16 v[6:9], v[178:181], v[222:225], v[6:9]
	s_barrier
	s_add_i32 s78, s78, 2
	s_add_u32 s56, s56, 0x100
	s_addc_u32 s57, s57, 0
	s_add_u32 s76, s76, 0x100
	s_addc_u32 s77, s77, 0
	s_cmp_gt_u32 s78, 61
	s_cbranch_scc0 .LBB0_1685
	s_and_b64 vcc, exec, s[18:19]
	s_cbranch_vccz .LBB0_1688
	s_barrier

.LBB0_1701:
	s_add_u32 s36, s56, s44
	s_addc_u32 s37, s57, 0
	s_add_u32 s64, s36, 0x100
	s_addc_u32 s65, s37, 0
	s_and_b64 s[62:63], s[60:61], exec
	s_cselect_b32 s65, s21, s65
	s_cselect_b32 s64, s86, s64
	s_add_u32 s44, s54, s44
	s_addc_u32 s62, s55, 0
	s_add_u32 s44, s44, 0x100
	s_addc_u32 s62, s62, 0
	s_and_b64 s[60:61], s[60:61], exec
	s_cselect_b32 s67, s25, s62
	s_cselect_b32 s66, s87, s44
	s_add_u32 s70, s36, 0x10080
	s_addc_u32 s71, s37, 0
	s_add_i32 s97, s81, s39
	ds_read_b128 v[152:155], v147
	ds_read_b128 v[156:159], v147 offset:1024
	ds_read_b128 v[166:169], v147 offset:2048
	ds_read_b128 v[170:173], v147 offset:3072
	ds_read_b128 v[174:177], v150
	ds_read_b128 v[178:181], v150 offset:1024
	ds_read_b128 v[182:185], v150 offset:2048
	ds_read_b128 v[186:189], v150 offset:3072
	s_add_i32 m0, s74, 0xc000
	s_add_i32 vcc_lo, s74, 0xe000
	s_add_i32 s94, s97, 0x2000
	s_add_u32 s68, s66, 0x10000
	s_addc_u32 s69, s67, 0
	s_add_i32 s96, s82, s39
	s_add_i32 s95, s96, 0x2000
	s_add_i32 s93, 0, 0x18000
	s_add_i32 s92, 0, 0x1c000
	s_add_u32 s62, s64, 0x10000
	s_addc_u32 s63, s65, 0
	s_add_i32 s91, s93, s39
	s_add_i32 s89, s91, 0x2000
	s_add_u32 s60, s66, 0x10080
	s_addc_u32 s61, s67, 0
	s_add_i32 s90, s92, s39
	s_add_i32 s44, s90, 0x2000
	v_lshl_add_u64 v[160:161], s[70:71], 0, v[138:139]
	ds_read_b128 v[190:193], v151
	ds_read_b128 v[194:197], v151 offset:1024
	ds_read_b128 v[202:205], v151 offset:2048
	ds_read_b128 v[206:209], v151 offset:3072
	ds_read_b128 v[210:213], v151 offset:4096
	ds_read_b128 v[214:217], v151 offset:5120
	ds_read_b128 v[218:221], v151 offset:6144
	ds_read_b128 v[222:225], v151 offset:7168
	global_load_lds_dwordx4 v[160:161], off
	v_lshl_add_u64 v[160:161], s[70:71], 0, v[134:135]
	s_mov_b32 m0, vcc_lo
	s_nop 0
	global_load_lds_dwordx4 v[160:161], off
	s_waitcnt vmcnt(8)
	s_waitcnt lgkmcnt(0)
	s_barrier
	s_waitcnt lgkmcnt(0)
	v_mfma_f32_16x16x32_bf16 v[126:129], v[152:155], v[190:193], v[126:129]
	v_mfma_f32_16x16x32_bf16 v[126:129], v[156:159], v[194:197], v[126:129]
	v_mfma_f32_16x16x32_bf16 v[122:125], v[170:173], v[194:197], v[122:125]
	v_mfma_f32_16x16x32_bf16 v[122:125], v[166:169], v[190:193], v[122:125]
	v_mfma_f32_16x16x32_bf16 v[110:113], v[166:169], v[202:205], v[110:113]
	v_mfma_f32_16x16x32_bf16 v[110:113], v[170:173], v[206:209], v[110:113]
	v_mfma_f32_16x16x32_bf16 v[118:121], v[156:159], v[206:209], v[118:121]
	v_mfma_f32_16x16x32_bf16 v[118:121], v[152:155], v[202:205], v[118:121]
	v_mfma_f32_16x16x32_bf16 v[102:105], v[152:155], v[210:213], v[102:105]
	v_mfma_f32_16x16x32_bf16 v[102:105], v[156:159], v[214:217], v[102:105]
	v_mfma_f32_16x16x32_bf16 v[94:97], v[170:173], v[214:217], v[94:97]
	v_mfma_f32_16x16x32_bf16 v[94:97], v[166:169], v[210:213], v[94:97]
	v_mfma_f32_16x16x32_bf16 v[78:81], v[166:169], v[218:221], v[78:81]
	v_mfma_f32_16x16x32_bf16 v[78:81], v[170:173], v[222:225], v[78:81]
	v_mfma_f32_16x16x32_bf16 v[86:89], v[156:159], v[222:225], v[86:89]
	v_mfma_f32_16x16x32_bf16 v[86:89], v[152:155], v[218:221], v[86:89]
	v_mfma_f32_16x16x32_bf16 v[114:117], v[174:177], v[190:193], v[114:117]
	v_mfma_f32_16x16x32_bf16 v[114:117], v[178:181], v[194:197], v[114:117]
	v_mfma_f32_16x16x32_bf16 v[106:109], v[186:189], v[194:197], v[106:109]
	v_mfma_f32_16x16x32_bf16 v[106:109], v[182:185], v[190:193], v[106:109]
	v_mfma_f32_16x16x32_bf16 v[90:93], v[182:185], v[202:205], v[90:93]
	v_mfma_f32_16x16x32_bf16 v[90:93], v[186:189], v[206:209], v[90:93]
	v_mfma_f32_16x16x32_bf16 v[98:101], v[178:181], v[206:209], v[98:101]
	v_mfma_f32_16x16x32_bf16 v[98:101], v[174:177], v[202:205], v[98:101]
	v_mfma_f32_16x16x32_bf16 v[82:85], v[174:177], v[210:213], v[82:85]
	v_mfma_f32_16x16x32_bf16 v[82:85], v[178:181], v[214:217], v[82:85]
	v_mfma_f32_16x16x32_bf16 v[74:77], v[186:189], v[214:217], v[74:77]
	v_mfma_f32_16x16x32_bf16 v[74:77], v[182:185], v[210:213], v[74:77]
	v_mfma_f32_16x16x32_bf16 v[66:69], v[182:185], v[218:221], v[66:69]
	v_mfma_f32_16x16x32_bf16 v[66:69], v[186:189], v[222:225], v[66:69]
	v_mfma_f32_16x16x32_bf16 v[70:73], v[178:181], v[222:225], v[70:73]
	v_mfma_f32_16x16x32_bf16 v[70:73], v[174:177], v[218:221], v[70:73]
	s_barrier
	s_mov_b32 m0, s97
	v_lshl_add_u64 v[160:161], s[66:67], 0, v[136:137]
	ds_read_b128 v[190:193], v151 offset:16384
	ds_read_b128 v[194:197], v151 offset:17408
	ds_read_b128 v[202:205], v151 offset:18432
	ds_read_b128 v[206:209], v151 offset:19456
	ds_read_b128 v[210:213], v151 offset:20480
	ds_read_b128 v[214:217], v151 offset:21504
	ds_read_b128 v[218:221], v151 offset:22528
	ds_read_b128 v[222:225], v151 offset:23552
	global_load_lds_dwordx4 v[160:161], off
	v_lshl_add_u64 v[198:199], s[66:67], 0, v[132:133]
	s_mov_b32 m0, s94
	v_lshl_add_u64 v[226:227], s[68:69], 0, v[136:137]
	global_load_lds_dwordx4 v[198:199], off
	s_mov_b32 m0, s96
	v_lshl_add_u64 v[228:229], s[64:65], 0, v[134:135]
	global_load_lds_dwordx4 v[226:227], off
	v_lshl_add_u64 v[226:227], s[68:69], 0, v[132:133]
	s_mov_b32 m0, s95
	s_nop 0
	global_load_lds_dwordx4 v[226:227], off
	v_lshl_add_u64 v[226:227], s[64:65], 0, v[138:139]
	s_mov_b32 m0, s74
	s_nop 0
	global_load_lds_dwordx4 v[226:227], off
	s_mov_b32 m0, s75
	s_nop 0
	global_load_lds_dwordx4 v[228:229], off
	s_waitcnt vmcnt(8)
	s_waitcnt lgkmcnt(0)
	s_barrier
	s_waitcnt lgkmcnt(0)
	v_mfma_f32_16x16x32_bf16 v[62:65], v[152:155], v[190:193], v[62:65]
	v_mfma_f32_16x16x32_bf16 v[62:65], v[156:159], v[194:197], v[62:65]
	v_mfma_f32_16x16x32_bf16 v[58:61], v[170:173], v[194:197], v[58:61]
	v_mfma_f32_16x16x32_bf16 v[58:61], v[166:169], v[190:193], v[58:61]
	v_mfma_f32_16x16x32_bf16 v[46:49], v[166:169], v[202:205], v[46:49]
	v_mfma_f32_16x16x32_bf16 v[46:49], v[170:173], v[206:209], v[46:49]
	v_mfma_f32_16x16x32_bf16 v[54:57], v[156:159], v[206:209], v[54:57]
	v_mfma_f32_16x16x32_bf16 v[54:57], v[152:155], v[202:205], v[54:57]
	v_mfma_f32_16x16x32_bf16 v[38:41], v[152:155], v[210:213], v[38:41]
	v_mfma_f32_16x16x32_bf16 v[38:41], v[156:159], v[214:217], v[38:41]
	v_mfma_f32_16x16x32_bf16 v[30:33], v[170:173], v[214:217], v[30:33]
	v_mfma_f32_16x16x32_bf16 v[30:33], v[166:169], v[210:213], v[30:33]
	v_mfma_f32_16x16x32_bf16 v[14:17], v[166:169], v[218:221], v[14:17]
	v_mfma_f32_16x16x32_bf16 v[14:17], v[170:173], v[222:225], v[14:17]
	v_mfma_f32_16x16x32_bf16 v[22:25], v[156:159], v[222:225], v[22:25]
	v_mfma_f32_16x16x32_bf16 v[22:25], v[152:155], v[218:221], v[22:25]
	v_mfma_f32_16x16x32_bf16 v[50:53], v[174:177], v[190:193], v[50:53]
	v_mfma_f32_16x16x32_bf16 v[50:53], v[178:181], v[194:197], v[50:53]
	v_mfma_f32_16x16x32_bf16 v[42:45], v[186:189], v[194:197], v[42:45]
	v_mfma_f32_16x16x32_bf16 v[42:45], v[182:185], v[190:193], v[42:45]
	v_mfma_f32_16x16x32_bf16 v[26:29], v[182:185], v[202:205], v[26:29]
	v_mfma_f32_16x16x32_bf16 v[26:29], v[186:189], v[206:209], v[26:29]
	v_mfma_f32_16x16x32_bf16 v[34:37], v[178:181], v[206:209], v[34:37]
	v_mfma_f32_16x16x32_bf16 v[34:37], v[174:177], v[202:205], v[34:37]
	v_mfma_f32_16x16x32_bf16 v[18:21], v[174:177], v[210:213], v[18:21]
	v_mfma_f32_16x16x32_bf16 v[18:21], v[178:181], v[214:217], v[18:21]
	v_mfma_f32_16x16x32_bf16 v[10:13], v[186:189], v[214:217], v[10:13]
	v_mfma_f32_16x16x32_bf16 v[10:13], v[182:185], v[210:213], v[10:13]
	v_mfma_f32_16x16x32_bf16 v[2:5], v[182:185], v[218:221], v[2:5]
	v_mfma_f32_16x16x32_bf16 v[2:5], v[186:189], v[222:225], v[2:5]
	v_mfma_f32_16x16x32_bf16 v[6:9], v[178:181], v[222:225], v[6:9]
	v_mfma_f32_16x16x32_bf16 v[6:9], v[174:177], v[218:221], v[6:9]
	s_barrier
	v_add_u32_e32 v165, s93, v145
	ds_read_b128 v[152:155], v165
	ds_read_b128 v[156:159], v165 offset:1024
	ds_read_b128 v[166:169], v165 offset:2048
	ds_read_b128 v[170:173], v165 offset:3072
	v_add_u32_e32 v165, s92, v145
	ds_read_b128 v[174:177], v165
	ds_read_b128 v[178:181], v165 offset:1024
	ds_read_b128 v[182:185], v165 offset:2048
	ds_read_b128 v[186:189], v165 offset:3072
	s_mov_b32 m0, s76
	v_lshl_add_u64 v[230:231], s[62:63], 0, v[138:139]
	ds_read_b128 v[190:193], v151 offset:32768
	ds_read_b128 v[194:197], v151 offset:33792
	ds_read_b128 v[202:205], v151 offset:34816
	ds_read_b128 v[206:209], v151 offset:35840
	ds_read_b128 v[210:213], v151 offset:36864
	ds_read_b128 v[214:217], v151 offset:37888
	ds_read_b128 v[218:221], v151 offset:38912
	ds_read_b128 v[222:225], v151 offset:39936
	global_load_lds_dwordx4 v[230:231], off
	v_lshl_add_u64 v[230:231], s[62:63], 0, v[134:135]
	s_mov_b32 m0, s77
	s_nop 0
	global_load_lds_dwordx4 v[230:231], off
	s_waitcnt vmcnt(8)
	s_waitcnt lgkmcnt(0)
	s_barrier
	s_waitcnt lgkmcnt(0)
	v_mfma_f32_16x16x32_bf16 v[126:129], v[152:155], v[190:193], v[126:129]
	v_mfma_f32_16x16x32_bf16 v[126:129], v[156:159], v[194:197], v[126:129]
	v_mfma_f32_16x16x32_bf16 v[122:125], v[170:173], v[194:197], v[122:125]
	v_mfma_f32_16x16x32_bf16 v[122:125], v[166:169], v[190:193], v[122:125]
	v_mfma_f32_16x16x32_bf16 v[110:113], v[166:169], v[202:205], v[110:113]
	v_mfma_f32_16x16x32_bf16 v[110:113], v[170:173], v[206:209], v[110:113]
	v_mfma_f32_16x16x32_bf16 v[118:121], v[156:159], v[206:209], v[118:121]
	v_mfma_f32_16x16x32_bf16 v[118:121], v[152:155], v[202:205], v[118:121]
	v_mfma_f32_16x16x32_bf16 v[102:105], v[152:155], v[210:213], v[102:105]
	v_mfma_f32_16x16x32_bf16 v[102:105], v[156:159], v[214:217], v[102:105]
	v_mfma_f32_16x16x32_bf16 v[94:97], v[170:173], v[214:217], v[94:97]
	v_mfma_f32_16x16x32_bf16 v[94:97], v[166:169], v[210:213], v[94:97]
	v_mfma_f32_16x16x32_bf16 v[78:81], v[166:169], v[218:221], v[78:81]
	v_mfma_f32_16x16x32_bf16 v[78:81], v[170:173], v[222:225], v[78:81]
	v_mfma_f32_16x16x32_bf16 v[86:89], v[156:159], v[222:225], v[86:89]
	v_mfma_f32_16x16x32_bf16 v[86:89], v[152:155], v[218:221], v[86:89]
	v_mfma_f32_16x16x32_bf16 v[114:117], v[174:177], v[190:193], v[114:117]
	v_mfma_f32_16x16x32_bf16 v[114:117], v[178:181], v[194:197], v[114:117]
	v_mfma_f32_16x16x32_bf16 v[106:109], v[186:189], v[194:197], v[106:109]
	v_mfma_f32_16x16x32_bf16 v[106:109], v[182:185], v[190:193], v[106:109]
	v_mfma_f32_16x16x32_bf16 v[90:93], v[182:185], v[202:205], v[90:93]
	v_mfma_f32_16x16x32_bf16 v[90:93], v[186:189], v[206:209], v[90:93]
	v_mfma_f32_16x16x32_bf16 v[98:101], v[178:181], v[206:209], v[98:101]
	v_mfma_f32_16x16x32_bf16 v[98:101], v[174:177], v[202:205], v[98:101]
	v_mfma_f32_16x16x32_bf16 v[82:85], v[174:177], v[210:213], v[82:85]
	v_mfma_f32_16x16x32_bf16 v[82:85], v[178:181], v[214:217], v[82:85]
	v_mfma_f32_16x16x32_bf16 v[74:77], v[186:189], v[214:217], v[74:77]
	v_mfma_f32_16x16x32_bf16 v[74:77], v[182:185], v[210:213], v[74:77]
	v_mfma_f32_16x16x32_bf16 v[66:69], v[182:185], v[218:221], v[66:69]
	v_mfma_f32_16x16x32_bf16 v[66:69], v[186:189], v[222:225], v[66:69]
	v_mfma_f32_16x16x32_bf16 v[70:73], v[178:181], v[222:225], v[70:73]
	v_mfma_f32_16x16x32_bf16 v[70:73], v[174:177], v[218:221], v[70:73]
	s_barrier
	s_mov_b32 m0, s91
	v_lshl_add_u64 v[160:161], v[160:161], 0, s[14:15]
	ds_read_b128 v[190:193], v151 offset:49152
	ds_read_b128 v[194:197], v151 offset:50176
	ds_read_b128 v[202:205], v151 offset:51200
	ds_read_b128 v[206:209], v151 offset:52224
	ds_read_b128 v[210:213], v151 offset:53248
	ds_read_b128 v[214:217], v151 offset:54272
	ds_read_b128 v[218:221], v151 offset:55296
	ds_read_b128 v[222:225], v151 offset:56320
	global_load_lds_dwordx4 v[160:161], off
	v_lshl_add_u64 v[160:161], v[198:199], 0, s[14:15]
	s_mov_b32 m0, s89
	s_nop 0
	global_load_lds_dwordx4 v[160:161], off
	v_lshl_add_u64 v[160:161], s[60:61], 0, v[136:137]
	s_mov_b32 m0, s90
	s_nop 0
	global_load_lds_dwordx4 v[160:161], off
	v_lshl_add_u64 v[160:161], s[60:61], 0, v[132:133]
	s_mov_b32 m0, s44
	s_nop 0
	global_load_lds_dwordx4 v[160:161], off
	v_lshl_add_u64 v[160:161], v[226:227], 0, s[14:15]
	s_mov_b32 m0, s79
	s_nop 0
	global_load_lds_dwordx4 v[160:161], off
	v_lshl_add_u64 v[160:161], v[228:229], 0, s[14:15]
	s_mov_b32 m0, s80
	s_nop 0
	global_load_lds_dwordx4 v[160:161], off
	s_waitcnt vmcnt(8)
	s_waitcnt lgkmcnt(0)
	s_barrier
	s_waitcnt lgkmcnt(0)
	v_mfma_f32_16x16x32_bf16 v[62:65], v[152:155], v[190:193], v[62:65]
	v_mfma_f32_16x16x32_bf16 v[62:65], v[156:159], v[194:197], v[62:65]
	v_mfma_f32_16x16x32_bf16 v[58:61], v[170:173], v[194:197], v[58:61]
	v_mfma_f32_16x16x32_bf16 v[58:61], v[166:169], v[190:193], v[58:61]
	v_mfma_f32_16x16x32_bf16 v[46:49], v[166:169], v[202:205], v[46:49]
	v_mfma_f32_16x16x32_bf16 v[46:49], v[170:173], v[206:209], v[46:49]
	v_mfma_f32_16x16x32_bf16 v[54:57], v[156:159], v[206:209], v[54:57]
	v_mfma_f32_16x16x32_bf16 v[54:57], v[152:155], v[202:205], v[54:57]
	v_mfma_f32_16x16x32_bf16 v[38:41], v[152:155], v[210:213], v[38:41]
	v_mfma_f32_16x16x32_bf16 v[38:41], v[156:159], v[214:217], v[38:41]
	v_mfma_f32_16x16x32_bf16 v[30:33], v[170:173], v[214:217], v[30:33]
	v_mfma_f32_16x16x32_bf16 v[30:33], v[166:169], v[210:213], v[30:33]
	v_mfma_f32_16x16x32_bf16 v[14:17], v[166:169], v[218:221], v[14:17]
	v_mfma_f32_16x16x32_bf16 v[14:17], v[170:173], v[222:225], v[14:17]
	v_mfma_f32_16x16x32_bf16 v[22:25], v[156:159], v[222:225], v[22:25]
	v_mfma_f32_16x16x32_bf16 v[22:25], v[152:155], v[218:221], v[22:25]
	v_mfma_f32_16x16x32_bf16 v[50:53], v[174:177], v[190:193], v[50:53]
	v_mfma_f32_16x16x32_bf16 v[50:53], v[178:181], v[194:197], v[50:53]
	v_mfma_f32_16x16x32_bf16 v[42:45], v[186:189], v[194:197], v[42:45]
	v_mfma_f32_16x16x32_bf16 v[42:45], v[182:185], v[190:193], v[42:45]
	v_mfma_f32_16x16x32_bf16 v[26:29], v[182:185], v[202:205], v[26:29]
	v_mfma_f32_16x16x32_bf16 v[26:29], v[186:189], v[206:209], v[26:29]
	v_mfma_f32_16x16x32_bf16 v[34:37], v[178:181], v[206:209], v[34:37]
	v_mfma_f32_16x16x32_bf16 v[34:37], v[174:177], v[202:205], v[34:37]
	v_mfma_f32_16x16x32_bf16 v[18:21], v[174:177], v[210:213], v[18:21]
	v_mfma_f32_16x16x32_bf16 v[18:21], v[178:181], v[214:217], v[18:21]
	v_mfma_f32_16x16x32_bf16 v[10:13], v[186:189], v[214:217], v[10:13]
	v_mfma_f32_16x16x32_bf16 v[10:13], v[182:185], v[210:213], v[10:13]
	v_mfma_f32_16x16x32_bf16 v[2:5], v[182:185], v[218:221], v[2:5]
	v_mfma_f32_16x16x32_bf16 v[2:5], v[186:189], v[222:225], v[2:5]
	v_mfma_f32_16x16x32_bf16 v[6:9], v[178:181], v[222:225], v[6:9]
	v_mfma_f32_16x16x32_bf16 v[6:9], v[174:177], v[218:221], v[6:9]
	s_barrier
	s_movk_i32 s44, 0x100
	s_andn2_b64 vcc, exec, s[58:59]
	s_mov_b64 s[60:61], -1
	s_mov_b64 s[58:59], 0
	s_cbranch_vccz .LBB0_1701
	s_and_b64 vcc, exec, s[16:17]
	s_cbranch_vccz .LBB0_1704
	s_barrier

.LBB0_1712:
	s_mov_b32 m0, s54
	s_waitcnt lgkmcnt(0)
	s_waitcnt vmcnt(8)
	s_barrier
	ds_read_b128 v[56:59], v50
	ds_read_b128 v[60:63], v50 offset:1024
	ds_read_b128 v[64:67], v50 offset:2048
	ds_read_b128 v[68:71], v50 offset:3072
	ds_read_b128 v[72:75], v50 offset:4096
	ds_read_b128 v[76:79], v50 offset:5120
	ds_read_b128 v[80:83], v50 offset:6144
	ds_read_b128 v[84:87], v50 offset:7168
	ds_read_b128 v[88:91], v51
	ds_read_b128 v[92:95], v51 offset:1024
	ds_read_b128 v[96:99], v51 offset:2048
	ds_read_b128 v[100:103], v51 offset:3072
	v_mfma_f32_16x16x32_bf16 v[30:33], v[234:237], v[202:205], v[30:33]
	v_mfma_f32_16x16x32_bf16 v[26:29], v[166:169], v[202:205], v[26:29]
	v_mfma_f32_16x16x32_bf16 v[22:25], v[234:237], v[210:213], v[22:25]
	v_mfma_f32_16x16x32_bf16 v[18:21], v[166:169], v[210:213], v[18:21]
	global_load_lds_dwordx4 v[42:43], off
	v_mfma_f32_16x16x32_bf16 v[14:17], v[234:237], v[218:221], v[14:17]
	v_mfma_f32_16x16x32_bf16 v[10:13], v[166:169], v[218:221], v[10:13]
	v_mfma_f32_16x16x32_bf16 v[6:9], v[234:237], v[226:229], v[6:9]
	v_mfma_f32_16x16x32_bf16 v[2:5], v[166:169], v[226:229], v[2:5]
	s_mov_b32 m0, s39
	s_add_i32 s36, s53, 7
	global_load_lds_dwordx4 v[46:47], off
	v_mfma_f32_16x16x32_bf16 v[30:33], v[238:241], v[206:209], v[30:33]
	v_mfma_f32_16x16x32_bf16 v[26:29], v[170:173], v[206:209], v[26:29]
	v_mfma_f32_16x16x32_bf16 v[22:25], v[238:241], v[214:217], v[22:25]
	v_mfma_f32_16x16x32_bf16 v[18:21], v[170:173], v[214:217], v[18:21]
	s_mov_b32 m0, s55
	s_nop 0
	global_load_lds_dwordx4 v[44:45], off
	v_mfma_f32_16x16x32_bf16 v[14:17], v[238:241], v[222:225], v[14:17]
	v_mfma_f32_16x16x32_bf16 v[10:13], v[170:173], v[222:225], v[10:13]
	v_mfma_f32_16x16x32_bf16 v[6:9], v[238:241], v[230:233], v[6:9]
	v_mfma_f32_16x16x32_bf16 v[2:5], v[170:173], v[230:233], v[2:5]
	s_mov_b32 m0, s41
	s_nop 0
	global_load_lds_dwordx4 v[48:49], off
	s_add_i32 s37, s53, 5
	s_cmp_lt_u32 s37, 61
	s_cselect_b32 s56, 3, 0xffffffc3
	s_add_i32 s56, s37, s56
	s_ashr_i32 s57, s56, 31
	s_lshl_b64 s[56:57], s[56:57], 7
	s_add_u32 s58, s14, s56
	s_addc_u32 s59, s15, s57
	s_add_u32 s56, s16, s56
	s_mov_b32 m0, s11
	s_addc_u32 s57, s17, s57
	v_lshl_add_u64 v[104:105], s[58:59], 0, v[34:35]
	s_waitcnt lgkmcnt(0)
	s_waitcnt vmcnt(8)
	s_barrier
	ds_read_b128 v[202:205], v50 offset:16384
	ds_read_b128 v[206:209], v50 offset:17408
	ds_read_b128 v[210:213], v50 offset:18432
	ds_read_b128 v[214:217], v50 offset:19456
	ds_read_b128 v[218:221], v50 offset:20480
	ds_read_b128 v[222:225], v50 offset:21504
	ds_read_b128 v[226:229], v50 offset:22528
	ds_read_b128 v[230:233], v50 offset:23552
	ds_read_b128 v[234:237], v52
	ds_read_b128 v[238:241], v52 offset:1024
	ds_read_b128 v[166:169], v52 offset:2048
	ds_read_b128 v[170:173], v52 offset:3072
	v_mfma_f32_16x16x32_bf16 v[30:33], v[88:91], v[56:59], v[30:33]
	v_mfma_f32_16x16x32_bf16 v[26:29], v[96:99], v[56:59], v[26:29]
	v_mfma_f32_16x16x32_bf16 v[22:25], v[88:91], v[64:67], v[22:25]
	v_mfma_f32_16x16x32_bf16 v[18:21], v[96:99], v[64:67], v[18:21]
	global_load_lds_dwordx4 v[104:105], off
	v_mfma_f32_16x16x32_bf16 v[14:17], v[88:91], v[72:75], v[14:17]
	v_mfma_f32_16x16x32_bf16 v[10:13], v[96:99], v[72:75], v[10:13]
	v_mfma_f32_16x16x32_bf16 v[6:9], v[88:91], v[80:83], v[6:9]
	v_mfma_f32_16x16x32_bf16 v[2:5], v[96:99], v[80:83], v[2:5]
	v_lshl_add_u64 v[104:105], s[56:57], 0, v[36:37]
	s_mov_b32 m0, s43
	s_nop 0
	global_load_lds_dwordx4 v[104:105], off
	v_mfma_f32_16x16x32_bf16 v[30:33], v[92:95], v[60:63], v[30:33]
	v_mfma_f32_16x16x32_bf16 v[26:29], v[100:103], v[60:63], v[26:29]
	v_mfma_f32_16x16x32_bf16 v[22:25], v[92:95], v[68:71], v[22:25]
	v_mfma_f32_16x16x32_bf16 v[18:21], v[100:103], v[68:71], v[18:21]
	v_lshl_add_u64 v[104:105], s[58:59], 0, v[38:39]
	s_mov_b32 m0, s21
	s_nop 0
	global_load_lds_dwordx4 v[104:105], off
	v_mfma_f32_16x16x32_bf16 v[14:17], v[92:95], v[76:79], v[14:17]
	v_mfma_f32_16x16x32_bf16 v[10:13], v[100:103], v[76:79], v[10:13]
	v_mfma_f32_16x16x32_bf16 v[6:9], v[92:95], v[84:87], v[6:9]
	v_mfma_f32_16x16x32_bf16 v[2:5], v[100:103], v[84:87], v[2:5]
	v_lshl_add_u64 v[104:105], s[56:57], 0, v[40:41]
	s_mov_b32 m0, s44
	s_nop 0
	global_load_lds_dwordx4 v[104:105], off
	s_add_i32 s37, s53, 6
	s_cmp_lt_u32 s37, 61
	s_cselect_b32 s56, 3, 0xffffffc3
	s_add_i32 s56, s37, s56
	s_ashr_i32 s57, s56, 31
	s_lshl_b64 s[56:57], s[56:57], 7
	s_add_u32 s58, s14, s56
	s_addc_u32 s59, s15, s57
	s_add_u32 s56, s16, s56
	s_mov_b32 m0, s24
	s_addc_u32 s57, s17, s57
	v_lshl_add_u64 v[104:105], s[58:59], 0, v[34:35]
	s_waitcnt lgkmcnt(0)
	s_waitcnt vmcnt(8)
	s_barrier
	ds_read_b128 v[56:59], v50 offset:32768
	ds_read_b128 v[60:63], v50 offset:33792
	ds_read_b128 v[64:67], v50 offset:34816
	ds_read_b128 v[68:71], v50 offset:35840
	ds_read_b128 v[72:75], v50 offset:36864
	ds_read_b128 v[76:79], v50 offset:37888
	ds_read_b128 v[80:83], v50 offset:38912
	ds_read_b128 v[84:87], v50 offset:39936
	ds_read_b128 v[88:91], v53
	ds_read_b128 v[92:95], v53 offset:1024
	ds_read_b128 v[96:99], v53 offset:2048
	ds_read_b128 v[100:103], v53 offset:3072
	v_mfma_f32_16x16x32_bf16 v[30:33], v[234:237], v[202:205], v[30:33]
	v_mfma_f32_16x16x32_bf16 v[26:29], v[166:169], v[202:205], v[26:29]
	v_mfma_f32_16x16x32_bf16 v[22:25], v[234:237], v[210:213], v[22:25]
	v_mfma_f32_16x16x32_bf16 v[18:21], v[166:169], v[210:213], v[18:21]
	global_load_lds_dwordx4 v[104:105], off
	v_mfma_f32_16x16x32_bf16 v[14:17], v[234:237], v[218:221], v[14:17]
	v_mfma_f32_16x16x32_bf16 v[10:13], v[166:169], v[218:221], v[10:13]
	v_mfma_f32_16x16x32_bf16 v[6:9], v[234:237], v[226:229], v[6:9]
	v_mfma_f32_16x16x32_bf16 v[2:5], v[166:169], v[226:229], v[2:5]
	v_lshl_add_u64 v[104:105], s[56:57], 0, v[36:37]
	s_mov_b32 m0, s45
	s_nop 0
	global_load_lds_dwordx4 v[104:105], off
	v_mfma_f32_16x16x32_bf16 v[30:33], v[238:241], v[206:209], v[30:33]
	v_mfma_f32_16x16x32_bf16 v[26:29], v[170:173], v[206:209], v[26:29]
	v_mfma_f32_16x16x32_bf16 v[22:25], v[238:241], v[214:217], v[22:25]
	v_mfma_f32_16x16x32_bf16 v[18:21], v[170:173], v[214:217], v[18:21]
	v_lshl_add_u64 v[104:105], s[58:59], 0, v[38:39]
	s_mov_b32 m0, s25
	s_nop 0
	global_load_lds_dwordx4 v[104:105], off
	v_mfma_f32_16x16x32_bf16 v[14:17], v[238:241], v[222:225], v[14:17]
	v_mfma_f32_16x16x32_bf16 v[10:13], v[170:173], v[222:225], v[10:13]
	v_mfma_f32_16x16x32_bf16 v[6:9], v[238:241], v[230:233], v[6:9]
	v_mfma_f32_16x16x32_bf16 v[2:5], v[170:173], v[230:233], v[2:5]
	v_lshl_add_u64 v[104:105], s[56:57], 0, v[40:41]
	s_mov_b32 m0, s50
	s_nop 0
	global_load_lds_dwordx4 v[104:105], off
	s_cmp_lt_u32 s36, 61
	s_cselect_b32 s37, 3, 0xffffffc3
	s_add_i32 s56, s36, s37
	s_ashr_i32 s57, s56, 31
	s_lshl_b64 s[56:57], s[56:57], 7
	s_add_u32 s58, s14, s56
	s_addc_u32 s59, s15, s57
	s_add_u32 s56, s16, s56
	s_mov_b32 m0, s27
	s_addc_u32 s57, s17, s57
	v_lshl_add_u64 v[104:105], s[58:59], 0, v[34:35]
	s_waitcnt lgkmcnt(0)
	s_waitcnt vmcnt(8)
	s_barrier
	ds_read_b128 v[202:205], v50 offset:49152
	ds_read_b128 v[206:209], v50 offset:50176
	ds_read_b128 v[210:213], v50 offset:51200
	ds_read_b128 v[214:217], v50 offset:52224
	ds_read_b128 v[218:221], v50 offset:53248
	ds_read_b128 v[222:225], v50 offset:54272
	ds_read_b128 v[226:229], v50 offset:55296
	ds_read_b128 v[230:233], v50 offset:56320
	ds_read_b128 v[234:237], v54
	ds_read_b128 v[238:241], v54 offset:1024
	ds_read_b128 v[166:169], v54 offset:2048
	ds_read_b128 v[170:173], v54 offset:3072
	v_mfma_f32_16x16x32_bf16 v[30:33], v[88:91], v[56:59], v[30:33]
	v_mfma_f32_16x16x32_bf16 v[26:29], v[96:99], v[56:59], v[26:29]
	v_mfma_f32_16x16x32_bf16 v[22:25], v[88:91], v[64:67], v[22:25]
	v_mfma_f32_16x16x32_bf16 v[18:21], v[96:99], v[64:67], v[18:21]
	global_load_lds_dwordx4 v[104:105], off
	v_mfma_f32_16x16x32_bf16 v[14:17], v[88:91], v[72:75], v[14:17]
	v_mfma_f32_16x16x32_bf16 v[10:13], v[96:99], v[72:75], v[10:13]
	v_mfma_f32_16x16x32_bf16 v[6:9], v[88:91], v[80:83], v[6:9]
	v_mfma_f32_16x16x32_bf16 v[2:5], v[96:99], v[80:83], v[2:5]
	v_lshl_add_u64 v[104:105], s[56:57], 0, v[36:37]
	s_mov_b32 m0, s51
	s_nop 0
	global_load_lds_dwordx4 v[104:105], off
	v_mfma_f32_16x16x32_bf16 v[30:33], v[92:95], v[60:63], v[30:33]
	v_mfma_f32_16x16x32_bf16 v[26:29], v[100:103], v[60:63], v[26:29]
	v_mfma_f32_16x16x32_bf16 v[22:25], v[92:95], v[68:71], v[22:25]
	v_mfma_f32_16x16x32_bf16 v[18:21], v[100:103], v[68:71], v[18:21]
	v_lshl_add_u64 v[104:105], s[58:59], 0, v[38:39]
	s_mov_b32 m0, s38
	s_nop 0
	global_load_lds_dwordx4 v[104:105], off
	v_mfma_f32_16x16x32_bf16 v[14:17], v[92:95], v[76:79], v[14:17]
	v_mfma_f32_16x16x32_bf16 v[10:13], v[100:103], v[76:79], v[10:13]
	v_mfma_f32_16x16x32_bf16 v[6:9], v[92:95], v[84:87], v[6:9]
	v_mfma_f32_16x16x32_bf16 v[2:5], v[100:103], v[84:87], v[2:5]
	v_lshl_add_u64 v[104:105], s[56:57], 0, v[40:41]
	s_mov_b32 m0, s52
	s_nop 0
	global_load_lds_dwordx4 v[104:105], off
	s_add_i32 s53, s53, 4
	v_lshl_add_u64 v[42:43], v[42:43], 0, s[18:19]
	v_lshl_add_u64 v[44:45], v[44:45], 0, s[18:19]
	v_lshl_add_u64 v[46:47], v[46:47], 0, s[18:19]
	s_cmp_lt_u32 s53, 60
	v_lshl_add_u64 v[48:49], v[48:49], 0, s[18:19]
	s_cbranch_scc1 .LBB0_1712
	s_waitcnt lgkmcnt(0)
	v_mfma_f32_16x16x32_bf16 v[30:33], v[234:237], v[202:205], v[30:33]
	v_mfma_f32_16x16x32_bf16 v[26:29], v[166:169], v[202:205], v[26:29]
	v_mfma_f32_16x16x32_bf16 v[22:25], v[234:237], v[210:213], v[22:25]
	v_mfma_f32_16x16x32_bf16 v[18:21], v[166:169], v[210:213], v[18:21]
	v_mfma_f32_16x16x32_bf16 v[14:17], v[234:237], v[218:221], v[14:17]
	v_mfma_f32_16x16x32_bf16 v[10:13], v[166:169], v[218:221], v[10:13]
	v_mfma_f32_16x16x32_bf16 v[6:9], v[234:237], v[226:229], v[6:9]
	v_mfma_f32_16x16x32_bf16 v[2:5], v[166:169], v[226:229], v[2:5]
	v_mfma_f32_16x16x32_bf16 v[30:33], v[238:241], v[206:209], v[30:33]
	v_mfma_f32_16x16x32_bf16 v[26:29], v[170:173], v[206:209], v[26:29]
	v_mfma_f32_16x16x32_bf16 v[22:25], v[238:241], v[214:217], v[22:25]
	v_mfma_f32_16x16x32_bf16 v[18:21], v[170:173], v[214:217], v[18:21]
	v_mfma_f32_16x16x32_bf16 v[14:17], v[238:241], v[222:225], v[14:17]
	v_mfma_f32_16x16x32_bf16 v[10:13], v[170:173], v[222:225], v[10:13]
	v_mfma_f32_16x16x32_bf16 v[6:9], v[238:241], v[230:233], v[6:9]
	v_mfma_f32_16x16x32_bf16 v[2:5], v[170:173], v[230:233], v[2:5]
	s_lshl_b32 s10, s10, 7
	s_or_b32 s5, s5, s10
	s_lshl_b32 s4, s4, 7
	v_or_b32_e32 v34, s5, v131
	s_add_i32 s4, s4, s20
	v_ashrrev_i32_e32 v35, 31, v34
	v_or_b32_e32 v36, s4, v163
	v_lshl_add_u64 v[34:35], v[34:35], 1, s[46:47]
	s_mov_b32 s10, 0xac00
	s_waitcnt vmcnt(0)
	s_barrier
	v_cvt_pk_bf16_f32 v30, v30, v31
	v_cvt_pk_bf16_f32 v31, v32, v33
	v_cvt_pk_bf16_f32 v32, v26, v27
	v_mad_i64_i32 v[26:27], s[4:5], v36, s10, v[34:35]
	v_cvt_pk_bf16_f32 v33, v28, v29
	global_store_dwordx4 v[26:27], v[30:33], off nt
	v_or_b32_e32 v26, 16, v36
	v_cvt_pk_bf16_f32 v22, v22, v23
	v_cvt_pk_bf16_f32 v23, v24, v25
	v_cvt_pk_bf16_f32 v24, v18, v19
	v_mad_i64_i32 v[18:19], s[4:5], v26, s10, v[34:35]
	v_cvt_pk_bf16_f32 v25, v20, v21
	global_store_dwordx4 v[18:19], v[22:25], off nt
	v_or_b32_e32 v18, 32, v36
	v_cvt_pk_bf16_f32 v14, v14, v15
	v_cvt_pk_bf16_f32 v15, v16, v17
	v_cvt_pk_bf16_f32 v16, v10, v11
	v_mad_i64_i32 v[10:11], s[4:5], v18, s10, v[34:35]
	v_cvt_pk_bf16_f32 v17, v12, v13
	global_store_dwordx4 v[10:11], v[14:17], off nt
	v_or_b32_e32 v10, 48, v36
	v_cvt_pk_bf16_f32 v6, v6, v7
	v_cvt_pk_bf16_f32 v7, v8, v9
	v_cvt_pk_bf16_f32 v8, v2, v3
	v_mad_i64_i32 v[2:3], s[4:5], v10, s10, v[34:35]
	v_cvt_pk_bf16_f32 v9, v4, v5
	global_store_dwordx4 v[2:3], v[6:9], off nt

.LBB0_1902:
	ds_read_b128 v[148:151], v156
	ds_read_b128 v[166:169], v156 offset:1024
	ds_read_b128 v[170:173], v156 offset:2048
	ds_read_b128 v[174:177], v156 offset:3072
	ds_read_b128 v[178:181], v157
	ds_read_b128 v[182:185], v157 offset:1024
	ds_read_b128 v[186:189], v157 offset:2048
	ds_read_b128 v[190:193], v157 offset:3072
	s_add_i32 s92, s58, 2
	s_add_u32 s36, s56, 0xffd50080
	s_addc_u32 s37, s57, -1
	s_cmp_eq_u32 s89, s58
	s_cselect_b32 s58, s54, s90
	s_cselect_b32 s61, s53, s37
	s_cselect_b32 s60, s52, s36
	s_cselect_b32 s59, s55, s91
	v_lshl_add_u64 v[152:153], s[56:57], 0, v[142:143]
	s_add_i32 m0, s67, 0xc000
	ds_read_b128 v[194:197], v158
	ds_read_b128 v[202:205], v158 offset:1024
	ds_read_b128 v[206:209], v158 offset:2048
	ds_read_b128 v[210:213], v158 offset:3072
	ds_read_b128 v[214:217], v158 offset:4096
	ds_read_b128 v[218:221], v158 offset:5120
	ds_read_b128 v[222:225], v158 offset:6144
	ds_read_b128 v[226:229], v158 offset:7168
	global_load_lds_dwordx4 v[152:153], off
	v_lshl_add_u64 v[152:153], s[56:57], 0, v[144:145]
	s_add_i32 m0, s67, 0xe000
	s_nop 0
	global_load_lds_dwordx4 v[152:153], off
	s_waitcnt vmcnt(8)
	s_waitcnt lgkmcnt(0)
	s_barrier
	s_waitcnt lgkmcnt(0)
	v_mfma_f32_16x16x32_bf16 v[126:129], v[148:151], v[194:197], v[126:129]
	v_mfma_f32_16x16x32_bf16 v[126:129], v[166:169], v[202:205], v[126:129]
	v_mfma_f32_16x16x32_bf16 v[122:125], v[174:177], v[202:205], v[122:125]
	v_mfma_f32_16x16x32_bf16 v[122:125], v[170:173], v[194:197], v[122:125]
	v_mfma_f32_16x16x32_bf16 v[106:109], v[170:173], v[206:209], v[106:109]
	v_mfma_f32_16x16x32_bf16 v[106:109], v[174:177], v[210:213], v[106:109]
	v_mfma_f32_16x16x32_bf16 v[110:113], v[166:169], v[210:213], v[110:113]
	v_mfma_f32_16x16x32_bf16 v[110:113], v[148:151], v[206:209], v[110:113]
	v_mfma_f32_16x16x32_bf16 v[94:97], v[148:151], v[214:217], v[94:97]
	v_mfma_f32_16x16x32_bf16 v[94:97], v[166:169], v[218:221], v[94:97]
	v_mfma_f32_16x16x32_bf16 v[90:93], v[174:177], v[218:221], v[90:93]
	v_mfma_f32_16x16x32_bf16 v[90:93], v[170:173], v[214:217], v[90:93]
	v_mfma_f32_16x16x32_bf16 v[74:77], v[170:173], v[222:225], v[74:77]
	v_mfma_f32_16x16x32_bf16 v[74:77], v[174:177], v[226:229], v[74:77]
	v_mfma_f32_16x16x32_bf16 v[78:81], v[166:169], v[226:229], v[78:81]
	v_mfma_f32_16x16x32_bf16 v[78:81], v[148:151], v[222:225], v[78:81]
	v_mfma_f32_16x16x32_bf16 v[118:121], v[178:181], v[194:197], v[118:121]
	v_mfma_f32_16x16x32_bf16 v[118:121], v[182:185], v[202:205], v[118:121]
	v_mfma_f32_16x16x32_bf16 v[114:117], v[190:193], v[202:205], v[114:117]
	v_mfma_f32_16x16x32_bf16 v[114:117], v[186:189], v[194:197], v[114:117]
	v_mfma_f32_16x16x32_bf16 v[98:101], v[186:189], v[206:209], v[98:101]
	v_mfma_f32_16x16x32_bf16 v[98:101], v[190:193], v[210:213], v[98:101]
	v_mfma_f32_16x16x32_bf16 v[102:105], v[182:185], v[210:213], v[102:105]
	v_mfma_f32_16x16x32_bf16 v[102:105], v[178:181], v[206:209], v[102:105]
	v_mfma_f32_16x16x32_bf16 v[86:89], v[178:181], v[214:217], v[86:89]
	v_mfma_f32_16x16x32_bf16 v[86:89], v[182:185], v[218:221], v[86:89]
	v_mfma_f32_16x16x32_bf16 v[82:85], v[190:193], v[218:221], v[82:85]
	v_mfma_f32_16x16x32_bf16 v[82:85], v[186:189], v[214:217], v[82:85]
	v_mfma_f32_16x16x32_bf16 v[66:69], v[186:189], v[222:225], v[66:69]
	v_mfma_f32_16x16x32_bf16 v[66:69], v[190:193], v[226:229], v[66:69]
	v_mfma_f32_16x16x32_bf16 v[70:73], v[182:185], v[226:229], v[70:73]
	v_mfma_f32_16x16x32_bf16 v[70:73], v[178:181], v[222:225], v[70:73]
	s_barrier
	s_add_i32 s36, s77, s64
	v_lshl_add_u64 v[152:153], s[58:59], 0, v[134:135]
	s_mov_b32 m0, s36
	ds_read_b128 v[194:197], v158 offset:16384
	ds_read_b128 v[202:205], v158 offset:17408
	ds_read_b128 v[206:209], v158 offset:18432
	ds_read_b128 v[210:213], v158 offset:19456
	ds_read_b128 v[214:217], v158 offset:20480
	ds_read_b128 v[218:221], v158 offset:21504
	ds_read_b128 v[222:225], v158 offset:22528
	ds_read_b128 v[226:229], v158 offset:23552
	global_load_lds_dwordx4 v[152:153], off
	s_add_i32 m0, s36, 0x2000
	s_add_u32 s94, s58, 0x2b0000
	v_lshl_add_u64 v[160:161], s[58:59], 0, v[138:139]
	s_addc_u32 s95, s59, 0
	s_add_i32 s36, s78, s64
	global_load_lds_dwordx4 v[160:161], off
	v_lshl_add_u64 v[198:199], s[94:95], 0, v[134:135]
	s_mov_b32 m0, s36
	v_lshl_add_u64 v[230:231], s[60:61], 0, v[136:137]
	global_load_lds_dwordx4 v[198:199], off
	v_lshl_add_u64 v[198:199], s[94:95], 0, v[138:139]
	s_add_i32 m0, s36, 0x2000
	s_nop 0
	global_load_lds_dwordx4 v[198:199], off
	v_lshl_add_u64 v[198:199], s[60:61], 0, v[132:133]
	s_mov_b32 m0, s67
	s_nop 0
	global_load_lds_dwordx4 v[198:199], off
	s_mov_b32 m0, s68
	s_nop 0
	global_load_lds_dwordx4 v[230:231], off
	s_waitcnt vmcnt(8)
	s_waitcnt lgkmcnt(0)
	s_barrier
	s_waitcnt lgkmcnt(0)
	v_mfma_f32_16x16x32_bf16 v[62:65], v[148:151], v[194:197], v[62:65]
	v_mfma_f32_16x16x32_bf16 v[62:65], v[166:169], v[202:205], v[62:65]
	v_mfma_f32_16x16x32_bf16 v[58:61], v[174:177], v[202:205], v[58:61]
	v_mfma_f32_16x16x32_bf16 v[58:61], v[170:173], v[194:197], v[58:61]
	v_mfma_f32_16x16x32_bf16 v[42:45], v[170:173], v[206:209], v[42:45]
	v_mfma_f32_16x16x32_bf16 v[42:45], v[174:177], v[210:213], v[42:45]
	v_mfma_f32_16x16x32_bf16 v[46:49], v[166:169], v[210:213], v[46:49]
	v_mfma_f32_16x16x32_bf16 v[46:49], v[148:151], v[206:209], v[46:49]
	v_mfma_f32_16x16x32_bf16 v[30:33], v[148:151], v[214:217], v[30:33]
	v_mfma_f32_16x16x32_bf16 v[30:33], v[166:169], v[218:221], v[30:33]
	v_mfma_f32_16x16x32_bf16 v[26:29], v[174:177], v[218:221], v[26:29]
	v_mfma_f32_16x16x32_bf16 v[26:29], v[170:173], v[214:217], v[26:29]
	v_mfma_f32_16x16x32_bf16 v[10:13], v[170:173], v[222:225], v[10:13]
	v_mfma_f32_16x16x32_bf16 v[10:13], v[174:177], v[226:229], v[10:13]
	v_mfma_f32_16x16x32_bf16 v[14:17], v[166:169], v[226:229], v[14:17]
	v_mfma_f32_16x16x32_bf16 v[14:17], v[148:151], v[222:225], v[14:17]
	v_mfma_f32_16x16x32_bf16 v[54:57], v[178:181], v[194:197], v[54:57]
	v_mfma_f32_16x16x32_bf16 v[54:57], v[182:185], v[202:205], v[54:57]
	v_mfma_f32_16x16x32_bf16 v[50:53], v[190:193], v[202:205], v[50:53]
	v_mfma_f32_16x16x32_bf16 v[50:53], v[186:189], v[194:197], v[50:53]
	v_mfma_f32_16x16x32_bf16 v[34:37], v[186:189], v[206:209], v[34:37]
	v_mfma_f32_16x16x32_bf16 v[34:37], v[190:193], v[210:213], v[34:37]
	v_mfma_f32_16x16x32_bf16 v[38:41], v[182:185], v[210:213], v[38:41]
	v_mfma_f32_16x16x32_bf16 v[38:41], v[178:181], v[206:209], v[38:41]
	v_mfma_f32_16x16x32_bf16 v[22:25], v[178:181], v[214:217], v[22:25]
	v_mfma_f32_16x16x32_bf16 v[22:25], v[182:185], v[218:221], v[22:25]
	v_mfma_f32_16x16x32_bf16 v[18:21], v[190:193], v[218:221], v[18:21]
	v_mfma_f32_16x16x32_bf16 v[18:21], v[186:189], v[214:217], v[18:21]
	v_mfma_f32_16x16x32_bf16 v[2:5], v[186:189], v[222:225], v[2:5]
	v_mfma_f32_16x16x32_bf16 v[2:5], v[190:193], v[226:229], v[2:5]
	v_mfma_f32_16x16x32_bf16 v[6:9], v[182:185], v[226:229], v[6:9]
	v_mfma_f32_16x16x32_bf16 v[6:9], v[178:181], v[222:225], v[6:9]
	s_barrier
	s_add_i32 s36, 0, 0x18000
	v_add_u32_e32 v140, s36, v154
	s_add_i32 s37, 0, 0x1c000
	ds_read_b128 v[148:151], v140
	ds_read_b128 v[166:169], v140 offset:1024
	ds_read_b128 v[170:173], v140 offset:2048
	ds_read_b128 v[174:177], v140 offset:3072
	v_add_u32_e32 v140, s37, v154
	ds_read_b128 v[178:181], v140
	ds_read_b128 v[182:185], v140 offset:1024
	ds_read_b128 v[186:189], v140 offset:2048
	ds_read_b128 v[190:193], v140 offset:3072
	s_add_u32 s60, s60, 0x2b0000
	s_addc_u32 s61, s61, 0
	s_mov_b32 m0, s69
	v_lshl_add_u64 v[232:233], s[60:61], 0, v[132:133]
	ds_read_b128 v[194:197], v158 offset:32768
	ds_read_b128 v[202:205], v158 offset:33792
	ds_read_b128 v[206:209], v158 offset:34816
	ds_read_b128 v[210:213], v158 offset:35840
	ds_read_b128 v[214:217], v158 offset:36864
	ds_read_b128 v[218:221], v158 offset:37888
	ds_read_b128 v[222:225], v158 offset:38912
	ds_read_b128 v[226:229], v158 offset:39936
	global_load_lds_dwordx4 v[232:233], off
	v_lshl_add_u64 v[232:233], s[60:61], 0, v[136:137]
	s_mov_b32 m0, s70
	s_nop 0
	global_load_lds_dwordx4 v[232:233], off
	s_waitcnt vmcnt(8)
	s_waitcnt lgkmcnt(0)
	s_barrier
	s_waitcnt lgkmcnt(0)
	v_mfma_f32_16x16x32_bf16 v[126:129], v[148:151], v[194:197], v[126:129]
	v_mfma_f32_16x16x32_bf16 v[126:129], v[166:169], v[202:205], v[126:129]
	v_mfma_f32_16x16x32_bf16 v[122:125], v[174:177], v[202:205], v[122:125]
	v_mfma_f32_16x16x32_bf16 v[122:125], v[170:173], v[194:197], v[122:125]
	v_mfma_f32_16x16x32_bf16 v[106:109], v[170:173], v[206:209], v[106:109]
	v_mfma_f32_16x16x32_bf16 v[106:109], v[174:177], v[210:213], v[106:109]
	v_mfma_f32_16x16x32_bf16 v[110:113], v[166:169], v[210:213], v[110:113]
	v_mfma_f32_16x16x32_bf16 v[110:113], v[148:151], v[206:209], v[110:113]
	v_mfma_f32_16x16x32_bf16 v[94:97], v[148:151], v[214:217], v[94:97]
	v_mfma_f32_16x16x32_bf16 v[94:97], v[166:169], v[218:221], v[94:97]
	v_mfma_f32_16x16x32_bf16 v[90:93], v[174:177], v[218:221], v[90:93]
	v_mfma_f32_16x16x32_bf16 v[90:93], v[170:173], v[214:217], v[90:93]
	v_mfma_f32_16x16x32_bf16 v[74:77], v[170:173], v[222:225], v[74:77]
	v_mfma_f32_16x16x32_bf16 v[74:77], v[174:177], v[226:229], v[74:77]
	v_mfma_f32_16x16x32_bf16 v[78:81], v[166:169], v[226:229], v[78:81]
	v_mfma_f32_16x16x32_bf16 v[78:81], v[148:151], v[222:225], v[78:81]
	v_mfma_f32_16x16x32_bf16 v[118:121], v[178:181], v[194:197], v[118:121]
	v_mfma_f32_16x16x32_bf16 v[118:121], v[182:185], v[202:205], v[118:121]
	v_mfma_f32_16x16x32_bf16 v[114:117], v[190:193], v[202:205], v[114:117]
	v_mfma_f32_16x16x32_bf16 v[114:117], v[186:189], v[194:197], v[114:117]
	v_mfma_f32_16x16x32_bf16 v[98:101], v[186:189], v[206:209], v[98:101]
	v_mfma_f32_16x16x32_bf16 v[98:101], v[190:193], v[210:213], v[98:101]
	v_mfma_f32_16x16x32_bf16 v[102:105], v[182:185], v[210:213], v[102:105]
	v_mfma_f32_16x16x32_bf16 v[102:105], v[178:181], v[206:209], v[102:105]
	v_mfma_f32_16x16x32_bf16 v[86:89], v[178:181], v[214:217], v[86:89]
	v_mfma_f32_16x16x32_bf16 v[86:89], v[182:185], v[218:221], v[86:89]
	v_mfma_f32_16x16x32_bf16 v[82:85], v[190:193], v[218:221], v[82:85]
	v_mfma_f32_16x16x32_bf16 v[82:85], v[186:189], v[214:217], v[82:85]
	v_mfma_f32_16x16x32_bf16 v[66:69], v[186:189], v[222:225], v[66:69]
	v_mfma_f32_16x16x32_bf16 v[66:69], v[190:193], v[226:229], v[66:69]
	v_mfma_f32_16x16x32_bf16 v[70:73], v[182:185], v[226:229], v[70:73]
	v_mfma_f32_16x16x32_bf16 v[70:73], v[178:181], v[222:225], v[70:73]
	s_barrier
	s_add_i32 s36, s36, s64
	v_lshl_add_u64 v[152:153], v[152:153], 0, s[20:21]
	s_mov_b32 m0, s36
	ds_read_b128 v[194:197], v158 offset:49152
	ds_read_b128 v[202:205], v158 offset:50176
	ds_read_b128 v[206:209], v158 offset:51200
	ds_read_b128 v[210:213], v158 offset:52224
	ds_read_b128 v[214:217], v158 offset:53248
	ds_read_b128 v[218:221], v158 offset:54272
	ds_read_b128 v[222:225], v158 offset:55296
	ds_read_b128 v[226:229], v158 offset:56320
	global_load_lds_dwordx4 v[152:153], off
	s_add_i32 m0, s36, 0x2000
	s_add_u32 s58, s58, 0x2b0080
	v_lshl_add_u64 v[152:153], v[160:161], 0, s[20:21]
	s_addc_u32 s59, s59, 0
	s_add_i32 s36, s37, s64
	global_load_lds_dwordx4 v[152:153], off
	v_lshl_add_u64 v[152:153], s[58:59], 0, v[134:135]
	s_mov_b32 m0, s36
	s_nop 0
	global_load_lds_dwordx4 v[152:153], off
	v_lshl_add_u64 v[152:153], s[58:59], 0, v[138:139]
	s_add_i32 m0, s36, 0x2000
	s_nop 0
	global_load_lds_dwordx4 v[152:153], off
	v_lshl_add_u64 v[152:153], v[198:199], 0, s[20:21]
	s_mov_b32 m0, s73
	s_nop 0
	global_load_lds_dwordx4 v[152:153], off
	v_lshl_add_u64 v[152:153], v[230:231], 0, s[20:21]
	s_mov_b32 m0, s74
	s_nop 0
	global_load_lds_dwordx4 v[152:153], off
	s_waitcnt vmcnt(8)
	s_waitcnt lgkmcnt(0)
	s_barrier
	s_waitcnt lgkmcnt(0)
	v_mfma_f32_16x16x32_bf16 v[62:65], v[148:151], v[194:197], v[62:65]
	v_mfma_f32_16x16x32_bf16 v[62:65], v[166:169], v[202:205], v[62:65]
	v_mfma_f32_16x16x32_bf16 v[58:61], v[174:177], v[202:205], v[58:61]
	v_mfma_f32_16x16x32_bf16 v[58:61], v[170:173], v[194:197], v[58:61]
	v_mfma_f32_16x16x32_bf16 v[42:45], v[170:173], v[206:209], v[42:45]
	v_mfma_f32_16x16x32_bf16 v[42:45], v[174:177], v[210:213], v[42:45]
	v_mfma_f32_16x16x32_bf16 v[46:49], v[166:169], v[210:213], v[46:49]
	v_mfma_f32_16x16x32_bf16 v[46:49], v[148:151], v[206:209], v[46:49]
	v_mfma_f32_16x16x32_bf16 v[30:33], v[148:151], v[214:217], v[30:33]
	v_mfma_f32_16x16x32_bf16 v[30:33], v[166:169], v[218:221], v[30:33]
	v_mfma_f32_16x16x32_bf16 v[26:29], v[174:177], v[218:221], v[26:29]
	v_mfma_f32_16x16x32_bf16 v[26:29], v[170:173], v[214:217], v[26:29]
	v_mfma_f32_16x16x32_bf16 v[10:13], v[170:173], v[222:225], v[10:13]
	v_mfma_f32_16x16x32_bf16 v[10:13], v[174:177], v[226:229], v[10:13]
	v_mfma_f32_16x16x32_bf16 v[14:17], v[166:169], v[226:229], v[14:17]
	v_mfma_f32_16x16x32_bf16 v[14:17], v[148:151], v[222:225], v[14:17]
	v_mfma_f32_16x16x32_bf16 v[54:57], v[178:181], v[194:197], v[54:57]
	v_mfma_f32_16x16x32_bf16 v[54:57], v[182:185], v[202:205], v[54:57]
	v_mfma_f32_16x16x32_bf16 v[50:53], v[190:193], v[202:205], v[50:53]
	v_mfma_f32_16x16x32_bf16 v[50:53], v[186:189], v[194:197], v[50:53]
	v_mfma_f32_16x16x32_bf16 v[34:37], v[186:189], v[206:209], v[34:37]
	v_mfma_f32_16x16x32_bf16 v[34:37], v[190:193], v[210:213], v[34:37]
	v_mfma_f32_16x16x32_bf16 v[38:41], v[182:185], v[210:213], v[38:41]
	v_mfma_f32_16x16x32_bf16 v[38:41], v[178:181], v[206:209], v[38:41]
	v_mfma_f32_16x16x32_bf16 v[22:25], v[178:181], v[214:217], v[22:25]
	v_mfma_f32_16x16x32_bf16 v[22:25], v[182:185], v[218:221], v[22:25]
	v_mfma_f32_16x16x32_bf16 v[18:21], v[190:193], v[218:221], v[18:21]
	v_mfma_f32_16x16x32_bf16 v[18:21], v[186:189], v[214:217], v[18:21]
	v_mfma_f32_16x16x32_bf16 v[2:5], v[186:189], v[222:225], v[2:5]
	v_mfma_f32_16x16x32_bf16 v[2:5], v[190:193], v[226:229], v[2:5]
	v_mfma_f32_16x16x32_bf16 v[6:9], v[182:185], v[226:229], v[6:9]
	v_mfma_f32_16x16x32_bf16 v[6:9], v[178:181], v[222:225], v[6:9]
	s_barrier
	s_add_u32 s56, s56, 0x100
	s_addc_u32 s57, s57, 0
	s_add_u32 s90, s90, 0x100
	s_addc_u32 s91, s91, 0
	s_cmp_ge_i32 s92, s39
	s_mov_b32 s58, s92
	s_cbranch_scc0 .LBB0_1902
	s_and_b64 vcc, exec, s[24:25]
	s_cbranch_vccz .LBB0_1905

.LBB0_2138:
	ds_read_b128 v[146:149], v157
	ds_read_b128 v[164:167], v157 offset:1024
	ds_read_b128 v[168:171], v157 offset:2048
	ds_read_b128 v[172:175], v157 offset:3072
	ds_read_b128 v[176:179], v158
	ds_read_b128 v[180:183], v158 offset:1024
	ds_read_b128 v[184:187], v158 offset:2048
	ds_read_b128 v[188:191], v158 offset:3072
	s_add_u32 s24, s22, 0xfff00080
	s_addc_u32 s25, s23, -1
	s_cmp_eq_u32 s54, 60
	s_cselect_b32 s35, s15, s25
	s_cselect_b32 s34, s50, s24
	s_cselect_b32 s25, s13, s53
	s_cselect_b32 s24, s51, s52
	v_lshl_add_u64 v[150:151], s[22:23], 0, v[138:139]
	s_add_i32 m0, s21, 0xc000
	ds_read_b128 v[192:195], v159
	ds_read_b128 v[196:199], v159 offset:1024
	ds_read_b128 v[200:203], v159 offset:2048
	ds_read_b128 v[204:207], v159 offset:3072
	ds_read_b128 v[208:211], v159 offset:4096
	ds_read_b128 v[212:215], v159 offset:5120
	ds_read_b128 v[216:219], v159 offset:6144
	ds_read_b128 v[220:223], v159 offset:7168
	global_load_lds_dwordx4 v[150:151], off
	v_lshl_add_u64 v[150:151], s[22:23], 0, v[140:141]
	s_add_i32 m0, s21, 0xe000
	s_nop 0
	global_load_lds_dwordx4 v[150:151], off
	s_waitcnt vmcnt(8)
	s_waitcnt lgkmcnt(0)
	s_barrier
	s_waitcnt lgkmcnt(0)
	v_mfma_f32_16x16x32_bf16 v[126:129], v[146:149], v[192:195], v[126:129]
	v_mfma_f32_16x16x32_bf16 v[126:129], v[164:167], v[196:199], v[126:129]
	v_mfma_f32_16x16x32_bf16 v[122:125], v[172:175], v[196:199], v[122:125]
	v_mfma_f32_16x16x32_bf16 v[122:125], v[168:171], v[192:195], v[122:125]
	v_mfma_f32_16x16x32_bf16 v[106:109], v[168:171], v[200:203], v[106:109]
	v_mfma_f32_16x16x32_bf16 v[106:109], v[172:175], v[204:207], v[106:109]
	v_mfma_f32_16x16x32_bf16 v[110:113], v[164:167], v[204:207], v[110:113]
	v_mfma_f32_16x16x32_bf16 v[110:113], v[146:149], v[200:203], v[110:113]
	v_mfma_f32_16x16x32_bf16 v[94:97], v[146:149], v[208:211], v[94:97]
	v_mfma_f32_16x16x32_bf16 v[94:97], v[164:167], v[212:215], v[94:97]
	v_mfma_f32_16x16x32_bf16 v[90:93], v[172:175], v[212:215], v[90:93]
	v_mfma_f32_16x16x32_bf16 v[90:93], v[168:171], v[208:211], v[90:93]
	v_mfma_f32_16x16x32_bf16 v[74:77], v[168:171], v[216:219], v[74:77]
	v_mfma_f32_16x16x32_bf16 v[74:77], v[172:175], v[220:223], v[74:77]
	v_mfma_f32_16x16x32_bf16 v[78:81], v[164:167], v[220:223], v[78:81]
	v_mfma_f32_16x16x32_bf16 v[78:81], v[146:149], v[216:219], v[78:81]
	v_mfma_f32_16x16x32_bf16 v[118:121], v[176:179], v[192:195], v[118:121]
	v_mfma_f32_16x16x32_bf16 v[118:121], v[180:183], v[196:199], v[118:121]
	v_mfma_f32_16x16x32_bf16 v[114:117], v[188:191], v[196:199], v[114:117]
	v_mfma_f32_16x16x32_bf16 v[114:117], v[184:187], v[192:195], v[114:117]
	v_mfma_f32_16x16x32_bf16 v[98:101], v[184:187], v[200:203], v[98:101]
	v_mfma_f32_16x16x32_bf16 v[98:101], v[188:191], v[204:207], v[98:101]
	v_mfma_f32_16x16x32_bf16 v[102:105], v[180:183], v[204:207], v[102:105]
	v_mfma_f32_16x16x32_bf16 v[102:105], v[176:179], v[200:203], v[102:105]
	v_mfma_f32_16x16x32_bf16 v[86:89], v[176:179], v[208:211], v[86:89]
	v_mfma_f32_16x16x32_bf16 v[86:89], v[180:183], v[212:215], v[86:89]
	v_mfma_f32_16x16x32_bf16 v[82:85], v[188:191], v[212:215], v[82:85]
	v_mfma_f32_16x16x32_bf16 v[82:85], v[184:187], v[208:211], v[82:85]
	v_mfma_f32_16x16x32_bf16 v[66:69], v[184:187], v[216:219], v[66:69]
	v_mfma_f32_16x16x32_bf16 v[66:69], v[188:191], v[220:223], v[66:69]
	v_mfma_f32_16x16x32_bf16 v[70:73], v[180:183], v[220:223], v[70:73]
	v_mfma_f32_16x16x32_bf16 v[70:73], v[176:179], v[216:219], v[70:73]
	s_barrier
	s_add_i32 s55, s47, s27
	v_lshl_add_u64 v[150:151], s[24:25], 0, v[134:135]
	s_mov_b32 m0, s55
	ds_read_b128 v[192:195], v159 offset:16384
	ds_read_b128 v[196:199], v159 offset:17408
	ds_read_b128 v[200:203], v159 offset:18432
	ds_read_b128 v[204:207], v159 offset:19456
	ds_read_b128 v[208:211], v159 offset:20480
	ds_read_b128 v[212:215], v159 offset:21504
	ds_read_b128 v[216:219], v159 offset:22528
	ds_read_b128 v[220:223], v159 offset:23552
	global_load_lds_dwordx4 v[150:151], off
	s_add_i32 m0, s55, 0x2000
	s_add_u32 s56, s24, 0x100000
	v_lshl_add_u64 v[160:161], s[24:25], 0, v[130:131]
	s_addc_u32 s57, s25, 0
	s_add_i32 s55, s48, s27
	global_load_lds_dwordx4 v[160:161], off
	v_lshl_add_u64 v[224:225], s[56:57], 0, v[134:135]
	s_mov_b32 m0, s55
	v_lshl_add_u64 v[226:227], s[34:35], 0, v[132:133]
	global_load_lds_dwordx4 v[224:225], off
	v_lshl_add_u64 v[224:225], s[56:57], 0, v[130:131]
	s_add_i32 m0, s55, 0x2000
	s_nop 0
	global_load_lds_dwordx4 v[224:225], off
	v_lshl_add_u64 v[224:225], s[34:35], 0, v[136:137]
	s_mov_b32 m0, s21
	s_nop 0
	global_load_lds_dwordx4 v[224:225], off
	s_mov_b32 m0, s40
	s_nop 0
	global_load_lds_dwordx4 v[226:227], off
	s_waitcnt vmcnt(8)
	s_waitcnt lgkmcnt(0)
	s_barrier
	s_waitcnt lgkmcnt(0)
	v_mfma_f32_16x16x32_bf16 v[62:65], v[146:149], v[192:195], v[62:65]
	v_mfma_f32_16x16x32_bf16 v[62:65], v[164:167], v[196:199], v[62:65]
	v_mfma_f32_16x16x32_bf16 v[58:61], v[172:175], v[196:199], v[58:61]
	v_mfma_f32_16x16x32_bf16 v[58:61], v[168:171], v[192:195], v[58:61]
	v_mfma_f32_16x16x32_bf16 v[42:45], v[168:171], v[200:203], v[42:45]
	v_mfma_f32_16x16x32_bf16 v[42:45], v[172:175], v[204:207], v[42:45]
	v_mfma_f32_16x16x32_bf16 v[46:49], v[164:167], v[204:207], v[46:49]
	v_mfma_f32_16x16x32_bf16 v[46:49], v[146:149], v[200:203], v[46:49]
	v_mfma_f32_16x16x32_bf16 v[30:33], v[146:149], v[208:211], v[30:33]
	v_mfma_f32_16x16x32_bf16 v[30:33], v[164:167], v[212:215], v[30:33]
	v_mfma_f32_16x16x32_bf16 v[26:29], v[172:175], v[212:215], v[26:29]
	v_mfma_f32_16x16x32_bf16 v[26:29], v[168:171], v[208:211], v[26:29]
	v_mfma_f32_16x16x32_bf16 v[10:13], v[168:171], v[216:219], v[10:13]
	v_mfma_f32_16x16x32_bf16 v[10:13], v[172:175], v[220:223], v[10:13]
	v_mfma_f32_16x16x32_bf16 v[14:17], v[164:167], v[220:223], v[14:17]
	v_mfma_f32_16x16x32_bf16 v[14:17], v[146:149], v[216:219], v[14:17]
	v_mfma_f32_16x16x32_bf16 v[54:57], v[176:179], v[192:195], v[54:57]
	v_mfma_f32_16x16x32_bf16 v[54:57], v[180:183], v[196:199], v[54:57]
	v_mfma_f32_16x16x32_bf16 v[50:53], v[188:191], v[196:199], v[50:53]
	v_mfma_f32_16x16x32_bf16 v[50:53], v[184:187], v[192:195], v[50:53]
	v_mfma_f32_16x16x32_bf16 v[34:37], v[184:187], v[200:203], v[34:37]
	v_mfma_f32_16x16x32_bf16 v[34:37], v[188:191], v[204:207], v[34:37]
	v_mfma_f32_16x16x32_bf16 v[38:41], v[180:183], v[204:207], v[38:41]
	v_mfma_f32_16x16x32_bf16 v[38:41], v[176:179], v[200:203], v[38:41]
	v_mfma_f32_16x16x32_bf16 v[22:25], v[176:179], v[208:211], v[22:25]
	v_mfma_f32_16x16x32_bf16 v[22:25], v[180:183], v[212:215], v[22:25]
	v_mfma_f32_16x16x32_bf16 v[18:21], v[188:191], v[212:215], v[18:21]
	v_mfma_f32_16x16x32_bf16 v[18:21], v[184:187], v[208:211], v[18:21]
	v_mfma_f32_16x16x32_bf16 v[2:5], v[184:187], v[216:219], v[2:5]
	v_mfma_f32_16x16x32_bf16 v[2:5], v[188:191], v[220:223], v[2:5]
	v_mfma_f32_16x16x32_bf16 v[6:9], v[180:183], v[220:223], v[6:9]
	v_mfma_f32_16x16x32_bf16 v[6:9], v[176:179], v[216:219], v[6:9]
	s_barrier
	s_add_i32 s55, 0, 0x18000
	v_add_u32_e32 v162, s55, v155
	s_add_i32 s56, 0, 0x1c000
	ds_read_b128 v[146:149], v162
	ds_read_b128 v[164:167], v162 offset:1024
	ds_read_b128 v[168:171], v162 offset:2048
	ds_read_b128 v[172:175], v162 offset:3072
	v_add_u32_e32 v162, s56, v155
	ds_read_b128 v[176:179], v162
	ds_read_b128 v[180:183], v162 offset:1024
	ds_read_b128 v[184:187], v162 offset:2048
	ds_read_b128 v[188:191], v162 offset:3072
	s_add_u32 s34, s34, 0x100000
	s_addc_u32 s35, s35, 0
	s_mov_b32 m0, s41
	v_lshl_add_u64 v[228:229], s[34:35], 0, v[136:137]
	ds_read_b128 v[192:195], v159 offset:32768
	ds_read_b128 v[196:199], v159 offset:33792
	ds_read_b128 v[200:203], v159 offset:34816
	ds_read_b128 v[204:207], v159 offset:35840
	ds_read_b128 v[208:211], v159 offset:36864
	ds_read_b128 v[212:215], v159 offset:37888
	ds_read_b128 v[216:219], v159 offset:38912
	ds_read_b128 v[220:223], v159 offset:39936
	global_load_lds_dwordx4 v[228:229], off
	v_lshl_add_u64 v[228:229], s[34:35], 0, v[132:133]
	s_mov_b32 m0, s42
	s_nop 0
	global_load_lds_dwordx4 v[228:229], off
	s_waitcnt vmcnt(8)
	s_waitcnt lgkmcnt(0)
	s_barrier
	s_waitcnt lgkmcnt(0)
	v_mfma_f32_16x16x32_bf16 v[126:129], v[146:149], v[192:195], v[126:129]
	v_mfma_f32_16x16x32_bf16 v[126:129], v[164:167], v[196:199], v[126:129]
	v_mfma_f32_16x16x32_bf16 v[122:125], v[172:175], v[196:199], v[122:125]
	v_mfma_f32_16x16x32_bf16 v[122:125], v[168:171], v[192:195], v[122:125]
	v_mfma_f32_16x16x32_bf16 v[106:109], v[168:171], v[200:203], v[106:109]
	v_mfma_f32_16x16x32_bf16 v[106:109], v[172:175], v[204:207], v[106:109]
	v_mfma_f32_16x16x32_bf16 v[110:113], v[164:167], v[204:207], v[110:113]
	v_mfma_f32_16x16x32_bf16 v[110:113], v[146:149], v[200:203], v[110:113]
	v_mfma_f32_16x16x32_bf16 v[94:97], v[146:149], v[208:211], v[94:97]
	v_mfma_f32_16x16x32_bf16 v[94:97], v[164:167], v[212:215], v[94:97]
	v_mfma_f32_16x16x32_bf16 v[90:93], v[172:175], v[212:215], v[90:93]
	v_mfma_f32_16x16x32_bf16 v[90:93], v[168:171], v[208:211], v[90:93]
	v_mfma_f32_16x16x32_bf16 v[74:77], v[168:171], v[216:219], v[74:77]
	v_mfma_f32_16x16x32_bf16 v[74:77], v[172:175], v[220:223], v[74:77]
	v_mfma_f32_16x16x32_bf16 v[78:81], v[164:167], v[220:223], v[78:81]
	v_mfma_f32_16x16x32_bf16 v[78:81], v[146:149], v[216:219], v[78:81]
	v_mfma_f32_16x16x32_bf16 v[118:121], v[176:179], v[192:195], v[118:121]
	v_mfma_f32_16x16x32_bf16 v[118:121], v[180:183], v[196:199], v[118:121]
	v_mfma_f32_16x16x32_bf16 v[114:117], v[188:191], v[196:199], v[114:117]
	v_mfma_f32_16x16x32_bf16 v[114:117], v[184:187], v[192:195], v[114:117]
	v_mfma_f32_16x16x32_bf16 v[98:101], v[184:187], v[200:203], v[98:101]
	v_mfma_f32_16x16x32_bf16 v[98:101], v[188:191], v[204:207], v[98:101]
	v_mfma_f32_16x16x32_bf16 v[102:105], v[180:183], v[204:207], v[102:105]
	v_mfma_f32_16x16x32_bf16 v[102:105], v[176:179], v[200:203], v[102:105]
	v_mfma_f32_16x16x32_bf16 v[86:89], v[176:179], v[208:211], v[86:89]
	v_mfma_f32_16x16x32_bf16 v[86:89], v[180:183], v[212:215], v[86:89]
	v_mfma_f32_16x16x32_bf16 v[82:85], v[188:191], v[212:215], v[82:85]
	v_mfma_f32_16x16x32_bf16 v[82:85], v[184:187], v[208:211], v[82:85]
	v_mfma_f32_16x16x32_bf16 v[66:69], v[184:187], v[216:219], v[66:69]
	v_mfma_f32_16x16x32_bf16 v[66:69], v[188:191], v[220:223], v[66:69]
	v_mfma_f32_16x16x32_bf16 v[70:73], v[180:183], v[220:223], v[70:73]
	v_mfma_f32_16x16x32_bf16 v[70:73], v[176:179], v[216:219], v[70:73]
	s_barrier
	s_add_i32 s34, s55, s27
	v_lshl_add_u64 v[150:151], v[150:151], 0, s[8:9]
	s_mov_b32 m0, s34
	ds_read_b128 v[192:195], v159 offset:49152
	ds_read_b128 v[196:199], v159 offset:50176
	ds_read_b128 v[200:203], v159 offset:51200
	ds_read_b128 v[204:207], v159 offset:52224
	ds_read_b128 v[208:211], v159 offset:53248
	ds_read_b128 v[212:215], v159 offset:54272
	ds_read_b128 v[216:219], v159 offset:55296
	ds_read_b128 v[220:223], v159 offset:56320
	global_load_lds_dwordx4 v[150:151], off
	s_add_i32 m0, s34, 0x2000
	s_add_u32 s24, s24, 0x100080
	v_lshl_add_u64 v[150:151], v[160:161], 0, s[8:9]
	s_addc_u32 s25, s25, 0
	s_add_i32 s34, s56, s27
	global_load_lds_dwordx4 v[150:151], off
	v_lshl_add_u64 v[150:151], s[24:25], 0, v[134:135]
	s_mov_b32 m0, s34
	s_nop 0
	global_load_lds_dwordx4 v[150:151], off
	v_lshl_add_u64 v[150:151], s[24:25], 0, v[130:131]
	s_add_i32 m0, s34, 0x2000
	s_nop 0
	global_load_lds_dwordx4 v[150:151], off
	v_lshl_add_u64 v[150:151], v[224:225], 0, s[8:9]
	s_mov_b32 m0, s44
	s_nop 0
	global_load_lds_dwordx4 v[150:151], off
	v_lshl_add_u64 v[150:151], v[226:227], 0, s[8:9]
	s_mov_b32 m0, s45
	s_nop 0
	global_load_lds_dwordx4 v[150:151], off
	s_waitcnt vmcnt(8)
	s_waitcnt lgkmcnt(0)
	s_barrier
	s_waitcnt lgkmcnt(0)
	v_mfma_f32_16x16x32_bf16 v[62:65], v[146:149], v[192:195], v[62:65]
	v_mfma_f32_16x16x32_bf16 v[62:65], v[164:167], v[196:199], v[62:65]
	v_mfma_f32_16x16x32_bf16 v[58:61], v[172:175], v[196:199], v[58:61]
	v_mfma_f32_16x16x32_bf16 v[58:61], v[168:171], v[192:195], v[58:61]
	v_mfma_f32_16x16x32_bf16 v[42:45], v[168:171], v[200:203], v[42:45]
	v_mfma_f32_16x16x32_bf16 v[42:45], v[172:175], v[204:207], v[42:45]
	v_mfma_f32_16x16x32_bf16 v[46:49], v[164:167], v[204:207], v[46:49]
	v_mfma_f32_16x16x32_bf16 v[46:49], v[146:149], v[200:203], v[46:49]
	v_mfma_f32_16x16x32_bf16 v[30:33], v[146:149], v[208:211], v[30:33]
	v_mfma_f32_16x16x32_bf16 v[30:33], v[164:167], v[212:215], v[30:33]
	v_mfma_f32_16x16x32_bf16 v[26:29], v[172:175], v[212:215], v[26:29]
	v_mfma_f32_16x16x32_bf16 v[26:29], v[168:171], v[208:211], v[26:29]
	v_mfma_f32_16x16x32_bf16 v[10:13], v[168:171], v[216:219], v[10:13]
	v_mfma_f32_16x16x32_bf16 v[10:13], v[172:175], v[220:223], v[10:13]
	v_mfma_f32_16x16x32_bf16 v[14:17], v[164:167], v[220:223], v[14:17]
	v_mfma_f32_16x16x32_bf16 v[14:17], v[146:149], v[216:219], v[14:17]
	v_mfma_f32_16x16x32_bf16 v[54:57], v[176:179], v[192:195], v[54:57]
	v_mfma_f32_16x16x32_bf16 v[54:57], v[180:183], v[196:199], v[54:57]
	v_mfma_f32_16x16x32_bf16 v[50:53], v[188:191], v[196:199], v[50:53]
	v_mfma_f32_16x16x32_bf16 v[50:53], v[184:187], v[192:195], v[50:53]
	v_mfma_f32_16x16x32_bf16 v[34:37], v[184:187], v[200:203], v[34:37]
	v_mfma_f32_16x16x32_bf16 v[34:37], v[188:191], v[204:207], v[34:37]
	v_mfma_f32_16x16x32_bf16 v[38:41], v[180:183], v[204:207], v[38:41]
	v_mfma_f32_16x16x32_bf16 v[38:41], v[176:179], v[200:203], v[38:41]
	v_mfma_f32_16x16x32_bf16 v[22:25], v[176:179], v[208:211], v[22:25]
	v_mfma_f32_16x16x32_bf16 v[22:25], v[180:183], v[212:215], v[22:25]
	v_mfma_f32_16x16x32_bf16 v[18:21], v[188:191], v[212:215], v[18:21]
	v_mfma_f32_16x16x32_bf16 v[18:21], v[184:187], v[208:211], v[18:21]
	v_mfma_f32_16x16x32_bf16 v[2:5], v[184:187], v[216:219], v[2:5]
	v_mfma_f32_16x16x32_bf16 v[2:5], v[188:191], v[220:223], v[2:5]
	v_mfma_f32_16x16x32_bf16 v[6:9], v[180:183], v[220:223], v[6:9]
	v_mfma_f32_16x16x32_bf16 v[6:9], v[176:179], v[216:219], v[6:9]
	s_barrier
	s_add_i32 s54, s54, 2
	s_add_u32 s22, s22, 0x100
	s_addc_u32 s23, s23, 0
	s_add_u32 s52, s52, 0x100
	s_addc_u32 s53, s53, 0
	s_cmp_gt_u32 s54, 61
	s_cbranch_scc0 .LBB0_2138
	s_and_b64 vcc, exec, s[10:11]
	s_cbranch_vccz .LBB0_2141
	s_barrier

.LBB0_2158:
	ds_read_b128 v[146:149], v157
	ds_read_b128 v[164:167], v157 offset:1024
	ds_read_b128 v[168:171], v157 offset:2048
	ds_read_b128 v[172:175], v157 offset:3072
	ds_read_b128 v[176:179], v158
	ds_read_b128 v[180:183], v158 offset:1024
	ds_read_b128 v[184:187], v158 offset:2048
	ds_read_b128 v[188:191], v158 offset:3072
	s_add_u32 s26, s24, 0xfff00080
	s_addc_u32 s27, s25, -1
	s_cmp_eq_u32 s52, 60
	s_cselect_b32 s35, s17, s27
	s_cselect_b32 s34, s48, s26
	s_cselect_b32 s27, s15, s51
	s_cselect_b32 s26, s49, s50
	v_lshl_add_u64 v[150:151], s[24:25], 0, v[138:139]
	s_add_i32 m0, s23, 0xc000
	ds_read_b128 v[192:195], v159
	ds_read_b128 v[196:199], v159 offset:1024
	ds_read_b128 v[200:203], v159 offset:2048
	ds_read_b128 v[204:207], v159 offset:3072
	ds_read_b128 v[208:211], v159 offset:4096
	ds_read_b128 v[212:215], v159 offset:5120
	ds_read_b128 v[216:219], v159 offset:6144
	ds_read_b128 v[220:223], v159 offset:7168
	global_load_lds_dwordx4 v[150:151], off
	v_lshl_add_u64 v[150:151], s[24:25], 0, v[140:141]
	s_add_i32 m0, s23, 0xe000
	s_nop 0
	global_load_lds_dwordx4 v[150:151], off
	s_waitcnt vmcnt(8)
	s_waitcnt lgkmcnt(0)
	s_barrier
	s_waitcnt lgkmcnt(0)
	v_mfma_f32_16x16x32_bf16 v[126:129], v[146:149], v[192:195], v[126:129]
	v_mfma_f32_16x16x32_bf16 v[126:129], v[164:167], v[196:199], v[126:129]
	v_mfma_f32_16x16x32_bf16 v[122:125], v[172:175], v[196:199], v[122:125]
	v_mfma_f32_16x16x32_bf16 v[122:125], v[168:171], v[192:195], v[122:125]
	v_mfma_f32_16x16x32_bf16 v[106:109], v[168:171], v[200:203], v[106:109]
	v_mfma_f32_16x16x32_bf16 v[106:109], v[172:175], v[204:207], v[106:109]
	v_mfma_f32_16x16x32_bf16 v[110:113], v[164:167], v[204:207], v[110:113]
	v_mfma_f32_16x16x32_bf16 v[110:113], v[146:149], v[200:203], v[110:113]
	v_mfma_f32_16x16x32_bf16 v[94:97], v[146:149], v[208:211], v[94:97]
	v_mfma_f32_16x16x32_bf16 v[94:97], v[164:167], v[212:215], v[94:97]
	v_mfma_f32_16x16x32_bf16 v[90:93], v[172:175], v[212:215], v[90:93]
	v_mfma_f32_16x16x32_bf16 v[90:93], v[168:171], v[208:211], v[90:93]
	v_mfma_f32_16x16x32_bf16 v[74:77], v[168:171], v[216:219], v[74:77]
	v_mfma_f32_16x16x32_bf16 v[74:77], v[172:175], v[220:223], v[74:77]
	v_mfma_f32_16x16x32_bf16 v[78:81], v[164:167], v[220:223], v[78:81]
	v_mfma_f32_16x16x32_bf16 v[78:81], v[146:149], v[216:219], v[78:81]
	v_mfma_f32_16x16x32_bf16 v[118:121], v[176:179], v[192:195], v[118:121]
	v_mfma_f32_16x16x32_bf16 v[118:121], v[180:183], v[196:199], v[118:121]
	v_mfma_f32_16x16x32_bf16 v[114:117], v[188:191], v[196:199], v[114:117]
	v_mfma_f32_16x16x32_bf16 v[114:117], v[184:187], v[192:195], v[114:117]
	v_mfma_f32_16x16x32_bf16 v[98:101], v[184:187], v[200:203], v[98:101]
	v_mfma_f32_16x16x32_bf16 v[98:101], v[188:191], v[204:207], v[98:101]
	v_mfma_f32_16x16x32_bf16 v[102:105], v[180:183], v[204:207], v[102:105]
	v_mfma_f32_16x16x32_bf16 v[102:105], v[176:179], v[200:203], v[102:105]
	v_mfma_f32_16x16x32_bf16 v[86:89], v[176:179], v[208:211], v[86:89]
	v_mfma_f32_16x16x32_bf16 v[86:89], v[180:183], v[212:215], v[86:89]
	v_mfma_f32_16x16x32_bf16 v[82:85], v[188:191], v[212:215], v[82:85]
	v_mfma_f32_16x16x32_bf16 v[82:85], v[184:187], v[208:211], v[82:85]
	v_mfma_f32_16x16x32_bf16 v[66:69], v[184:187], v[216:219], v[66:69]
	v_mfma_f32_16x16x32_bf16 v[66:69], v[188:191], v[220:223], v[66:69]
	v_mfma_f32_16x16x32_bf16 v[70:73], v[180:183], v[220:223], v[70:73]
	v_mfma_f32_16x16x32_bf16 v[70:73], v[176:179], v[216:219], v[70:73]
	s_barrier
	s_add_i32 s53, s45, s38
	v_lshl_add_u64 v[150:151], s[26:27], 0, v[132:133]
	s_mov_b32 m0, s53
	ds_read_b128 v[192:195], v159 offset:16384
	ds_read_b128 v[196:199], v159 offset:17408
	ds_read_b128 v[200:203], v159 offset:18432
	ds_read_b128 v[204:207], v159 offset:19456
	ds_read_b128 v[208:211], v159 offset:20480
	ds_read_b128 v[212:215], v159 offset:21504
	ds_read_b128 v[216:219], v159 offset:22528
	ds_read_b128 v[220:223], v159 offset:23552
	global_load_lds_dwordx4 v[150:151], off
	s_add_i32 m0, s53, 0x2000
	s_add_u32 s54, s26, 0x100000
	v_lshl_add_u64 v[160:161], s[26:27], 0, v[134:135]
	s_addc_u32 s55, s27, 0
	s_add_i32 s53, s46, s38
	global_load_lds_dwordx4 v[160:161], off
	v_lshl_add_u64 v[224:225], s[54:55], 0, v[132:133]
	s_mov_b32 m0, s53
	v_lshl_add_u64 v[226:227], s[34:35], 0, v[136:137]
	global_load_lds_dwordx4 v[224:225], off
	v_lshl_add_u64 v[224:225], s[54:55], 0, v[134:135]
	s_add_i32 m0, s53, 0x2000
	s_nop 0
	global_load_lds_dwordx4 v[224:225], off
	v_lshl_add_u64 v[224:225], s[34:35], 0, v[130:131]
	s_mov_b32 m0, s23
	s_nop 0
	global_load_lds_dwordx4 v[224:225], off
	s_mov_b32 m0, s40
	s_nop 0
	global_load_lds_dwordx4 v[226:227], off
	s_waitcnt vmcnt(8)
	s_waitcnt lgkmcnt(0)
	s_barrier
	s_waitcnt lgkmcnt(0)
	v_mfma_f32_16x16x32_bf16 v[62:65], v[146:149], v[192:195], v[62:65]
	v_mfma_f32_16x16x32_bf16 v[62:65], v[164:167], v[196:199], v[62:65]
	v_mfma_f32_16x16x32_bf16 v[58:61], v[172:175], v[196:199], v[58:61]
	v_mfma_f32_16x16x32_bf16 v[58:61], v[168:171], v[192:195], v[58:61]
	v_mfma_f32_16x16x32_bf16 v[42:45], v[168:171], v[200:203], v[42:45]
	v_mfma_f32_16x16x32_bf16 v[42:45], v[172:175], v[204:207], v[42:45]
	v_mfma_f32_16x16x32_bf16 v[46:49], v[164:167], v[204:207], v[46:49]
	v_mfma_f32_16x16x32_bf16 v[46:49], v[146:149], v[200:203], v[46:49]
	v_mfma_f32_16x16x32_bf16 v[30:33], v[146:149], v[208:211], v[30:33]
	v_mfma_f32_16x16x32_bf16 v[30:33], v[164:167], v[212:215], v[30:33]
	v_mfma_f32_16x16x32_bf16 v[26:29], v[172:175], v[212:215], v[26:29]
	v_mfma_f32_16x16x32_bf16 v[26:29], v[168:171], v[208:211], v[26:29]
	v_mfma_f32_16x16x32_bf16 v[10:13], v[168:171], v[216:219], v[10:13]
	v_mfma_f32_16x16x32_bf16 v[10:13], v[172:175], v[220:223], v[10:13]
	v_mfma_f32_16x16x32_bf16 v[14:17], v[164:167], v[220:223], v[14:17]
	v_mfma_f32_16x16x32_bf16 v[14:17], v[146:149], v[216:219], v[14:17]
	v_mfma_f32_16x16x32_bf16 v[54:57], v[176:179], v[192:195], v[54:57]
	v_mfma_f32_16x16x32_bf16 v[54:57], v[180:183], v[196:199], v[54:57]
	v_mfma_f32_16x16x32_bf16 v[50:53], v[188:191], v[196:199], v[50:53]
	v_mfma_f32_16x16x32_bf16 v[50:53], v[184:187], v[192:195], v[50:53]
	v_mfma_f32_16x16x32_bf16 v[34:37], v[184:187], v[200:203], v[34:37]
	v_mfma_f32_16x16x32_bf16 v[34:37], v[188:191], v[204:207], v[34:37]
	v_mfma_f32_16x16x32_bf16 v[38:41], v[180:183], v[204:207], v[38:41]
	v_mfma_f32_16x16x32_bf16 v[38:41], v[176:179], v[200:203], v[38:41]
	v_mfma_f32_16x16x32_bf16 v[22:25], v[176:179], v[208:211], v[22:25]
	v_mfma_f32_16x16x32_bf16 v[22:25], v[180:183], v[212:215], v[22:25]
	v_mfma_f32_16x16x32_bf16 v[18:21], v[188:191], v[212:215], v[18:21]
	v_mfma_f32_16x16x32_bf16 v[18:21], v[184:187], v[208:211], v[18:21]
	v_mfma_f32_16x16x32_bf16 v[2:5], v[184:187], v[216:219], v[2:5]
	v_mfma_f32_16x16x32_bf16 v[2:5], v[188:191], v[220:223], v[2:5]
	v_mfma_f32_16x16x32_bf16 v[6:9], v[180:183], v[220:223], v[6:9]
	v_mfma_f32_16x16x32_bf16 v[6:9], v[176:179], v[216:219], v[6:9]
	s_barrier
	s_add_i32 s53, 0, 0x18000
	v_add_u32_e32 v162, s53, v155
	s_add_i32 s54, 0, 0x1c000
	ds_read_b128 v[146:149], v162
	ds_read_b128 v[164:167], v162 offset:1024
	ds_read_b128 v[168:171], v162 offset:2048
	ds_read_b128 v[172:175], v162 offset:3072
	v_add_u32_e32 v162, s54, v155
	ds_read_b128 v[176:179], v162
	ds_read_b128 v[180:183], v162 offset:1024
	ds_read_b128 v[184:187], v162 offset:2048
	ds_read_b128 v[188:191], v162 offset:3072
	s_add_u32 s34, s34, 0x100000
	s_addc_u32 s35, s35, 0
	s_mov_b32 m0, s41
	v_lshl_add_u64 v[228:229], s[34:35], 0, v[130:131]
	ds_read_b128 v[192:195], v159 offset:32768
	ds_read_b128 v[196:199], v159 offset:33792
	ds_read_b128 v[200:203], v159 offset:34816
	ds_read_b128 v[204:207], v159 offset:35840
	ds_read_b128 v[208:211], v159 offset:36864
	ds_read_b128 v[212:215], v159 offset:37888
	ds_read_b128 v[216:219], v159 offset:38912
	ds_read_b128 v[220:223], v159 offset:39936
	global_load_lds_dwordx4 v[228:229], off
	v_lshl_add_u64 v[228:229], s[34:35], 0, v[136:137]
	s_mov_b32 m0, s42
	s_nop 0
	global_load_lds_dwordx4 v[228:229], off
	s_waitcnt vmcnt(8)
	s_waitcnt lgkmcnt(0)
	s_barrier
	s_waitcnt lgkmcnt(0)
	v_mfma_f32_16x16x32_bf16 v[126:129], v[146:149], v[192:195], v[126:129]
	v_mfma_f32_16x16x32_bf16 v[126:129], v[164:167], v[196:199], v[126:129]
	v_mfma_f32_16x16x32_bf16 v[122:125], v[172:175], v[196:199], v[122:125]
	v_mfma_f32_16x16x32_bf16 v[122:125], v[168:171], v[192:195], v[122:125]
	v_mfma_f32_16x16x32_bf16 v[106:109], v[168:171], v[200:203], v[106:109]
	v_mfma_f32_16x16x32_bf16 v[106:109], v[172:175], v[204:207], v[106:109]
	v_mfma_f32_16x16x32_bf16 v[110:113], v[164:167], v[204:207], v[110:113]
	v_mfma_f32_16x16x32_bf16 v[110:113], v[146:149], v[200:203], v[110:113]
	v_mfma_f32_16x16x32_bf16 v[94:97], v[146:149], v[208:211], v[94:97]
	v_mfma_f32_16x16x32_bf16 v[94:97], v[164:167], v[212:215], v[94:97]
	v_mfma_f32_16x16x32_bf16 v[90:93], v[172:175], v[212:215], v[90:93]
	v_mfma_f32_16x16x32_bf16 v[90:93], v[168:171], v[208:211], v[90:93]
	v_mfma_f32_16x16x32_bf16 v[74:77], v[168:171], v[216:219], v[74:77]
	v_mfma_f32_16x16x32_bf16 v[74:77], v[172:175], v[220:223], v[74:77]
	v_mfma_f32_16x16x32_bf16 v[78:81], v[164:167], v[220:223], v[78:81]
	v_mfma_f32_16x16x32_bf16 v[78:81], v[146:149], v[216:219], v[78:81]
	v_mfma_f32_16x16x32_bf16 v[118:121], v[176:179], v[192:195], v[118:121]
	v_mfma_f32_16x16x32_bf16 v[118:121], v[180:183], v[196:199], v[118:121]
	v_mfma_f32_16x16x32_bf16 v[114:117], v[188:191], v[196:199], v[114:117]
	v_mfma_f32_16x16x32_bf16 v[114:117], v[184:187], v[192:195], v[114:117]
	v_mfma_f32_16x16x32_bf16 v[98:101], v[184:187], v[200:203], v[98:101]
	v_mfma_f32_16x16x32_bf16 v[98:101], v[188:191], v[204:207], v[98:101]
	v_mfma_f32_16x16x32_bf16 v[102:105], v[180:183], v[204:207], v[102:105]
	v_mfma_f32_16x16x32_bf16 v[102:105], v[176:179], v[200:203], v[102:105]
	v_mfma_f32_16x16x32_bf16 v[86:89], v[176:179], v[208:211], v[86:89]
	v_mfma_f32_16x16x32_bf16 v[86:89], v[180:183], v[212:215], v[86:89]
	v_mfma_f32_16x16x32_bf16 v[82:85], v[188:191], v[212:215], v[82:85]
	v_mfma_f32_16x16x32_bf16 v[82:85], v[184:187], v[208:211], v[82:85]
	v_mfma_f32_16x16x32_bf16 v[66:69], v[184:187], v[216:219], v[66:69]
	v_mfma_f32_16x16x32_bf16 v[66:69], v[188:191], v[220:223], v[66:69]
	v_mfma_f32_16x16x32_bf16 v[70:73], v[180:183], v[220:223], v[70:73]
	v_mfma_f32_16x16x32_bf16 v[70:73], v[176:179], v[216:219], v[70:73]
	s_barrier
	s_add_i32 s34, s53, s38
	v_lshl_add_u64 v[150:151], v[150:151], 0, s[10:11]
	s_mov_b32 m0, s34
	ds_read_b128 v[192:195], v159 offset:49152
	ds_read_b128 v[196:199], v159 offset:50176
	ds_read_b128 v[200:203], v159 offset:51200
	ds_read_b128 v[204:207], v159 offset:52224
	ds_read_b128 v[208:211], v159 offset:53248
	ds_read_b128 v[212:215], v159 offset:54272
	ds_read_b128 v[216:219], v159 offset:55296
	ds_read_b128 v[220:223], v159 offset:56320
	global_load_lds_dwordx4 v[150:151], off
	s_add_i32 m0, s34, 0x2000
	s_add_u32 s26, s26, 0x100080
	v_lshl_add_u64 v[150:151], v[160:161], 0, s[10:11]
	s_addc_u32 s27, s27, 0
	s_add_i32 s34, s54, s38
	global_load_lds_dwordx4 v[150:151], off
	v_lshl_add_u64 v[150:151], s[26:27], 0, v[132:133]
	s_mov_b32 m0, s34
	s_nop 0
	global_load_lds_dwordx4 v[150:151], off
	v_lshl_add_u64 v[150:151], s[26:27], 0, v[134:135]
	s_add_i32 m0, s34, 0x2000
	s_nop 0
	global_load_lds_dwordx4 v[150:151], off
	v_lshl_add_u64 v[150:151], v[224:225], 0, s[10:11]
	s_mov_b32 m0, s43
	s_nop 0
	global_load_lds_dwordx4 v[150:151], off
	v_lshl_add_u64 v[150:151], v[226:227], 0, s[10:11]
	s_mov_b32 m0, s44
	s_nop 0
	global_load_lds_dwordx4 v[150:151], off
	s_waitcnt vmcnt(8)
	s_waitcnt lgkmcnt(0)
	s_barrier
	s_waitcnt lgkmcnt(0)
	v_mfma_f32_16x16x32_bf16 v[62:65], v[146:149], v[192:195], v[62:65]
	v_mfma_f32_16x16x32_bf16 v[62:65], v[164:167], v[196:199], v[62:65]
	v_mfma_f32_16x16x32_bf16 v[58:61], v[172:175], v[196:199], v[58:61]
	v_mfma_f32_16x16x32_bf16 v[58:61], v[168:171], v[192:195], v[58:61]
	v_mfma_f32_16x16x32_bf16 v[42:45], v[168:171], v[200:203], v[42:45]
	v_mfma_f32_16x16x32_bf16 v[42:45], v[172:175], v[204:207], v[42:45]
	v_mfma_f32_16x16x32_bf16 v[46:49], v[164:167], v[204:207], v[46:49]
	v_mfma_f32_16x16x32_bf16 v[46:49], v[146:149], v[200:203], v[46:49]
	v_mfma_f32_16x16x32_bf16 v[30:33], v[146:149], v[208:211], v[30:33]
	v_mfma_f32_16x16x32_bf16 v[30:33], v[164:167], v[212:215], v[30:33]
	v_mfma_f32_16x16x32_bf16 v[26:29], v[172:175], v[212:215], v[26:29]
	v_mfma_f32_16x16x32_bf16 v[26:29], v[168:171], v[208:211], v[26:29]
	v_mfma_f32_16x16x32_bf16 v[10:13], v[168:171], v[216:219], v[10:13]
	v_mfma_f32_16x16x32_bf16 v[10:13], v[172:175], v[220:223], v[10:13]
	v_mfma_f32_16x16x32_bf16 v[14:17], v[164:167], v[220:223], v[14:17]
	v_mfma_f32_16x16x32_bf16 v[14:17], v[146:149], v[216:219], v[14:17]
	v_mfma_f32_16x16x32_bf16 v[54:57], v[176:179], v[192:195], v[54:57]
	v_mfma_f32_16x16x32_bf16 v[54:57], v[180:183], v[196:199], v[54:57]
	v_mfma_f32_16x16x32_bf16 v[50:53], v[188:191], v[196:199], v[50:53]
	v_mfma_f32_16x16x32_bf16 v[50:53], v[184:187], v[192:195], v[50:53]
	v_mfma_f32_16x16x32_bf16 v[34:37], v[184:187], v[200:203], v[34:37]
	v_mfma_f32_16x16x32_bf16 v[34:37], v[188:191], v[204:207], v[34:37]
	v_mfma_f32_16x16x32_bf16 v[38:41], v[180:183], v[204:207], v[38:41]
	v_mfma_f32_16x16x32_bf16 v[38:41], v[176:179], v[200:203], v[38:41]
	v_mfma_f32_16x16x32_bf16 v[22:25], v[176:179], v[208:211], v[22:25]
	v_mfma_f32_16x16x32_bf16 v[22:25], v[180:183], v[212:215], v[22:25]
	v_mfma_f32_16x16x32_bf16 v[18:21], v[188:191], v[212:215], v[18:21]
	v_mfma_f32_16x16x32_bf16 v[18:21], v[184:187], v[208:211], v[18:21]
	v_mfma_f32_16x16x32_bf16 v[2:5], v[184:187], v[216:219], v[2:5]
	v_mfma_f32_16x16x32_bf16 v[2:5], v[188:191], v[220:223], v[2:5]
	v_mfma_f32_16x16x32_bf16 v[6:9], v[180:183], v[220:223], v[6:9]
	v_mfma_f32_16x16x32_bf16 v[6:9], v[176:179], v[216:219], v[6:9]
	s_barrier
	s_add_i32 s52, s52, 2
	s_add_u32 s24, s24, 0x100
	s_addc_u32 s25, s25, 0
	s_add_u32 s50, s50, 0x100
	s_addc_u32 s51, s51, 0
	s_cmp_gt_u32 s52, 61
	s_cbranch_scc0 .LBB0_2158
	s_and_b64 vcc, exec, s[12:13]
	s_cbranch_vccz .LBB0_2161
	s_barrier

.LBB0_2166:
	s_mov_b32 m0, s25
	v_lshl_add_u64 v[104:105], s[30:31], 0, v[32:33]
	s_waitcnt lgkmcnt(0)
	s_waitcnt vmcnt(8)
	s_barrier
	ds_read_b128 v[46:49], v40
	ds_read_b128 v[50:53], v40 offset:1024
	ds_read_b128 v[54:57], v40 offset:2048
	ds_read_b128 v[58:61], v40 offset:3072
	ds_read_b128 v[62:65], v40 offset:4096
	ds_read_b128 v[66:69], v40 offset:5120
	ds_read_b128 v[70:73], v40 offset:6144
	ds_read_b128 v[74:77], v40 offset:7168
	ds_read_b128 v[78:81], v41
	ds_read_b128 v[82:85], v41 offset:1024
	ds_read_b128 v[86:89], v41 offset:2048
	ds_read_b128 v[90:93], v41 offset:3072
	v_mfma_f32_16x16x32_bf16 v[28:31], v[234:237], v[202:205], v[28:31]
	v_mfma_f32_16x16x32_bf16 v[24:27], v[166:169], v[202:205], v[24:27]
	v_mfma_f32_16x16x32_bf16 v[20:23], v[234:237], v[210:213], v[20:23]
	v_mfma_f32_16x16x32_bf16 v[16:19], v[166:169], v[210:213], v[16:19]
	global_load_lds_dwordx4 v[104:105], off
	v_mfma_f32_16x16x32_bf16 v[12:15], v[234:237], v[218:221], v[12:15]
	v_mfma_f32_16x16x32_bf16 v[8:11], v[166:169], v[218:221], v[8:11]
	v_mfma_f32_16x16x32_bf16 v[4:7], v[234:237], v[226:229], v[4:7]
	v_mfma_f32_16x16x32_bf16 v[0:3], v[166:169], v[226:229], v[0:3]
	v_lshl_add_u64 v[104:105], s[30:31], 0, v[36:37]
	s_mov_b32 m0, s16
	s_add_i32 s27, s24, 7
	global_load_lds_dwordx4 v[104:105], off
	v_mfma_f32_16x16x32_bf16 v[28:31], v[238:241], v[206:209], v[28:31]
	v_mfma_f32_16x16x32_bf16 v[24:27], v[170:173], v[206:209], v[24:27]
	v_mfma_f32_16x16x32_bf16 v[20:23], v[238:241], v[214:217], v[20:23]
	v_mfma_f32_16x16x32_bf16 v[16:19], v[170:173], v[214:217], v[16:19]
	v_lshl_add_u64 v[104:105], s[30:31], 0, v[34:35]
	s_mov_b32 m0, s26
	s_nop 0
	global_load_lds_dwordx4 v[104:105], off
	v_mfma_f32_16x16x32_bf16 v[12:15], v[238:241], v[222:225], v[12:15]
	v_mfma_f32_16x16x32_bf16 v[8:11], v[170:173], v[222:225], v[8:11]
	v_mfma_f32_16x16x32_bf16 v[4:7], v[238:241], v[230:233], v[4:7]
	v_mfma_f32_16x16x32_bf16 v[0:3], v[170:173], v[230:233], v[0:3]
	v_lshl_add_u64 v[104:105], s[30:31], 0, v[38:39]
	s_mov_b32 m0, s17
	s_nop 0
	global_load_lds_dwordx4 v[104:105], off
	s_add_i32 s33, s24, 5
	s_cmp_lt_u32 s33, 61
	s_cselect_b32 s34, 3, 0xffffffc3
	s_add_i32 s34, s33, s34
	s_ashr_i32 s35, s34, 31
	s_lshl_b64 s[34:35], s[34:35], 7
	s_add_u32 s36, s2, s34
	s_addc_u32 s37, s3, s35
	s_add_u32 s34, s4, s34
	s_mov_b32 m0, s10
	s_addc_u32 s35, s5, s35
	v_lshl_add_u64 v[104:105], s[36:37], 0, v[130:131]
	s_waitcnt lgkmcnt(0)
	s_waitcnt vmcnt(8)
	s_barrier
	ds_read_b128 v[202:205], v40 offset:16384
	ds_read_b128 v[206:209], v40 offset:17408
	ds_read_b128 v[210:213], v40 offset:18432
	ds_read_b128 v[214:217], v40 offset:19456
	ds_read_b128 v[218:221], v40 offset:20480
	ds_read_b128 v[222:225], v40 offset:21504
	ds_read_b128 v[226:229], v40 offset:22528
	ds_read_b128 v[230:233], v40 offset:23552
	ds_read_b128 v[234:237], v42
	ds_read_b128 v[238:241], v42 offset:1024
	ds_read_b128 v[166:169], v42 offset:2048
	ds_read_b128 v[170:173], v42 offset:3072
	v_mfma_f32_16x16x32_bf16 v[28:31], v[78:81], v[46:49], v[28:31]
	v_mfma_f32_16x16x32_bf16 v[24:27], v[86:89], v[46:49], v[24:27]
	v_mfma_f32_16x16x32_bf16 v[20:23], v[78:81], v[54:57], v[20:23]
	v_mfma_f32_16x16x32_bf16 v[16:19], v[86:89], v[54:57], v[16:19]
	global_load_lds_dwordx4 v[104:105], off
	v_mfma_f32_16x16x32_bf16 v[12:15], v[78:81], v[62:65], v[12:15]
	v_mfma_f32_16x16x32_bf16 v[8:11], v[86:89], v[62:65], v[8:11]
	v_mfma_f32_16x16x32_bf16 v[4:7], v[78:81], v[70:73], v[4:7]
	v_mfma_f32_16x16x32_bf16 v[0:3], v[86:89], v[70:73], v[0:3]
	v_lshl_add_u64 v[104:105], s[34:35], 0, v[132:133]
	s_mov_b32 m0, s18
	s_nop 0
	global_load_lds_dwordx4 v[104:105], off
	v_mfma_f32_16x16x32_bf16 v[28:31], v[82:85], v[50:53], v[28:31]
	v_mfma_f32_16x16x32_bf16 v[24:27], v[90:93], v[50:53], v[24:27]
	v_mfma_f32_16x16x32_bf16 v[20:23], v[82:85], v[58:61], v[20:23]
	v_mfma_f32_16x16x32_bf16 v[16:19], v[90:93], v[58:61], v[16:19]
	v_lshl_add_u64 v[104:105], s[36:37], 0, v[136:137]
	s_mov_b32 m0, s11
	s_nop 0
	global_load_lds_dwordx4 v[104:105], off
	v_mfma_f32_16x16x32_bf16 v[12:15], v[82:85], v[66:69], v[12:15]
	v_mfma_f32_16x16x32_bf16 v[8:11], v[90:93], v[66:69], v[8:11]
	v_mfma_f32_16x16x32_bf16 v[4:7], v[82:85], v[74:77], v[4:7]
	v_mfma_f32_16x16x32_bf16 v[0:3], v[90:93], v[74:77], v[0:3]
	v_lshl_add_u64 v[104:105], s[34:35], 0, v[134:135]
	s_mov_b32 m0, s19
	s_nop 0
	global_load_lds_dwordx4 v[104:105], off
	s_add_i32 s33, s24, 6
	s_cmp_lt_u32 s33, 61
	s_cselect_b32 s34, 3, 0xffffffc3
	s_add_i32 s34, s33, s34
	s_ashr_i32 s35, s34, 31
	s_lshl_b64 s[34:35], s[34:35], 7
	s_add_u32 s36, s2, s34
	s_addc_u32 s37, s3, s35
	s_add_u32 s34, s4, s34
	s_mov_b32 m0, s12
	s_addc_u32 s35, s5, s35
	v_lshl_add_u64 v[104:105], s[36:37], 0, v[130:131]
	s_waitcnt lgkmcnt(0)
	s_waitcnt vmcnt(8)
	s_barrier
	ds_read_b128 v[46:49], v40 offset:32768
	ds_read_b128 v[50:53], v40 offset:33792
	ds_read_b128 v[54:57], v40 offset:34816
	ds_read_b128 v[58:61], v40 offset:35840
	ds_read_b128 v[62:65], v40 offset:36864
	ds_read_b128 v[66:69], v40 offset:37888
	ds_read_b128 v[70:73], v40 offset:38912
	ds_read_b128 v[74:77], v40 offset:39936
	ds_read_b128 v[78:81], v43
	ds_read_b128 v[82:85], v43 offset:1024
	ds_read_b128 v[86:89], v43 offset:2048
	ds_read_b128 v[90:93], v43 offset:3072
	v_mfma_f32_16x16x32_bf16 v[28:31], v[234:237], v[202:205], v[28:31]
	v_mfma_f32_16x16x32_bf16 v[24:27], v[166:169], v[202:205], v[24:27]
	v_mfma_f32_16x16x32_bf16 v[20:23], v[234:237], v[210:213], v[20:23]
	v_mfma_f32_16x16x32_bf16 v[16:19], v[166:169], v[210:213], v[16:19]
	global_load_lds_dwordx4 v[104:105], off
	v_mfma_f32_16x16x32_bf16 v[12:15], v[234:237], v[218:221], v[12:15]
	v_mfma_f32_16x16x32_bf16 v[8:11], v[166:169], v[218:221], v[8:11]
	v_mfma_f32_16x16x32_bf16 v[4:7], v[234:237], v[226:229], v[4:7]
	v_mfma_f32_16x16x32_bf16 v[0:3], v[166:169], v[226:229], v[0:3]
	v_lshl_add_u64 v[104:105], s[34:35], 0, v[132:133]
	s_mov_b32 m0, s20
	s_nop 0
	global_load_lds_dwordx4 v[104:105], off
	v_mfma_f32_16x16x32_bf16 v[28:31], v[238:241], v[206:209], v[28:31]
	v_mfma_f32_16x16x32_bf16 v[24:27], v[170:173], v[206:209], v[24:27]
	v_mfma_f32_16x16x32_bf16 v[20:23], v[238:241], v[214:217], v[20:23]
	v_mfma_f32_16x16x32_bf16 v[16:19], v[170:173], v[214:217], v[16:19]
	v_lshl_add_u64 v[104:105], s[36:37], 0, v[136:137]
	s_mov_b32 m0, s13
	s_nop 0
	global_load_lds_dwordx4 v[104:105], off
	v_mfma_f32_16x16x32_bf16 v[12:15], v[238:241], v[222:225], v[12:15]
	v_mfma_f32_16x16x32_bf16 v[8:11], v[170:173], v[222:225], v[8:11]
	v_mfma_f32_16x16x32_bf16 v[4:7], v[238:241], v[230:233], v[4:7]
	v_mfma_f32_16x16x32_bf16 v[0:3], v[170:173], v[230:233], v[0:3]
	v_lshl_add_u64 v[104:105], s[34:35], 0, v[134:135]
	s_mov_b32 m0, s21
	s_nop 0
	global_load_lds_dwordx4 v[104:105], off
	s_cmp_lt_u32 s27, 61
	s_cselect_b32 s33, 3, 0xffffffc3
	s_add_i32 s34, s27, s33
	s_ashr_i32 s35, s34, 31
	s_lshl_b64 s[34:35], s[34:35], 7
	s_add_u32 s36, s2, s34
	s_addc_u32 s37, s3, s35
	s_add_u32 s34, s4, s34
	s_mov_b32 m0, s14
	s_addc_u32 s35, s5, s35
	v_lshl_add_u64 v[104:105], s[36:37], 0, v[130:131]
	s_waitcnt lgkmcnt(0)
	s_waitcnt vmcnt(8)
	s_barrier
	ds_read_b128 v[202:205], v40 offset:49152
	ds_read_b128 v[206:209], v40 offset:50176
	ds_read_b128 v[210:213], v40 offset:51200
	ds_read_b128 v[214:217], v40 offset:52224
	ds_read_b128 v[218:221], v40 offset:53248
	ds_read_b128 v[222:225], v40 offset:54272
	ds_read_b128 v[226:229], v40 offset:55296
	ds_read_b128 v[230:233], v40 offset:56320
	ds_read_b128 v[234:237], v44
	ds_read_b128 v[238:241], v44 offset:1024
	ds_read_b128 v[166:169], v44 offset:2048
	ds_read_b128 v[170:173], v44 offset:3072
	v_mfma_f32_16x16x32_bf16 v[28:31], v[78:81], v[46:49], v[28:31]
	v_mfma_f32_16x16x32_bf16 v[24:27], v[86:89], v[46:49], v[24:27]
	v_mfma_f32_16x16x32_bf16 v[20:23], v[78:81], v[54:57], v[20:23]
	v_mfma_f32_16x16x32_bf16 v[16:19], v[86:89], v[54:57], v[16:19]
	global_load_lds_dwordx4 v[104:105], off
	v_mfma_f32_16x16x32_bf16 v[12:15], v[78:81], v[62:65], v[12:15]
	v_mfma_f32_16x16x32_bf16 v[8:11], v[86:89], v[62:65], v[8:11]
	v_mfma_f32_16x16x32_bf16 v[4:7], v[78:81], v[70:73], v[4:7]
	v_mfma_f32_16x16x32_bf16 v[0:3], v[86:89], v[70:73], v[0:3]
	v_lshl_add_u64 v[104:105], s[34:35], 0, v[132:133]
	s_mov_b32 m0, s22
	s_nop 0
	global_load_lds_dwordx4 v[104:105], off
	v_mfma_f32_16x16x32_bf16 v[28:31], v[82:85], v[50:53], v[28:31]
	v_mfma_f32_16x16x32_bf16 v[24:27], v[90:93], v[50:53], v[24:27]
	v_mfma_f32_16x16x32_bf16 v[20:23], v[82:85], v[58:61], v[20:23]
	v_mfma_f32_16x16x32_bf16 v[16:19], v[90:93], v[58:61], v[16:19]
	v_lshl_add_u64 v[104:105], s[36:37], 0, v[136:137]
	s_mov_b32 m0, s15
	s_nop 0
	global_load_lds_dwordx4 v[104:105], off
	v_mfma_f32_16x16x32_bf16 v[12:15], v[82:85], v[66:69], v[12:15]
	v_mfma_f32_16x16x32_bf16 v[8:11], v[90:93], v[66:69], v[8:11]
	v_mfma_f32_16x16x32_bf16 v[4:7], v[82:85], v[74:77], v[4:7]
	v_mfma_f32_16x16x32_bf16 v[0:3], v[90:93], v[74:77], v[0:3]
	v_lshl_add_u64 v[104:105], s[34:35], 0, v[134:135]
	s_mov_b32 m0, s23
	s_nop 0
	global_load_lds_dwordx4 v[104:105], off
	s_add_i32 s24, s24, 4
	s_add_u32 s30, s30, 0x200
	s_addc_u32 s31, s31, 0
	s_cmp_lt_u32 s24, 60
	s_cbranch_scc1 .LBB0_2166
	s_waitcnt lgkmcnt(0)
	v_mfma_f32_16x16x32_bf16 v[28:31], v[234:237], v[202:205], v[28:31]
	v_mfma_f32_16x16x32_bf16 v[24:27], v[166:169], v[202:205], v[24:27]
	v_mfma_f32_16x16x32_bf16 v[20:23], v[234:237], v[210:213], v[20:23]
	v_mfma_f32_16x16x32_bf16 v[16:19], v[166:169], v[210:213], v[16:19]
	v_mfma_f32_16x16x32_bf16 v[12:15], v[234:237], v[218:221], v[12:15]
	v_mfma_f32_16x16x32_bf16 v[8:11], v[166:169], v[218:221], v[8:11]
	v_mfma_f32_16x16x32_bf16 v[4:7], v[234:237], v[226:229], v[4:7]
	v_mfma_f32_16x16x32_bf16 v[0:3], v[166:169], v[226:229], v[0:3]
	v_mfma_f32_16x16x32_bf16 v[28:31], v[238:241], v[206:209], v[28:31]
	v_mfma_f32_16x16x32_bf16 v[24:27], v[170:173], v[206:209], v[24:27]
	v_mfma_f32_16x16x32_bf16 v[20:23], v[238:241], v[214:217], v[20:23]
	v_mfma_f32_16x16x32_bf16 v[16:19], v[170:173], v[214:217], v[16:19]
	v_mfma_f32_16x16x32_bf16 v[12:15], v[238:241], v[222:225], v[12:15]
	v_mfma_f32_16x16x32_bf16 v[8:11], v[170:173], v[222:225], v[8:11]
	v_mfma_f32_16x16x32_bf16 v[4:7], v[238:241], v[230:233], v[4:7]
	v_mfma_f32_16x16x32_bf16 v[0:3], v[170:173], v[230:233], v[0:3]
	s_lshl_b32 s0, s0, 7
	s_lshl_b32 s2, s8, 7
	s_or_b32 s0, s1, s0
	s_add_i32 s9, s9, s2
	v_or_b32_e32 v34, s0, v152
	v_or_b32_e32 v32, s9, v163
	v_ashrrev_i32_e32 v35, 31, v34
	v_mov_b32_e32 v33, 0
	v_lshl_add_u64 v[36:37], v[34:35], 1, s[6:7]
	v_lshlrev_b64 v[38:39], 13, v[32:33]
	v_lshl_add_u64 v[38:39], v[36:37], 0, v[38:39]
	s_waitcnt vmcnt(0)
	s_barrier
	global_load_dwordx4 v[38:41], v[38:39], off
	v_lshl_add_u64 v[34:35], v[34:35], 2, s[28:29]
	v_lshlrev_b64 v[42:43], 14, v[32:33]
	v_lshl_add_u64 v[50:51], v[34:35], 0, v[42:43]
	global_load_dwordx4 v[42:45], v[50:51], off
	global_load_dwordx4 v[46:49], v[50:51], off offset:16
	v_mul_f32_e32 v28, 0xbfb8aa3b, v28
	v_mul_f32_e32 v29, 0xbfb8aa3b, v29
	v_mul_f32_e32 v30, 0xbfb8aa3b, v30
	v_mul_f32_e32 v31, 0xbfb8aa3b, v31
	v_mul_f32_e32 v24, 0xbfb8aa3b, v24
	v_mul_f32_e32 v25, 0xbfb8aa3b, v25
	v_mul_f32_e32 v26, 0xbfb8aa3b, v26
	v_mul_f32_e32 v27, 0xbfb8aa3b, v27
	v_exp_f32_e32 v28, v28
	v_exp_f32_e32 v29, v29
	v_exp_f32_e32 v30, v30
	v_exp_f32_e32 v31, v31
	v_exp_f32_e32 v54, v24
	v_exp_f32_e32 v55, v25
	v_exp_f32_e32 v26, v26
	v_exp_f32_e32 v27, v27
	v_mov_b32_e32 v53, v33
	v_or_b32_e32 v52, 16, v32
	v_lshlrev_b64 v[24:25], 13, v[52:53]
	v_add_f32_e32 v28, 1.0, v28
	v_add_f32_e32 v29, 1.0, v29
	v_add_f32_e32 v30, 1.0, v30
	v_add_f32_e32 v31, 1.0, v31
	v_add_f32_e32 v56, 1.0, v54
	v_add_f32_e32 v57, 1.0, v55
	v_add_f32_e32 v58, 1.0, v26
	v_add_f32_e32 v59, 1.0, v27
	v_lshl_add_u64 v[54:55], v[36:37], 0, v[24:25]
	v_rcp_f32_e32 v24, v28
	v_rcp_f32_e32 v25, v29
	v_rcp_f32_e32 v26, v30
	v_rcp_f32_e32 v27, v31
	v_rcp_f32_e32 v28, v56
	v_rcp_f32_e32 v29, v57
	v_rcp_f32_e32 v30, v58
	v_rcp_f32_e32 v31, v59
	v_mul_f32_e32 v20, 0xbfb8aa3b, v20
	v_mul_f32_e32 v21, 0xbfb8aa3b, v21
	v_mul_f32_e32 v22, 0xbfb8aa3b, v22
	v_mul_f32_e32 v23, 0xbfb8aa3b, v23
	v_mul_f32_e32 v16, 0xbfb8aa3b, v16
	v_mul_f32_e32 v17, 0xbfb8aa3b, v17
	v_mul_f32_e32 v18, 0xbfb8aa3b, v18
	v_mul_f32_e32 v19, 0xbfb8aa3b, v19
	v_exp_f32_e32 v20, v20
	v_exp_f32_e32 v21, v21
	v_exp_f32_e32 v22, v22
	v_exp_f32_e32 v23, v23
	v_exp_f32_e32 v18, v18
	v_exp_f32_e32 v19, v19
	v_add_f32_e32 v20, 1.0, v20
	v_add_f32_e32 v21, 1.0, v21
	v_add_f32_e32 v22, 1.0, v22
	v_add_f32_e32 v23, 1.0, v23
	v_mul_f32_e32 v12, 0xbfb8aa3b, v12
	v_mul_f32_e32 v13, 0xbfb8aa3b, v13
	v_mul_f32_e32 v14, 0xbfb8aa3b, v14
	v_mul_f32_e32 v15, 0xbfb8aa3b, v15
	v_mul_f32_e32 v8, 0xbfb8aa3b, v8
	v_mul_f32_e32 v9, 0xbfb8aa3b, v9
	v_mul_f32_e32 v10, 0xbfb8aa3b, v10
	v_mul_f32_e32 v11, 0xbfb8aa3b, v11
	v_exp_f32_e32 v12, v12
	v_exp_f32_e32 v13, v13
	v_exp_f32_e32 v14, v14
	v_exp_f32_e32 v15, v15
	v_exp_f32_e32 v10, v10
	v_exp_f32_e32 v11, v11
	v_add_f32_e32 v12, 1.0, v12
	v_add_f32_e32 v13, 1.0, v13
	v_add_f32_e32 v14, 1.0, v14
	v_add_f32_e32 v15, 1.0, v15
	v_mul_f32_e32 v4, 0xbfb8aa3b, v4
	v_mul_f32_e32 v5, 0xbfb8aa3b, v5
	v_mul_f32_e32 v6, 0xbfb8aa3b, v6
	s_waitcnt vmcnt(0)
	v_lshlrev_b32_e32 v56, 16, v38
	v_and_b32_e32 v57, 0xffff0000, v38
	v_lshlrev_b32_e32 v38, 16, v39
	v_and_b32_e32 v39, 0xffff0000, v39
	v_lshlrev_b32_e32 v58, 16, v40
	v_and_b32_e32 v59, 0xffff0000, v40
	v_lshlrev_b32_e32 v40, 16, v41
	v_and_b32_e32 v41, 0xffff0000, v41
	v_pk_fma_f32 v[26:27], v[26:27], v[38:39], v[44:45]
	v_pk_fma_f32 v[24:25], v[24:25], v[56:57], v[42:43]
	v_pk_fma_f32 v[30:31], v[30:31], v[40:41], v[48:49]
	v_pk_fma_f32 v[28:29], v[28:29], v[58:59], v[46:47]
	global_store_dwordx4 v[50:51], v[24:27], off
	global_store_dwordx4 v[50:51], v[28:31], off offset:16
	global_load_dwordx4 v[24:27], v[54:55], off
	v_exp_f32_e32 v46, v16
	v_lshlrev_b64 v[28:29], 14, v[52:53]
	v_lshl_add_u64 v[42:43], v[34:35], 0, v[28:29]
	global_load_dwordx4 v[28:31], v[42:43], off
	global_load_dwordx4 v[38:41], v[42:43], off offset:16
	v_exp_f32_e32 v47, v17
	v_mov_b32_e32 v45, v33
	v_or_b32_e32 v44, 32, v32
	v_lshlrev_b64 v[16:17], 13, v[44:45]
	v_add_f32_e32 v48, 1.0, v46
	v_add_f32_e32 v49, 1.0, v47
	v_add_f32_e32 v50, 1.0, v18
	v_add_f32_e32 v51, 1.0, v19
	v_lshl_add_u64 v[46:47], v[36:37], 0, v[16:17]
	v_rcp_f32_e32 v16, v20
	v_rcp_f32_e32 v17, v21
	v_rcp_f32_e32 v18, v22
	v_rcp_f32_e32 v19, v23
	v_rcp_f32_e32 v20, v48
	v_rcp_f32_e32 v21, v49
	v_rcp_f32_e32 v22, v50
	v_rcp_f32_e32 v23, v51
	v_or_b32_e32 v32, 48, v32
	v_mul_f32_e32 v7, 0xbfb8aa3b, v7
	v_mul_f32_e32 v0, 0xbfb8aa3b, v0
	v_mul_f32_e32 v1, 0xbfb8aa3b, v1
	v_mul_f32_e32 v2, 0xbfb8aa3b, v2
	v_mul_f32_e32 v3, 0xbfb8aa3b, v3
	v_exp_f32_e32 v4, v4
	v_exp_f32_e32 v5, v5
	v_exp_f32_e32 v6, v6
	v_exp_f32_e32 v7, v7
	v_exp_f32_e32 v0, v0
	v_exp_f32_e32 v1, v1
	v_exp_f32_e32 v2, v2
	v_exp_f32_e32 v3, v3
	v_add_f32_e32 v4, 1.0, v4
	v_add_f32_e32 v5, 1.0, v5
	v_add_f32_e32 v6, 1.0, v6
	v_add_f32_e32 v7, 1.0, v7
	s_waitcnt vmcnt(2)
	v_lshlrev_b32_e32 v48, 16, v24
	v_and_b32_e32 v49, 0xffff0000, v24
	v_lshlrev_b32_e32 v24, 16, v25
	v_and_b32_e32 v25, 0xffff0000, v25
	v_lshlrev_b32_e32 v50, 16, v26
	v_and_b32_e32 v51, 0xffff0000, v26
	v_lshlrev_b32_e32 v26, 16, v27
	v_and_b32_e32 v27, 0xffff0000, v27
	s_waitcnt vmcnt(1)
	v_pk_fma_f32 v[18:19], v[18:19], v[24:25], v[30:31]
	v_pk_fma_f32 v[16:17], v[16:17], v[48:49], v[28:29]
	s_waitcnt vmcnt(0)
	v_pk_fma_f32 v[22:23], v[22:23], v[26:27], v[40:41]
	v_pk_fma_f32 v[20:21], v[20:21], v[50:51], v[38:39]
	global_store_dwordx4 v[42:43], v[16:19], off
	global_store_dwordx4 v[42:43], v[20:23], off offset:16
	global_load_dwordx4 v[16:19], v[46:47], off
	v_exp_f32_e32 v30, v8
	v_lshlrev_b64 v[20:21], 14, v[44:45]
	v_lshl_add_u64 v[28:29], v[34:35], 0, v[20:21]
	global_load_dwordx4 v[20:23], v[28:29], off
	global_load_dwordx4 v[24:27], v[28:29], off offset:16
	v_exp_f32_e32 v31, v9
	v_lshlrev_b64 v[8:9], 13, v[32:33]
	v_add_f32_e32 v38, 1.0, v30
	v_add_f32_e32 v40, 1.0, v10
	v_add_f32_e32 v39, 1.0, v31
	v_add_f32_e32 v41, 1.0, v11
	v_lshl_add_u64 v[30:31], v[36:37], 0, v[8:9]
	v_rcp_f32_e32 v8, v12
	v_rcp_f32_e32 v9, v13
	v_rcp_f32_e32 v10, v14
	v_rcp_f32_e32 v11, v15
	v_rcp_f32_e32 v12, v38
	v_rcp_f32_e32 v13, v39
	v_rcp_f32_e32 v14, v40
	v_rcp_f32_e32 v15, v41
	s_waitcnt vmcnt(2)
	v_lshlrev_b32_e32 v36, 16, v16
	v_and_b32_e32 v37, 0xffff0000, v16
	v_lshlrev_b32_e32 v16, 16, v17
	v_and_b32_e32 v17, 0xffff0000, v17
	v_lshlrev_b32_e32 v38, 16, v18
	v_and_b32_e32 v39, 0xffff0000, v18
	v_lshlrev_b32_e32 v18, 16, v19
	v_and_b32_e32 v19, 0xffff0000, v19
	s_waitcnt vmcnt(1)
	v_pk_fma_f32 v[10:11], v[10:11], v[16:17], v[22:23]
	v_pk_fma_f32 v[8:9], v[8:9], v[36:37], v[20:21]
	s_waitcnt vmcnt(0)
	v_pk_fma_f32 v[14:15], v[14:15], v[18:19], v[26:27]
	v_pk_fma_f32 v[12:13], v[12:13], v[38:39], v[24:25]
	global_store_dwordx4 v[28:29], v[8:11], off
	global_store_dwordx4 v[28:29], v[12:15], off offset:16
	global_load_dwordx4 v[8:11], v[30:31], off
	v_add_f32_e32 v22, 1.0, v0
	v_lshlrev_b64 v[12:13], 14, v[32:33]
	v_lshl_add_u64 v[20:21], v[34:35], 0, v[12:13]
	global_load_dwordx4 v[12:15], v[20:21], off
	global_load_dwordx4 v[16:19], v[20:21], off offset:16
	v_add_f32_e32 v23, 1.0, v1
	v_add_f32_e32 v24, 1.0, v2
	v_add_f32_e32 v25, 1.0, v3
	v_rcp_f32_e32 v0, v4
	v_rcp_f32_e32 v1, v5
	v_rcp_f32_e32 v2, v6
	v_rcp_f32_e32 v3, v7
	v_rcp_f32_e32 v4, v22
	v_rcp_f32_e32 v5, v23
	v_rcp_f32_e32 v6, v24
	v_rcp_f32_e32 v7, v25
	s_waitcnt vmcnt(2)
	v_lshlrev_b32_e32 v22, 16, v8
	v_and_b32_e32 v23, 0xffff0000, v8
	v_lshlrev_b32_e32 v8, 16, v9
	v_and_b32_e32 v9, 0xffff0000, v9
	v_lshlrev_b32_e32 v24, 16, v10
	v_and_b32_e32 v25, 0xffff0000, v10
	v_lshlrev_b32_e32 v10, 16, v11
	v_and_b32_e32 v11, 0xffff0000, v11
	s_waitcnt vmcnt(1)
	v_pk_fma_f32 v[2:3], v[2:3], v[8:9], v[14:15]
	v_pk_fma_f32 v[0:1], v[0:1], v[22:23], v[12:13]
	s_waitcnt vmcnt(0)
	v_pk_fma_f32 v[6:7], v[6:7], v[10:11], v[18:19]
	v_pk_fma_f32 v[4:5], v[4:5], v[24:25], v[16:17]
	global_store_dwordx4 v[20:21], v[0:3], off
	global_store_dwordx4 v[20:21], v[4:7], off offset:16
